# removed the per-phase s_setprio 1/0 toggles inside the nine 8-phase GEMM K-loops (age arbitration alone schedules the two wave halves better here)
# speedup vs baseline: 1.1393x; 1.0041x over previous
; #define PG8_STAGE(bufoff, gbase, voff) do { _Pragma("unroll") for (int _i = 0; _i < 2; ++_i) \
;         __builtin_amdgcn_global_load_lds((const unsigned*)((const char*)(gbase) + (voff)[_i]), (LAS unsigned*)(lds + (bufoff) + ldsw + _i * 8192), 16, 0, 0); } while (0)
; #define PG8_LDA(dst, b, h) do { _Pragma("unroll") for (int m = 0; m < 4; ++m) _Pragma("unroll") for (int k = 0; k < 2; ++k) dst[m][k] = *(const LAS h16x8*)(lds + PG8_SA(b, h) + aoff + m * 2048 + k * 1024); } while (0)
; #define PG8_LDB(dst, b, h) do { _Pragma("unroll") for (int n = 0; n < 2; ++n) _Pragma("unroll") for (int k = 0; k < 2; ++k) dst[n][k] = *(const LAS h16x8*)(lds + PG8_SB(b, h) + boff + n * 2048 + k * 1024); } while (0)
; #define PG8_MMA(ai, bj, At, Bt_) do { __builtin_amdgcn_s_setprio(1); _Pragma("unroll") for (int m = 0; m < 4; ++m) _Pragma("unroll") for (int n = 0; n < 2; ++n) _Pragma("unroll") for (int k = 0; k < 2; ++k) \
;         acc[ai][bj][m][n] = __builtin_amdgcn_mfma_f32_16x16x32_f16(Bt_[n][k], At[m][k], acc[ai][bj][m][n], 0, 0, 0); __builtin_amdgcn_s_setprio(0); } while (0)
; #define PG8_WAIT_V(n) asm volatile("s_waitcnt vmcnt(" #n ")" ::: "memory")
; template <class Epi, class AMap>
; __device__ __forceinline__ void gemm_phase(LAS unsigned char* lds, const AMap am, const int lda, const h16* Bt, const int ldb, const int M, const int N, const int K, const Epi& E) {
;     ...
;         for (int t = 0; t < nt; t += 2) {
;             const bool last = (t == nt - 2);
;             const char* a1 = cA + (size_t)(t + 1) * kstep;
;             const char* a2 = last ? nA : cA + (size_t)(t + 2) * kstep; const char* b2 = last ? nB : cB + (size_t)(t + 2) * kstep;
;             const char* a3 = a2 + kstep; const char* b3 = b2 + kstep;
;             PG8_LDB(B0, 0, 0); PG8_SCHED; PG8_LDA(At, 0, 0); PG8_STAGE(PG8_SA(1, 1), a1 + hstepA, voffA);
;             PG8_WAIT_L(8); PG8_BAR; PG8_WAIT_L(0); PG8_MMA(0, 0, At, B0); PG8_BAR; PG8_SCHED;
;             PG8_LDB(B1, 0, 1); PG8_STAGE(PG8_SB(0, 0), b2, voffB);
;             PG8_BAR; PG8_WAIT_L(0); PG8_MMA(0, 1, At, B1); PG8_BAR;
;             PG8_LDA(At, 0, 1); PG8_STAGE(PG8_SA(0, 0), a2, voffA);
;             PG8_BAR; PG8_WAIT_L(0); PG8_MMA(1, 0, At, B0); PG8_BAR; PG8_SCHED;
;             PG8_STAGE(PG8_SB(0, 1), b2 + hstepB, voffB);
;             PG8_WAIT_V(6); PG8_BAR; PG8_MMA(1, 1, At, B1); PG8_BAR;
.LBB0_61:
	s_add_u32 s26, s22, 0x100
	s_addc_u32 s27, s23, 0
	s_add_i32 s51, 0, 0x10000
	v_add_u32_e32 v144, s51, v147
	ds_read_b128 v[140:143], v144
	ds_read_b128 v[150:153], v144 offset:1024
	ds_read_b128 v[154:157], v144 offset:2048
	ds_read_b128 v[158:161], v144 offset:3072
	s_cmpk_eq_i32 s29, 0x52
	s_cselect_b32 s45, s1, s27
	s_cselect_b32 s44, s0, s26
	s_cselect_b32 s43, s41, s21
	s_cselect_b32 s42, s40, s20
	v_lshl_add_u64 v[144:145], s[22:23], 0, v[136:137]
	s_add_i32 m0, s63, 0xc000
	ds_read_b128 v[162:165], v149
	ds_read_b128 v[166:169], v149 offset:1024
	ds_read_b128 v[170:173], v149 offset:2048
	ds_read_b128 v[174:177], v149 offset:3072
	ds_read_b128 v[178:181], v149 offset:4096
	ds_read_b128 v[182:185], v149 offset:5120
	ds_read_b128 v[186:189], v149 offset:6144
	ds_read_b128 v[190:193], v149 offset:7168
	global_load_lds_dwordx4 v[144:145], off
	v_lshl_add_u64 v[144:145], s[22:23], 0, v[138:139]
	s_add_i32 m0, s63, 0xe000
	s_nop 0
	global_load_lds_dwordx4 v[144:145], off
	s_waitcnt lgkmcnt(8)
	s_barrier
	s_waitcnt lgkmcnt(0)
	s_waitcnt lgkmcnt(0)
	v_mfma_f32_16x16x32_f16 v[126:129], v[140:143], v[162:165], v[126:129]
	v_mfma_f32_16x16x32_f16 v[122:125], v[154:157], v[162:165], v[122:125]
	v_mfma_f32_16x16x32_f16 v[110:113], v[140:143], v[170:173], v[110:113]
	v_mfma_f32_16x16x32_f16 v[106:109], v[154:157], v[170:173], v[106:109]
	v_mfma_f32_16x16x32_f16 v[94:97], v[140:143], v[178:181], v[94:97]
	v_mfma_f32_16x16x32_f16 v[90:93], v[154:157], v[178:181], v[90:93]
	v_mfma_f32_16x16x32_f16 v[78:81], v[140:143], v[186:189], v[78:81]
	v_mfma_f32_16x16x32_f16 v[74:77], v[154:157], v[186:189], v[74:77]
	v_mfma_f32_16x16x32_f16 v[126:129], v[150:153], v[166:169], v[126:129]
	v_mfma_f32_16x16x32_f16 v[122:125], v[158:161], v[166:169], v[122:125]
	v_mfma_f32_16x16x32_f16 v[110:113], v[150:153], v[174:177], v[110:113]
	v_mfma_f32_16x16x32_f16 v[106:109], v[158:161], v[174:177], v[106:109]
	v_mfma_f32_16x16x32_f16 v[94:97], v[150:153], v[182:185], v[94:97]
	v_mfma_f32_16x16x32_f16 v[90:93], v[158:161], v[182:185], v[90:93]
	v_mfma_f32_16x16x32_f16 v[78:81], v[150:153], v[190:193], v[78:81]
	v_mfma_f32_16x16x32_f16 v[74:77], v[158:161], v[190:193], v[74:77]
	s_barrier
	s_add_i32 s60, 0, 0x14000
	v_add_u32_e32 v144, s60, v147
	s_add_i32 s22, s51, s48
	ds_read_b128 v[194:197], v144
	ds_read_b128 v[198:201], v144 offset:1024
	ds_read_b128 v[202:205], v144 offset:2048
	ds_read_b128 v[220:223], v144 offset:3072
	v_lshl_add_u64 v[144:145], s[42:43], 0, v[0:1]
	s_mov_b32 m0, s22
	v_lshl_add_u64 v[206:207], s[42:43], 0, v[134:135]
	global_load_lds_dwordx4 v[144:145], off
	s_add_i32 m0, s22, 0x2000
	s_nop 0
	global_load_lds_dwordx4 v[206:207], off
	s_barrier
	s_waitcnt lgkmcnt(0)
	s_waitcnt lgkmcnt(0)
	v_mfma_f32_16x16x32_f16 v[118:121], v[194:197], v[162:165], v[118:121]
	v_mfma_f32_16x16x32_f16 v[114:117], v[202:205], v[162:165], v[114:117]
	v_mfma_f32_16x16x32_f16 v[102:105], v[194:197], v[170:173], v[102:105]
	v_mfma_f32_16x16x32_f16 v[98:101], v[202:205], v[170:173], v[98:101]
	v_mfma_f32_16x16x32_f16 v[86:89], v[194:197], v[178:181], v[86:89]
	v_mfma_f32_16x16x32_f16 v[82:85], v[202:205], v[178:181], v[82:85]
	v_mfma_f32_16x16x32_f16 v[70:73], v[194:197], v[186:189], v[70:73]
	v_mfma_f32_16x16x32_f16 v[66:69], v[202:205], v[186:189], v[66:69]
	v_mfma_f32_16x16x32_f16 v[118:121], v[198:201], v[166:169], v[118:121]
	v_mfma_f32_16x16x32_f16 v[114:117], v[220:223], v[166:169], v[114:117]
	v_mfma_f32_16x16x32_f16 v[102:105], v[198:201], v[174:177], v[102:105]
	v_mfma_f32_16x16x32_f16 v[98:101], v[220:223], v[174:177], v[98:101]
	v_mfma_f32_16x16x32_f16 v[86:89], v[198:201], v[182:185], v[86:89]
	v_mfma_f32_16x16x32_f16 v[82:85], v[220:223], v[182:185], v[82:85]
	v_mfma_f32_16x16x32_f16 v[70:73], v[198:201], v[190:193], v[70:73]
	v_mfma_f32_16x16x32_f16 v[66:69], v[220:223], v[190:193], v[66:69]
	s_mov_b32 m0, s63
	v_lshl_add_u64 v[212:213], s[44:45], 0, v[130:131]
	s_barrier
	ds_read_b128 v[162:165], v149 offset:16384
	ds_read_b128 v[166:169], v149 offset:17408
	ds_read_b128 v[170:173], v149 offset:18432
	ds_read_b128 v[174:177], v149 offset:19456
	ds_read_b128 v[178:181], v149 offset:20480
	ds_read_b128 v[182:185], v149 offset:21504
	ds_read_b128 v[186:189], v149 offset:22528
	ds_read_b128 v[190:193], v149 offset:23552
	global_load_lds_dwordx4 v[212:213], off
	v_lshl_add_u64 v[214:215], s[44:45], 0, v[132:133]
	s_mov_b32 m0, s64
	s_nop 0
	global_load_lds_dwordx4 v[214:215], off
	s_barrier
	s_waitcnt lgkmcnt(0)
	s_waitcnt lgkmcnt(0)
	v_mfma_f32_16x16x32_f16 v[62:65], v[140:143], v[162:165], v[62:65]
	v_mfma_f32_16x16x32_f16 v[58:61], v[154:157], v[162:165], v[58:61]
	v_mfma_f32_16x16x32_f16 v[46:49], v[140:143], v[170:173], v[46:49]
	v_mfma_f32_16x16x32_f16 v[42:45], v[154:157], v[170:173], v[42:45]
	v_mfma_f32_16x16x32_f16 v[30:33], v[140:143], v[178:181], v[30:33]
	v_mfma_f32_16x16x32_f16 v[26:29], v[154:157], v[178:181], v[26:29]
	v_mfma_f32_16x16x32_f16 v[14:17], v[140:143], v[186:189], v[14:17]
	v_mfma_f32_16x16x32_f16 v[10:13], v[154:157], v[186:189], v[10:13]
	v_mfma_f32_16x16x32_f16 v[62:65], v[150:153], v[166:169], v[62:65]
	v_mfma_f32_16x16x32_f16 v[58:61], v[158:161], v[166:169], v[58:61]
	v_mfma_f32_16x16x32_f16 v[46:49], v[150:153], v[174:177], v[46:49]
	v_mfma_f32_16x16x32_f16 v[42:45], v[158:161], v[174:177], v[42:45]
	v_mfma_f32_16x16x32_f16 v[30:33], v[150:153], v[182:185], v[30:33]
	v_mfma_f32_16x16x32_f16 v[26:29], v[158:161], v[182:185], v[26:29]
	v_mfma_f32_16x16x32_f16 v[14:17], v[150:153], v[190:193], v[14:17]
	v_mfma_f32_16x16x32_f16 v[10:13], v[158:161], v[190:193], v[10:13]
	s_barrier
; #define PG8_STAGE(bufoff, gbase, voff) do { _Pragma("unroll") for (int _i = 0; _i < 2; ++_i) \
;         __builtin_amdgcn_global_load_lds((const unsigned*)((const char*)(gbase) + (voff)[_i]), (LAS unsigned*)(lds + (bufoff) + ldsw + _i * 8192), 16, 0, 0); } while (0)
; #define PG8_LDA(dst, b, h) do { _Pragma("unroll") for (int m = 0; m < 4; ++m) _Pragma("unroll") for (int k = 0; k < 2; ++k) dst[m][k] = *(const LAS h16x8*)(lds + PG8_SA(b, h) + aoff + m * 2048 + k * 1024); } while (0)
; #define PG8_LDB(dst, b, h) do { _Pragma("unroll") for (int n = 0; n < 2; ++n) _Pragma("unroll") for (int k = 0; k < 2; ++k) dst[n][k] = *(const LAS h16x8*)(lds + PG8_SB(b, h) + boff + n * 2048 + k * 1024); } while (0)
; #define PG8_MMA(ai, bj, At, Bt_) do { __builtin_amdgcn_s_setprio(1); _Pragma("unroll") for (int m = 0; m < 4; ++m) _Pragma("unroll") for (int n = 0; n < 2; ++n) _Pragma("unroll") for (int k = 0; k < 2; ++k) \
;         acc[ai][bj][m][n] = __builtin_amdgcn_mfma_f32_16x16x32_f16(Bt_[n][k], At[m][k], acc[ai][bj][m][n], 0, 0, 0); __builtin_amdgcn_s_setprio(0); } while (0)
; #define PG8_WAIT_V(n) asm volatile("s_waitcnt vmcnt(" #n ")" ::: "memory")
; #define PG8_WAIT_L(n) asm volatile("s_waitcnt lgkmcnt(" #n ")" ::: "memory")
; #define PG8_BAR __builtin_amdgcn_s_barrier()
; #define PG8_SCHED __builtin_amdgcn_sched_barrier(0)
; template <class Epi, class AMap>
; __device__ __forceinline__ void gemm_phase(LAS unsigned char* lds, const AMap am, const int lda, const h16* Bt, const int ldb, const int M, const int N, const int K, const Epi& E) {
;     ...
;             PG8_BAR; PG8_WAIT_L(0); PG8_MMA(1, 0, At, B0); PG8_BAR; PG8_SCHED;
;             PG8_STAGE(PG8_SB(0, 1), b2 + hstepB, voffB);
;             PG8_WAIT_V(6); PG8_BAR; PG8_MMA(1, 1, At, B1); PG8_BAR;
;             PG8_LDB(B0, 1, 0); PG8_SCHED; PG8_LDA(At, 1, 0); PG8_STAGE(PG8_SA(0, 1), a2 + hstepA, voffA);
;             PG8_WAIT_L(8); PG8_BAR; PG8_WAIT_L(0); PG8_MMA(0, 0, At, B0); PG8_BAR; PG8_SCHED;
;             PG8_LDB(B1, 1, 1); PG8_STAGE(PG8_SB(1, 0), b3, voffB);
;             PG8_BAR; PG8_WAIT_L(0); PG8_MMA(0, 1, At, B1); PG8_BAR;
;             PG8_LDA(At, 1, 1); PG8_STAGE(PG8_SA(1, 0), a3, voffA);
;             PG8_BAR; PG8_WAIT_L(0); PG8_MMA(1, 0, At, B0); PG8_BAR; PG8_SCHED;
	s_add_u32 s22, s42, 0x158000
	s_addc_u32 s23, s43, 0
	s_add_i32 s51, s60, s48
	v_lshl_add_u64 v[140:141], s[22:23], 0, v[0:1]
	s_mov_b32 m0, s51
	s_nop 0
	global_load_lds_dwordx4 v[140:141], off
	v_lshl_add_u64 v[140:141], s[22:23], 0, v[134:135]
	s_add_i32 m0, s51, 0x2000
	s_nop 0
	global_load_lds_dwordx4 v[140:141], off
	s_waitcnt vmcnt(6)
	s_barrier
	v_mfma_f32_16x16x32_f16 v[54:57], v[194:197], v[162:165], v[54:57]
	v_mfma_f32_16x16x32_f16 v[50:53], v[202:205], v[162:165], v[50:53]
	v_mfma_f32_16x16x32_f16 v[38:41], v[194:197], v[170:173], v[38:41]
	v_mfma_f32_16x16x32_f16 v[34:37], v[202:205], v[170:173], v[34:37]
	v_mfma_f32_16x16x32_f16 v[22:25], v[194:197], v[178:181], v[22:25]
	v_mfma_f32_16x16x32_f16 v[18:21], v[202:205], v[178:181], v[18:21]
	v_mfma_f32_16x16x32_f16 v[6:9], v[194:197], v[186:189], v[6:9]
	v_mfma_f32_16x16x32_f16 v[2:5], v[202:205], v[186:189], v[2:5]
	v_mfma_f32_16x16x32_f16 v[54:57], v[198:201], v[166:169], v[54:57]
	v_mfma_f32_16x16x32_f16 v[50:53], v[220:223], v[166:169], v[50:53]
	v_mfma_f32_16x16x32_f16 v[38:41], v[198:201], v[174:177], v[38:41]
	v_mfma_f32_16x16x32_f16 v[34:37], v[220:223], v[174:177], v[34:37]
	v_mfma_f32_16x16x32_f16 v[22:25], v[198:201], v[182:185], v[22:25]
	v_mfma_f32_16x16x32_f16 v[18:21], v[220:223], v[182:185], v[18:21]
	v_mfma_f32_16x16x32_f16 v[6:9], v[198:201], v[190:193], v[6:9]
	v_mfma_f32_16x16x32_f16 v[2:5], v[220:223], v[190:193], v[2:5]
	s_add_i32 s51, 0, 0x18000
	v_add_u32_e32 v158, s51, v147
	s_barrier
	ds_read_b128 v[140:143], v158
	ds_read_b128 v[150:153], v158 offset:1024
	ds_read_b128 v[154:157], v158 offset:2048
	ds_read_b128 v[158:161], v158 offset:3072
	s_add_u32 s22, s44, 0x158000
	s_addc_u32 s23, s45, 0
	s_mov_b32 m0, s65
	v_lshl_add_u64 v[194:195], s[22:23], 0, v[130:131]
	ds_read_b128 v[162:165], v149 offset:32768
	ds_read_b128 v[166:169], v149 offset:33792
	ds_read_b128 v[170:173], v149 offset:34816
	ds_read_b128 v[174:177], v149 offset:35840
	ds_read_b128 v[178:181], v149 offset:36864
	ds_read_b128 v[182:185], v149 offset:37888
	ds_read_b128 v[186:189], v149 offset:38912
	ds_read_b128 v[190:193], v149 offset:39936
	global_load_lds_dwordx4 v[194:195], off
	v_lshl_add_u64 v[194:195], s[22:23], 0, v[132:133]
	s_mov_b32 m0, s68
	s_nop 0
	global_load_lds_dwordx4 v[194:195], off
	s_waitcnt lgkmcnt(8)
	s_barrier
	s_waitcnt lgkmcnt(0)
	s_waitcnt lgkmcnt(0)
	v_mfma_f32_16x16x32_f16 v[126:129], v[140:143], v[162:165], v[126:129]
	v_mfma_f32_16x16x32_f16 v[122:125], v[154:157], v[162:165], v[122:125]
	v_mfma_f32_16x16x32_f16 v[110:113], v[140:143], v[170:173], v[110:113]
	v_mfma_f32_16x16x32_f16 v[106:109], v[154:157], v[170:173], v[106:109]
	v_mfma_f32_16x16x32_f16 v[94:97], v[140:143], v[178:181], v[94:97]
	v_mfma_f32_16x16x32_f16 v[90:93], v[154:157], v[178:181], v[90:93]
	v_mfma_f32_16x16x32_f16 v[78:81], v[140:143], v[186:189], v[78:81]
	v_mfma_f32_16x16x32_f16 v[74:77], v[154:157], v[186:189], v[74:77]
	v_mfma_f32_16x16x32_f16 v[126:129], v[150:153], v[166:169], v[126:129]
	v_mfma_f32_16x16x32_f16 v[122:125], v[158:161], v[166:169], v[122:125]
	v_mfma_f32_16x16x32_f16 v[110:113], v[150:153], v[174:177], v[110:113]
	v_mfma_f32_16x16x32_f16 v[106:109], v[158:161], v[174:177], v[106:109]
	v_mfma_f32_16x16x32_f16 v[94:97], v[150:153], v[182:185], v[94:97]
	v_mfma_f32_16x16x32_f16 v[90:93], v[158:161], v[182:185], v[90:93]
	v_mfma_f32_16x16x32_f16 v[78:81], v[150:153], v[190:193], v[78:81]
	v_mfma_f32_16x16x32_f16 v[74:77], v[158:161], v[190:193], v[74:77]
	s_barrier
	s_add_i32 s44, 0, 0x1c000
	s_add_i32 s22, s51, s48
	v_add_u32_e32 v216, s44, v147
	v_lshl_add_u64 v[144:145], v[144:145], 0, s[92:93]
	s_mov_b32 m0, s22
	ds_read_b128 v[194:197], v216
	ds_read_b128 v[198:201], v216 offset:1024
	ds_read_b128 v[202:205], v216 offset:2048
	ds_read_b128 v[220:223], v216 offset:3072
	global_load_lds_dwordx4 v[144:145], off
	v_lshl_add_u64 v[144:145], v[206:207], 0, s[92:93]
	s_add_i32 m0, s22, 0x2000
	s_nop 0
	global_load_lds_dwordx4 v[144:145], off
	s_barrier
	s_waitcnt lgkmcnt(0)
	s_waitcnt lgkmcnt(0)
	v_mfma_f32_16x16x32_f16 v[118:121], v[194:197], v[162:165], v[118:121]
	v_mfma_f32_16x16x32_f16 v[114:117], v[202:205], v[162:165], v[114:117]
	v_mfma_f32_16x16x32_f16 v[102:105], v[194:197], v[170:173], v[102:105]
	v_mfma_f32_16x16x32_f16 v[98:101], v[202:205], v[170:173], v[98:101]
	v_mfma_f32_16x16x32_f16 v[86:89], v[194:197], v[178:181], v[86:89]
	v_mfma_f32_16x16x32_f16 v[82:85], v[202:205], v[178:181], v[82:85]
	v_mfma_f32_16x16x32_f16 v[70:73], v[194:197], v[186:189], v[70:73]
	v_mfma_f32_16x16x32_f16 v[66:69], v[202:205], v[186:189], v[66:69]
	v_mfma_f32_16x16x32_f16 v[118:121], v[198:201], v[166:169], v[118:121]
	v_mfma_f32_16x16x32_f16 v[114:117], v[220:223], v[166:169], v[114:117]
	v_mfma_f32_16x16x32_f16 v[102:105], v[198:201], v[174:177], v[102:105]
	v_mfma_f32_16x16x32_f16 v[98:101], v[220:223], v[174:177], v[98:101]
	v_mfma_f32_16x16x32_f16 v[86:89], v[198:201], v[182:185], v[86:89]
	v_mfma_f32_16x16x32_f16 v[82:85], v[220:223], v[182:185], v[82:85]
	v_mfma_f32_16x16x32_f16 v[70:73], v[198:201], v[190:193], v[70:73]
	v_mfma_f32_16x16x32_f16 v[66:69], v[220:223], v[190:193], v[66:69]
	s_mov_b32 m0, s69
	v_lshl_add_u64 v[144:145], v[212:213], 0, s[92:93]
	s_barrier
	ds_read_b128 v[162:165], v149 offset:49152
	ds_read_b128 v[166:169], v149 offset:50176
	ds_read_b128 v[170:173], v149 offset:51200
	ds_read_b128 v[174:177], v149 offset:52224
	ds_read_b128 v[178:181], v149 offset:53248
	ds_read_b128 v[182:185], v149 offset:54272
	ds_read_b128 v[186:189], v149 offset:55296
	ds_read_b128 v[190:193], v149 offset:56320
	global_load_lds_dwordx4 v[144:145], off
	v_lshl_add_u64 v[144:145], v[214:215], 0, s[92:93]
	s_mov_b32 m0, s70
	s_nop 0
	global_load_lds_dwordx4 v[144:145], off
	s_barrier
; #define PG8_STAGE(bufoff, gbase, voff) do { _Pragma("unroll") for (int _i = 0; _i < 2; ++_i) \
;         __builtin_amdgcn_global_load_lds((const unsigned*)((const char*)(gbase) + (voff)[_i]), (LAS unsigned*)(lds + (bufoff) + ldsw + _i * 8192), 16, 0, 0); } while (0)
; #define PG8_LDA(dst, b, h) do { _Pragma("unroll") for (int m = 0; m < 4; ++m) _Pragma("unroll") for (int k = 0; k < 2; ++k) dst[m][k] = *(const LAS h16x8*)(lds + PG8_SA(b, h) + aoff + m * 2048 + k * 1024); } while (0)
; #define PG8_MMA(ai, bj, At, Bt_) do { __builtin_amdgcn_s_setprio(1); _Pragma("unroll") for (int m = 0; m < 4; ++m) _Pragma("unroll") for (int n = 0; n < 2; ++n) _Pragma("unroll") for (int k = 0; k < 2; ++k) \
;         acc[ai][bj][m][n] = __builtin_amdgcn_mfma_f32_16x16x32_f16(Bt_[n][k], At[m][k], acc[ai][bj][m][n], 0, 0, 0); __builtin_amdgcn_s_setprio(0); } while (0)
; #define PG8_WAIT_V(n) asm volatile("s_waitcnt vmcnt(" #n ")" ::: "memory")
; #define PG8_WAIT_L(n) asm volatile("s_waitcnt lgkmcnt(" #n ")" ::: "memory")
; template <class Epi, class AMap>
; __device__ __forceinline__ void gemm_phase(LAS unsigned char* lds, const AMap am, const int lda, const h16* Bt, const int ldb, const int M, const int N, const int K, const Epi& E) {
;     ...
;             PG8_BAR; PG8_WAIT_L(0); PG8_MMA(0, 1, At, B1); PG8_BAR;
;             PG8_LDA(At, 1, 1); PG8_STAGE(PG8_SA(1, 0), a3, voffA);
;             PG8_BAR; PG8_WAIT_L(0); PG8_MMA(1, 0, At, B0); PG8_BAR; PG8_SCHED;
;             PG8_STAGE(PG8_SB(1, 1), b3 + hstepB, voffB);
;             PG8_WAIT_V(6); PG8_BAR; PG8_MMA(1, 1, At, B1); PG8_BAR;
;         }
;     __device__ __forceinline__ void operator()(const f32x4 (&acc)[2][2][4][2], const Unit& u, int wr, int wc, int fr, int fq) const {
;         EPI_ROWS_PERM
; #pragma unroll
;         for (int ai = 0; ai < 2; ++ai)
; #pragma unroll
;             for (int m = 0; m < 4; ++m) { const size_t off = (size_t)(row0 + ai * 128 + m * 16) * DM + colt;
; #pragma unroll
;                 for (int bj = 0; bj < 2; ++bj) {
;                     const h16x8 x = *(const h16x8*)(X + off + bj * 128);
;                     f32x4 o0, o1;
; #pragma unroll
;                     for (int e = 0; e < 4; ++e) { o0[e] = (float)x[e] * ALPHA + acc[ai][bj][m][0][e]; o1[e] = (float)x[4 + e] * ALPHA + acc[ai][bj][m][1][e]; }
;                     *(u32x4*)(PRE + off + bj * 128) = pack8(o0, o1); } }
	s_waitcnt lgkmcnt(0)
	s_waitcnt lgkmcnt(0)
	v_mfma_f32_16x16x32_f16 v[62:65], v[140:143], v[162:165], v[62:65]
	v_mfma_f32_16x16x32_f16 v[58:61], v[154:157], v[162:165], v[58:61]
	v_mfma_f32_16x16x32_f16 v[46:49], v[140:143], v[170:173], v[46:49]
	v_mfma_f32_16x16x32_f16 v[42:45], v[154:157], v[170:173], v[42:45]
	v_mfma_f32_16x16x32_f16 v[30:33], v[140:143], v[178:181], v[30:33]
	v_mfma_f32_16x16x32_f16 v[26:29], v[154:157], v[178:181], v[26:29]
	v_mfma_f32_16x16x32_f16 v[14:17], v[140:143], v[186:189], v[14:17]
	v_mfma_f32_16x16x32_f16 v[10:13], v[154:157], v[186:189], v[10:13]
	v_mfma_f32_16x16x32_f16 v[62:65], v[150:153], v[166:169], v[62:65]
	v_mfma_f32_16x16x32_f16 v[58:61], v[158:161], v[166:169], v[58:61]
	v_mfma_f32_16x16x32_f16 v[46:49], v[150:153], v[174:177], v[46:49]
	v_mfma_f32_16x16x32_f16 v[42:45], v[158:161], v[174:177], v[42:45]
	v_mfma_f32_16x16x32_f16 v[30:33], v[150:153], v[182:185], v[30:33]
	v_mfma_f32_16x16x32_f16 v[26:29], v[158:161], v[182:185], v[26:29]
	v_mfma_f32_16x16x32_f16 v[14:17], v[150:153], v[190:193], v[14:17]
	v_mfma_f32_16x16x32_f16 v[10:13], v[158:161], v[190:193], v[10:13]
	s_barrier
	s_add_u32 s22, s42, 0x158080
	s_addc_u32 s23, s43, 0
	s_add_i32 s42, s44, s48
	v_lshl_add_u64 v[140:141], s[22:23], 0, v[0:1]
	s_mov_b32 m0, s42
	s_nop 0
	global_load_lds_dwordx4 v[140:141], off
	v_lshl_add_u64 v[140:141], s[22:23], 0, v[134:135]
	s_add_i32 m0, s42, 0x2000
	s_nop 0
	global_load_lds_dwordx4 v[140:141], off
	s_waitcnt vmcnt(6)
	s_barrier
	v_mfma_f32_16x16x32_f16 v[54:57], v[194:197], v[162:165], v[54:57]
	v_mfma_f32_16x16x32_f16 v[50:53], v[202:205], v[162:165], v[50:53]
	v_mfma_f32_16x16x32_f16 v[38:41], v[194:197], v[170:173], v[38:41]
	v_mfma_f32_16x16x32_f16 v[34:37], v[202:205], v[170:173], v[34:37]
	v_mfma_f32_16x16x32_f16 v[22:25], v[194:197], v[178:181], v[22:25]
	v_mfma_f32_16x16x32_f16 v[18:21], v[202:205], v[178:181], v[18:21]
	v_mfma_f32_16x16x32_f16 v[6:9], v[194:197], v[186:189], v[6:9]
	v_mfma_f32_16x16x32_f16 v[2:5], v[202:205], v[186:189], v[2:5]
	v_mfma_f32_16x16x32_f16 v[54:57], v[198:201], v[166:169], v[54:57]
	v_mfma_f32_16x16x32_f16 v[50:53], v[220:223], v[166:169], v[50:53]
	v_mfma_f32_16x16x32_f16 v[38:41], v[198:201], v[174:177], v[38:41]
	v_mfma_f32_16x16x32_f16 v[34:37], v[220:223], v[174:177], v[34:37]
	v_mfma_f32_16x16x32_f16 v[22:25], v[198:201], v[182:185], v[22:25]
	v_mfma_f32_16x16x32_f16 v[18:21], v[220:223], v[182:185], v[18:21]
	v_mfma_f32_16x16x32_f16 v[6:9], v[198:201], v[190:193], v[6:9]
	v_mfma_f32_16x16x32_f16 v[2:5], v[220:223], v[190:193], v[2:5]
	s_add_i32 s29, s29, 2
	s_add_u32 s20, s20, 0x100
	s_addc_u32 s21, s21, 0
	s_cmpk_gt_u32 s29, 0x53
	s_mov_b64 s[22:23], s[26:27]
	s_barrier
	s_cbranch_scc0 .LBB0_61
	v_lshl_add_u32 v144, s35, 8, v146
	v_lshl_or_b32 v142, s50, 8, v148
	v_ashrrev_i32_e32 v145, 31, v144
	v_ashrrev_i32_e32 v143, 31, v142
	v_lshlrev_b64 v[140:141], 11, v[144:145]
	v_lshl_add_u64 v[140:141], v[140:141], 0, v[142:143]
	v_lshlrev_b64 v[140:141], 1, v[140:141]
	v_lshl_add_u64 v[154:155], s[94:95], 0, v[140:141]
	s_mov_b32 s101, 0
	global_load_dwordx4 v[158:161], v[154:155], off
	global_load_dwordx4 v[162:165], v[154:155], off offset:256
	s_mov_b32 s100, 0x10000
	v_lshl_add_u64 v[232:233], v[154:155], 0, s[100:101]
	global_load_dwordx4 v[166:169], v[232:233], off
	global_load_dwordx4 v[170:173], v[232:233], off offset:256
	s_mov_b32 s100, 0x20000
	v_lshl_add_u64 v[232:233], v[154:155], 0, s[100:101]
	global_load_dwordx4 v[174:177], v[232:233], off
	global_load_dwordx4 v[178:181], v[232:233], off offset:256
	s_mov_b32 s100, 0x30000
	v_lshl_add_u64 v[232:233], v[154:155], 0, s[100:101]
	global_load_dwordx4 v[182:185], v[232:233], off
	global_load_dwordx4 v[186:189], v[232:233], off offset:256
	s_mov_b32 s100, 0x80000
	v_lshl_add_u64 v[232:233], v[154:155], 0, s[100:101]
	global_load_dwordx4 v[190:193], v[232:233], off
	global_load_dwordx4 v[194:197], v[232:233], off offset:256
	s_mov_b32 s100, 0x90000
	v_lshl_add_u64 v[232:233], v[154:155], 0, s[100:101]
	global_load_dwordx4 v[198:201], v[232:233], off
	global_load_dwordx4 v[202:205], v[232:233], off offset:256
	s_mov_b32 s100, 0xa0000
	v_lshl_add_u64 v[232:233], v[154:155], 0, s[100:101]
	global_load_dwordx4 v[212:215], v[232:233], off
	global_load_dwordx4 v[220:223], v[232:233], off offset:256
	s_mov_b32 s100, 0xb0000
	v_lshl_add_u64 v[232:233], v[154:155], 0, s[100:101]
	global_load_dwordx4 v[224:227], v[232:233], off
	global_load_dwordx4 v[228:231], v[232:233], off offset:256
	s_mov_b64 s[4:5], 0xb0000
	s_and_b64 vcc, exec, s[38:39]
	s_mov_b32 s50, s72
	s_mov_b64 s[26:27], s[40:41]
	s_mov_b64 s[22:23], s[0:1]
	s_waitcnt vmcnt(15)
	v_mov_b64_e32 v[150:151], v[158:159]
	v_mov_b64_e32 v[152:153], v[160:161]
	v_cvt_f32_f16_e32 v156, v150
	v_cvt_f32_f16_sdwa v157, v150 dst_sel:DWORD dst_unused:UNUSED_PAD src0_sel:WORD_1
	v_cvt_f32_f16_e32 v150, v151
	v_cvt_f32_f16_sdwa v151, v151 dst_sel:DWORD dst_unused:UNUSED_PAD src0_sel:WORD_1
	v_pk_fma_f32 v[126:127], v[156:157], s[34:35], v[126:127] op_sel_hi:[1,0,1]
	s_nop 0
	v_cvt_pk_f16_f32 v126, v126, v127
	v_pk_fma_f32 v[128:129], v[150:151], s[34:35], v[128:129] op_sel_hi:[1,0,1]
	v_lshl_add_u64 v[150:151], s[8:9], 0, v[140:141]
	v_cvt_pk_f16_f32 v127, v128, v129
	v_cvt_f32_f16_e32 v128, v152
	v_cvt_f32_f16_sdwa v129, v152 dst_sel:DWORD dst_unused:UNUSED_PAD src0_sel:WORD_1
	v_pk_fma_f32 v[122:123], v[128:129], s[34:35], v[122:123] op_sel_hi:[1,0,1]
	s_nop 0
	v_cvt_pk_f16_f32 v128, v122, v123
	v_cvt_f32_f16_e32 v122, v153
	v_cvt_f32_f16_sdwa v123, v153 dst_sel:DWORD dst_unused:UNUSED_PAD src0_sel:WORD_1
	v_pk_fma_f32 v[122:123], v[122:123], s[34:35], v[124:125] op_sel_hi:[1,0,1]
	s_nop 0
	v_cvt_pk_f16_f32 v129, v122, v123
	s_nop 0
	global_store_dwordx4 v[150:151], v[126:129], off
	s_waitcnt vmcnt(15)
;     __device__ __forceinline__ void operator()(const f32x4 (&acc)[2][2][4][2], const Unit& u, int wr, int wc, int fr, int fq) const {
;     ...
;             for (int m = 0; m < 4; ++m) { const size_t off = (size_t)(row0 + ai * 128 + m * 16) * DM + colt;
; #pragma unroll
;                 for (int bj = 0; bj < 2; ++bj) {
;                     const h16x8 x = *(const h16x8*)(X + off + bj * 128);
;                     f32x4 o0, o1;
; #pragma unroll
;                     for (int e = 0; e < 4; ++e) { o0[e] = (float)x[e] * ALPHA + acc[ai][bj][m][0][e]; o1[e] = (float)x[4 + e] * ALPHA + acc[ai][bj][m][1][e]; }
;                     *(u32x4*)(PRE + off + bj * 128) = pack8(o0, o1); } }
	v_mov_b64_e32 v[122:123], v[162:163]
	v_mov_b64_e32 v[124:125], v[164:165]
	s_nop 0
	v_cvt_f32_f16_e32 v126, v122
	v_cvt_f32_f16_sdwa v127, v122 dst_sel:DWORD dst_unused:UNUSED_PAD src0_sel:WORD_1
	v_cvt_f32_f16_e32 v122, v123
	v_cvt_f32_f16_sdwa v123, v123 dst_sel:DWORD dst_unused:UNUSED_PAD src0_sel:WORD_1
	v_pk_fma_f32 v[118:119], v[126:127], s[34:35], v[118:119] op_sel_hi:[1,0,1]
	s_nop 0
	v_cvt_pk_f16_f32 v118, v118, v119
	v_pk_fma_f32 v[120:121], v[122:123], s[34:35], v[120:121] op_sel_hi:[1,0,1]
	s_nop 0
	v_cvt_pk_f16_f32 v119, v120, v121
	v_cvt_f32_f16_e32 v120, v124
	v_cvt_f32_f16_sdwa v121, v124 dst_sel:DWORD dst_unused:UNUSED_PAD src0_sel:WORD_1
	v_pk_fma_f32 v[114:115], v[120:121], s[34:35], v[114:115] op_sel_hi:[1,0,1]
	s_nop 0
	v_cvt_pk_f16_f32 v120, v114, v115
	v_cvt_f32_f16_e32 v114, v125
	v_cvt_f32_f16_sdwa v115, v125 dst_sel:DWORD dst_unused:UNUSED_PAD src0_sel:WORD_1
	v_pk_fma_f32 v[114:115], v[114:115], s[34:35], v[116:117] op_sel_hi:[1,0,1]
	s_nop 0
	v_cvt_pk_f16_f32 v121, v114, v115
	v_or_b32_e32 v114, 16, v144
	v_ashrrev_i32_e32 v115, 31, v114
	v_lshlrev_b64 v[114:115], 11, v[114:115]
	v_lshl_add_u64 v[114:115], v[114:115], 0, v[142:143]
	global_store_dwordx4 v[150:151], v[118:121], off offset:256
	s_nop 1
	v_lshlrev_b64 v[118:119], 1, v[114:115]
	v_lshl_add_u64 v[120:121], s[94:95], 0, v[118:119]
	s_waitcnt vmcnt(15)
	v_mov_b64_e32 v[114:115], v[166:167]
	v_mov_b64_e32 v[116:117], v[168:169]
	v_cvt_f32_f16_e32 v122, v114
	v_cvt_f32_f16_sdwa v123, v114 dst_sel:DWORD dst_unused:UNUSED_PAD src0_sel:WORD_1
	v_cvt_f32_f16_e32 v114, v115
	v_cvt_f32_f16_sdwa v115, v115 dst_sel:DWORD dst_unused:UNUSED_PAD src0_sel:WORD_1
	v_pk_fma_f32 v[110:111], v[122:123], s[34:35], v[110:111] op_sel_hi:[1,0,1]
	s_nop 0
	v_cvt_pk_f16_f32 v110, v110, v111
	v_pk_fma_f32 v[112:113], v[114:115], s[34:35], v[112:113] op_sel_hi:[1,0,1]
	v_lshl_add_u64 v[114:115], s[8:9], 0, v[118:119]
	v_cvt_pk_f16_f32 v111, v112, v113
	v_cvt_f32_f16_e32 v112, v116
	v_cvt_f32_f16_sdwa v113, v116 dst_sel:DWORD dst_unused:UNUSED_PAD src0_sel:WORD_1
	v_pk_fma_f32 v[106:107], v[112:113], s[34:35], v[106:107] op_sel_hi:[1,0,1]
	s_nop 0
	v_cvt_pk_f16_f32 v112, v106, v107
	v_cvt_f32_f16_e32 v106, v117
	v_cvt_f32_f16_sdwa v107, v117 dst_sel:DWORD dst_unused:UNUSED_PAD src0_sel:WORD_1
	v_pk_fma_f32 v[106:107], v[106:107], s[34:35], v[108:109] op_sel_hi:[1,0,1]
	s_nop 0
	v_cvt_pk_f16_f32 v113, v106, v107
	s_nop 0
	global_store_dwordx4 v[114:115], v[110:113], off
	s_waitcnt vmcnt(15)
	v_mov_b64_e32 v[106:107], v[170:171]
	v_mov_b64_e32 v[108:109], v[172:173]
	s_nop 0
	v_cvt_f32_f16_e32 v110, v106
	v_cvt_f32_f16_sdwa v111, v106 dst_sel:DWORD dst_unused:UNUSED_PAD src0_sel:WORD_1
	v_cvt_f32_f16_e32 v106, v107
	v_cvt_f32_f16_sdwa v107, v107 dst_sel:DWORD dst_unused:UNUSED_PAD src0_sel:WORD_1
	v_pk_fma_f32 v[102:103], v[110:111], s[34:35], v[102:103] op_sel_hi:[1,0,1]
	s_nop 0
	v_cvt_pk_f16_f32 v102, v102, v103
	v_pk_fma_f32 v[104:105], v[106:107], s[34:35], v[104:105] op_sel_hi:[1,0,1]
	s_nop 0
	v_cvt_pk_f16_f32 v103, v104, v105
	v_cvt_f32_f16_e32 v104, v108
	v_cvt_f32_f16_sdwa v105, v108 dst_sel:DWORD dst_unused:UNUSED_PAD src0_sel:WORD_1
	v_pk_fma_f32 v[98:99], v[104:105], s[34:35], v[98:99] op_sel_hi:[1,0,1]
	s_nop 0
	v_cvt_pk_f16_f32 v104, v98, v99
	v_cvt_f32_f16_e32 v98, v109
	v_cvt_f32_f16_sdwa v99, v109 dst_sel:DWORD dst_unused:UNUSED_PAD src0_sel:WORD_1
	v_pk_fma_f32 v[98:99], v[98:99], s[34:35], v[100:101] op_sel_hi:[1,0,1]
	s_nop 0
	v_cvt_pk_f16_f32 v105, v98, v99
	v_or_b32_e32 v98, 32, v144
	v_ashrrev_i32_e32 v99, 31, v98
	v_lshlrev_b64 v[98:99], 11, v[98:99]
	v_lshl_add_u64 v[98:99], v[98:99], 0, v[142:143]
	global_store_dwordx4 v[114:115], v[102:105], off offset:256
	s_nop 1
	v_lshlrev_b64 v[102:103], 1, v[98:99]
	v_lshl_add_u64 v[104:105], s[94:95], 0, v[102:103]
	s_waitcnt vmcnt(15)
	v_mov_b64_e32 v[98:99], v[174:175]
	v_mov_b64_e32 v[100:101], v[176:177]
	v_cvt_f32_f16_e32 v106, v98
	v_cvt_f32_f16_sdwa v107, v98 dst_sel:DWORD dst_unused:UNUSED_PAD src0_sel:WORD_1
	v_cvt_f32_f16_e32 v98, v99
	v_cvt_f32_f16_sdwa v99, v99 dst_sel:DWORD dst_unused:UNUSED_PAD src0_sel:WORD_1
	v_pk_fma_f32 v[94:95], v[106:107], s[34:35], v[94:95] op_sel_hi:[1,0,1]
	s_nop 0
	v_cvt_pk_f16_f32 v94, v94, v95
	v_pk_fma_f32 v[96:97], v[98:99], s[34:35], v[96:97] op_sel_hi:[1,0,1]
	v_lshl_add_u64 v[98:99], s[8:9], 0, v[102:103]
	v_cvt_pk_f16_f32 v95, v96, v97
	v_cvt_f32_f16_e32 v96, v100
	v_cvt_f32_f16_sdwa v97, v100 dst_sel:DWORD dst_unused:UNUSED_PAD src0_sel:WORD_1
	v_pk_fma_f32 v[90:91], v[96:97], s[34:35], v[90:91] op_sel_hi:[1,0,1]
	s_nop 0
	v_cvt_pk_f16_f32 v96, v90, v91
	v_cvt_f32_f16_e32 v90, v101
	v_cvt_f32_f16_sdwa v91, v101 dst_sel:DWORD dst_unused:UNUSED_PAD src0_sel:WORD_1
	v_pk_fma_f32 v[90:91], v[90:91], s[34:35], v[92:93] op_sel_hi:[1,0,1]
	s_nop 0
	v_cvt_pk_f16_f32 v97, v90, v91
	s_nop 0
	global_store_dwordx4 v[98:99], v[94:97], off
	s_waitcnt vmcnt(15)
	v_mov_b64_e32 v[90:91], v[178:179]
	v_mov_b64_e32 v[92:93], v[180:181]
	s_nop 0
	v_cvt_f32_f16_e32 v94, v90
	v_cvt_f32_f16_sdwa v95, v90 dst_sel:DWORD dst_unused:UNUSED_PAD src0_sel:WORD_1
	v_cvt_f32_f16_e32 v90, v91
	v_cvt_f32_f16_sdwa v91, v91 dst_sel:DWORD dst_unused:UNUSED_PAD src0_sel:WORD_1
	v_pk_fma_f32 v[86:87], v[94:95], s[34:35], v[86:87] op_sel_hi:[1,0,1]
	s_nop 0
	v_cvt_pk_f16_f32 v86, v86, v87
	v_pk_fma_f32 v[88:89], v[90:91], s[34:35], v[88:89] op_sel_hi:[1,0,1]
	s_nop 0
	v_cvt_pk_f16_f32 v87, v88, v89
	v_cvt_f32_f16_e32 v88, v92
	v_cvt_f32_f16_sdwa v89, v92 dst_sel:DWORD dst_unused:UNUSED_PAD src0_sel:WORD_1
	v_pk_fma_f32 v[82:83], v[88:89], s[34:35], v[82:83] op_sel_hi:[1,0,1]
	s_nop 0
	v_cvt_pk_f16_f32 v88, v82, v83
	v_cvt_f32_f16_e32 v82, v93
	v_cvt_f32_f16_sdwa v83, v93 dst_sel:DWORD dst_unused:UNUSED_PAD src0_sel:WORD_1
	v_pk_fma_f32 v[82:83], v[82:83], s[34:35], v[84:85] op_sel_hi:[1,0,1]
	s_nop 0
	v_cvt_pk_f16_f32 v89, v82, v83
	v_or_b32_e32 v82, 48, v144
	v_ashrrev_i32_e32 v83, 31, v82
	v_lshlrev_b64 v[82:83], 11, v[82:83]
	v_lshl_add_u64 v[82:83], v[82:83], 0, v[142:143]
	global_store_dwordx4 v[98:99], v[86:89], off offset:256
	s_nop 1
	v_lshlrev_b64 v[86:87], 1, v[82:83]
	v_lshl_add_u64 v[88:89], s[94:95], 0, v[86:87]
	s_waitcnt vmcnt(15)
;     __device__ __forceinline__ void operator()(const f32x4 (&acc)[2][2][4][2], const Unit& u, int wr, int wc, int fr, int fq) const {
;     ...
;             for (int m = 0; m < 4; ++m) { const size_t off = (size_t)(row0 + ai * 128 + m * 16) * DM + colt;
; #pragma unroll
;                 for (int bj = 0; bj < 2; ++bj) {
;                     const h16x8 x = *(const h16x8*)(X + off + bj * 128);
;                     f32x4 o0, o1;
; #pragma unroll
;                     for (int e = 0; e < 4; ++e) { o0[e] = (float)x[e] * ALPHA + acc[ai][bj][m][0][e]; o1[e] = (float)x[4 + e] * ALPHA + acc[ai][bj][m][1][e]; }
;                     *(u32x4*)(PRE + off + bj * 128) = pack8(o0, o1); } }
	v_mov_b64_e32 v[82:83], v[182:183]
	v_mov_b64_e32 v[84:85], v[184:185]
	v_cvt_f32_f16_e32 v90, v82
	v_cvt_f32_f16_sdwa v91, v82 dst_sel:DWORD dst_unused:UNUSED_PAD src0_sel:WORD_1
	v_cvt_f32_f16_e32 v82, v83
	v_cvt_f32_f16_sdwa v83, v83 dst_sel:DWORD dst_unused:UNUSED_PAD src0_sel:WORD_1
	v_pk_fma_f32 v[78:79], v[90:91], s[34:35], v[78:79] op_sel_hi:[1,0,1]
	s_nop 0
	v_cvt_pk_f16_f32 v78, v78, v79
	v_pk_fma_f32 v[80:81], v[82:83], s[34:35], v[80:81] op_sel_hi:[1,0,1]
	v_lshl_add_u64 v[82:83], s[8:9], 0, v[86:87]
	v_cvt_pk_f16_f32 v79, v80, v81
	v_cvt_f32_f16_e32 v80, v84
	v_cvt_f32_f16_sdwa v81, v84 dst_sel:DWORD dst_unused:UNUSED_PAD src0_sel:WORD_1
	v_pk_fma_f32 v[74:75], v[80:81], s[34:35], v[74:75] op_sel_hi:[1,0,1]
	s_nop 0
	v_cvt_pk_f16_f32 v80, v74, v75
	v_cvt_f32_f16_e32 v74, v85
	v_cvt_f32_f16_sdwa v75, v85 dst_sel:DWORD dst_unused:UNUSED_PAD src0_sel:WORD_1
	v_pk_fma_f32 v[74:75], v[74:75], s[34:35], v[76:77] op_sel_hi:[1,0,1]
	s_nop 0
	v_cvt_pk_f16_f32 v81, v74, v75
	s_nop 0
	global_store_dwordx4 v[82:83], v[78:81], off
	s_waitcnt vmcnt(15)
	v_mov_b64_e32 v[74:75], v[186:187]
	v_mov_b64_e32 v[76:77], v[188:189]
	s_nop 0
	v_cvt_f32_f16_e32 v78, v74
	v_cvt_f32_f16_sdwa v79, v74 dst_sel:DWORD dst_unused:UNUSED_PAD src0_sel:WORD_1
	v_cvt_f32_f16_e32 v74, v75
	v_cvt_f32_f16_sdwa v75, v75 dst_sel:DWORD dst_unused:UNUSED_PAD src0_sel:WORD_1
	v_pk_fma_f32 v[70:71], v[78:79], s[34:35], v[70:71] op_sel_hi:[1,0,1]
	s_nop 0
	v_cvt_pk_f16_f32 v70, v70, v71
	v_pk_fma_f32 v[72:73], v[74:75], s[34:35], v[72:73] op_sel_hi:[1,0,1]
	s_nop 0
	v_cvt_pk_f16_f32 v71, v72, v73
	v_cvt_f32_f16_e32 v72, v76
	v_cvt_f32_f16_sdwa v73, v76 dst_sel:DWORD dst_unused:UNUSED_PAD src0_sel:WORD_1
	v_pk_fma_f32 v[66:67], v[72:73], s[34:35], v[66:67] op_sel_hi:[1,0,1]
	s_nop 0
	v_cvt_pk_f16_f32 v72, v66, v67
	v_cvt_f32_f16_e32 v66, v77
	v_cvt_f32_f16_sdwa v67, v77 dst_sel:DWORD dst_unused:UNUSED_PAD src0_sel:WORD_1
	v_pk_fma_f32 v[66:67], v[66:67], s[34:35], v[68:69] op_sel_hi:[1,0,1]
	s_nop 0
	v_cvt_pk_f16_f32 v73, v66, v67
	global_store_dwordx4 v[82:83], v[70:73], off offset:256
	s_nop 1
	v_lshl_add_u64 v[70:71], v[140:141], 0, s[16:17]
	v_lshl_add_u64 v[72:73], s[94:95], 0, v[70:71]
	s_waitcnt vmcnt(15)
	v_mov_b64_e32 v[66:67], v[190:191]
	v_mov_b64_e32 v[68:69], v[192:193]
	v_cvt_f32_f16_e32 v74, v66
	v_cvt_f32_f16_sdwa v75, v66 dst_sel:DWORD dst_unused:UNUSED_PAD src0_sel:WORD_1
	v_cvt_f32_f16_e32 v66, v67
	v_cvt_f32_f16_sdwa v67, v67 dst_sel:DWORD dst_unused:UNUSED_PAD src0_sel:WORD_1
	v_pk_fma_f32 v[62:63], v[74:75], s[34:35], v[62:63] op_sel_hi:[1,0,1]
	s_nop 0
	v_cvt_pk_f16_f32 v62, v62, v63
	v_pk_fma_f32 v[64:65], v[66:67], s[34:35], v[64:65] op_sel_hi:[1,0,1]
	v_lshl_add_u64 v[66:67], s[8:9], 0, v[70:71]
	v_cvt_pk_f16_f32 v63, v64, v65
	v_cvt_f32_f16_e32 v64, v68
	v_cvt_f32_f16_sdwa v65, v68 dst_sel:DWORD dst_unused:UNUSED_PAD src0_sel:WORD_1
	v_pk_fma_f32 v[58:59], v[64:65], s[34:35], v[58:59] op_sel_hi:[1,0,1]
	s_nop 0
	v_cvt_pk_f16_f32 v64, v58, v59
	v_cvt_f32_f16_e32 v58, v69
	v_cvt_f32_f16_sdwa v59, v69 dst_sel:DWORD dst_unused:UNUSED_PAD src0_sel:WORD_1
	v_pk_fma_f32 v[58:59], v[58:59], s[34:35], v[60:61] op_sel_hi:[1,0,1]
	s_nop 0
	v_cvt_pk_f16_f32 v65, v58, v59
	s_nop 0
	global_store_dwordx4 v[66:67], v[62:65], off
	s_waitcnt vmcnt(15)
	v_mov_b64_e32 v[58:59], v[194:195]
	v_mov_b64_e32 v[60:61], v[196:197]
	s_nop 0
	v_cvt_f32_f16_e32 v62, v58
	v_cvt_f32_f16_sdwa v63, v58 dst_sel:DWORD dst_unused:UNUSED_PAD src0_sel:WORD_1
	v_cvt_f32_f16_e32 v58, v59
	v_cvt_f32_f16_sdwa v59, v59 dst_sel:DWORD dst_unused:UNUSED_PAD src0_sel:WORD_1
	v_pk_fma_f32 v[54:55], v[62:63], s[34:35], v[54:55] op_sel_hi:[1,0,1]
	s_nop 0
	v_cvt_pk_f16_f32 v54, v54, v55
	v_pk_fma_f32 v[56:57], v[58:59], s[34:35], v[56:57] op_sel_hi:[1,0,1]
	s_nop 0
	v_cvt_pk_f16_f32 v55, v56, v57
	v_cvt_f32_f16_e32 v56, v60
	v_cvt_f32_f16_sdwa v57, v60 dst_sel:DWORD dst_unused:UNUSED_PAD src0_sel:WORD_1
	v_pk_fma_f32 v[50:51], v[56:57], s[34:35], v[50:51] op_sel_hi:[1,0,1]
	s_nop 0
	v_cvt_pk_f16_f32 v56, v50, v51
	v_cvt_f32_f16_e32 v50, v61
	v_cvt_f32_f16_sdwa v51, v61 dst_sel:DWORD dst_unused:UNUSED_PAD src0_sel:WORD_1
	v_pk_fma_f32 v[50:51], v[50:51], s[34:35], v[52:53] op_sel_hi:[1,0,1]
	s_nop 0
	v_cvt_pk_f16_f32 v57, v50, v51
	global_store_dwordx4 v[66:67], v[54:57], off offset:256
	s_nop 1
	v_lshl_add_u64 v[54:55], v[140:141], 0, s[18:19]
	v_lshl_add_u64 v[56:57], s[94:95], 0, v[54:55]
	s_waitcnt vmcnt(15)
	v_mov_b64_e32 v[50:51], v[198:199]
	v_mov_b64_e32 v[52:53], v[200:201]
	v_cvt_f32_f16_e32 v58, v50
	v_cvt_f32_f16_sdwa v59, v50 dst_sel:DWORD dst_unused:UNUSED_PAD src0_sel:WORD_1
	v_cvt_f32_f16_e32 v50, v51
	v_cvt_f32_f16_sdwa v51, v51 dst_sel:DWORD dst_unused:UNUSED_PAD src0_sel:WORD_1
	v_pk_fma_f32 v[46:47], v[58:59], s[34:35], v[46:47] op_sel_hi:[1,0,1]
	s_nop 0
	v_cvt_pk_f16_f32 v46, v46, v47
	v_pk_fma_f32 v[48:49], v[50:51], s[34:35], v[48:49] op_sel_hi:[1,0,1]
	v_lshl_add_u64 v[50:51], s[8:9], 0, v[54:55]
	v_cvt_pk_f16_f32 v47, v48, v49
	v_cvt_f32_f16_e32 v48, v52
	v_cvt_f32_f16_sdwa v49, v52 dst_sel:DWORD dst_unused:UNUSED_PAD src0_sel:WORD_1
	v_pk_fma_f32 v[42:43], v[48:49], s[34:35], v[42:43] op_sel_hi:[1,0,1]
	s_nop 0
	v_cvt_pk_f16_f32 v48, v42, v43
	v_cvt_f32_f16_e32 v42, v53
	v_cvt_f32_f16_sdwa v43, v53 dst_sel:DWORD dst_unused:UNUSED_PAD src0_sel:WORD_1
	v_pk_fma_f32 v[42:43], v[42:43], s[34:35], v[44:45] op_sel_hi:[1,0,1]
	s_nop 0
	v_cvt_pk_f16_f32 v49, v42, v43
	s_nop 0
	global_store_dwordx4 v[50:51], v[46:49], off
	s_waitcnt vmcnt(15)
; #define PG8_WAIT_V(n) asm volatile("s_waitcnt vmcnt(" #n ")" ::: "memory")
; #define PG8_BAR __builtin_amdgcn_s_barrier()
; template <class Epi, class AMap>
; __device__ __forceinline__ void gemm_phase(LAS unsigned char* lds, const AMap am, const int lda, const h16* Bt, const int ldb, const int M, const int N, const int K, const Epi& E) {
;     ...
;         if (!has_next) break;
; #pragma unroll
;         for (int a = 0; a < 2; ++a)
; #pragma unroll
;             for (int b = 0; b < 2; ++b)
; #pragma unroll
;                 for (int m = 0; m < 4; ++m)
; #pragma unroll
;                     for (int n = 0; n < 2; ++n) acc[a][b][m][n] = (f32x4){0.f, 0.f, 0.f, 0.f};
;         cur = nxt; cA = nA; cB = nB; ++ui;
;     }
;     PG8_WAIT_V(0);
;     if (wr == 0) PG8_BAR;
;     PG8_BAR;
;     __device__ __forceinline__ void operator()(const f32x4 (&acc)[2][2][4][2], const Unit& u, int wr, int wc, int fr, int fq) const {
;     ...
;             for (int m = 0; m < 4; ++m) { const size_t off = (size_t)(row0 + ai * 128 + m * 16) * DM + colt;
; #pragma unroll
;                 for (int bj = 0; bj < 2; ++bj) {
;                     const h16x8 x = *(const h16x8*)(X + off + bj * 128);
;                     f32x4 o0, o1;
; #pragma unroll
;                     for (int e = 0; e < 4; ++e) { o0[e] = (float)x[e] * ALPHA + acc[ai][bj][m][0][e]; o1[e] = (float)x[4 + e] * ALPHA + acc[ai][bj][m][1][e]; }
;                     *(u32x4*)(PRE + off + bj * 128) = pack8(o0, o1); } }
	v_mov_b64_e32 v[42:43], v[202:203]
	v_mov_b64_e32 v[44:45], v[204:205]
	s_nop 0
	v_cvt_f32_f16_e32 v46, v42
	v_cvt_f32_f16_sdwa v47, v42 dst_sel:DWORD dst_unused:UNUSED_PAD src0_sel:WORD_1
	v_cvt_f32_f16_e32 v42, v43
	v_cvt_f32_f16_sdwa v43, v43 dst_sel:DWORD dst_unused:UNUSED_PAD src0_sel:WORD_1
	v_pk_fma_f32 v[38:39], v[46:47], s[34:35], v[38:39] op_sel_hi:[1,0,1]
	s_nop 0
	v_cvt_pk_f16_f32 v38, v38, v39
	v_pk_fma_f32 v[40:41], v[42:43], s[34:35], v[40:41] op_sel_hi:[1,0,1]
	s_nop 0
	v_cvt_pk_f16_f32 v39, v40, v41
	v_cvt_f32_f16_e32 v40, v44
	v_cvt_f32_f16_sdwa v41, v44 dst_sel:DWORD dst_unused:UNUSED_PAD src0_sel:WORD_1
	v_pk_fma_f32 v[34:35], v[40:41], s[34:35], v[34:35] op_sel_hi:[1,0,1]
	s_nop 0
	v_cvt_pk_f16_f32 v40, v34, v35
	v_cvt_f32_f16_e32 v34, v45
	v_cvt_f32_f16_sdwa v35, v45 dst_sel:DWORD dst_unused:UNUSED_PAD src0_sel:WORD_1
	v_pk_fma_f32 v[34:35], v[34:35], s[34:35], v[36:37] op_sel_hi:[1,0,1]
	s_nop 0
	v_cvt_pk_f16_f32 v41, v34, v35
	global_store_dwordx4 v[50:51], v[38:41], off offset:256
	s_nop 1
	v_lshl_add_u64 v[38:39], v[140:141], 0, s[14:15]
	v_lshl_add_u64 v[40:41], s[94:95], 0, v[38:39]
	s_waitcnt vmcnt(15)
	v_mov_b64_e32 v[34:35], v[212:213]
	v_mov_b64_e32 v[36:37], v[214:215]
	v_cvt_f32_f16_e32 v42, v34
	v_cvt_f32_f16_sdwa v43, v34 dst_sel:DWORD dst_unused:UNUSED_PAD src0_sel:WORD_1
	v_cvt_f32_f16_e32 v34, v35
	v_cvt_f32_f16_sdwa v35, v35 dst_sel:DWORD dst_unused:UNUSED_PAD src0_sel:WORD_1
	v_pk_fma_f32 v[30:31], v[42:43], s[34:35], v[30:31] op_sel_hi:[1,0,1]
	s_nop 0
	v_cvt_pk_f16_f32 v30, v30, v31
	v_pk_fma_f32 v[32:33], v[34:35], s[34:35], v[32:33] op_sel_hi:[1,0,1]
	v_lshl_add_u64 v[34:35], s[8:9], 0, v[38:39]
	v_cvt_pk_f16_f32 v31, v32, v33
	v_cvt_f32_f16_e32 v32, v36
	v_cvt_f32_f16_sdwa v33, v36 dst_sel:DWORD dst_unused:UNUSED_PAD src0_sel:WORD_1
	v_pk_fma_f32 v[26:27], v[32:33], s[34:35], v[26:27] op_sel_hi:[1,0,1]
	s_nop 0
	v_cvt_pk_f16_f32 v32, v26, v27
	v_cvt_f32_f16_e32 v26, v37
	v_cvt_f32_f16_sdwa v27, v37 dst_sel:DWORD dst_unused:UNUSED_PAD src0_sel:WORD_1
	v_pk_fma_f32 v[26:27], v[26:27], s[34:35], v[28:29] op_sel_hi:[1,0,1]
	s_nop 0
	v_cvt_pk_f16_f32 v33, v26, v27
	s_nop 0
	global_store_dwordx4 v[34:35], v[30:33], off
	s_waitcnt vmcnt(15)
	v_mov_b64_e32 v[26:27], v[220:221]
	v_mov_b64_e32 v[28:29], v[222:223]
	s_nop 0
	v_cvt_f32_f16_e32 v30, v26
	v_cvt_f32_f16_sdwa v31, v26 dst_sel:DWORD dst_unused:UNUSED_PAD src0_sel:WORD_1
	v_cvt_f32_f16_e32 v26, v27
	v_cvt_f32_f16_sdwa v27, v27 dst_sel:DWORD dst_unused:UNUSED_PAD src0_sel:WORD_1
	v_pk_fma_f32 v[22:23], v[30:31], s[34:35], v[22:23] op_sel_hi:[1,0,1]
	s_nop 0
	v_cvt_pk_f16_f32 v22, v22, v23
	v_pk_fma_f32 v[24:25], v[26:27], s[34:35], v[24:25] op_sel_hi:[1,0,1]
	s_nop 0
	v_cvt_pk_f16_f32 v23, v24, v25
	v_cvt_f32_f16_e32 v24, v28
	v_cvt_f32_f16_sdwa v25, v28 dst_sel:DWORD dst_unused:UNUSED_PAD src0_sel:WORD_1
	v_pk_fma_f32 v[18:19], v[24:25], s[34:35], v[18:19] op_sel_hi:[1,0,1]
	s_nop 0
	v_cvt_pk_f16_f32 v24, v18, v19
	v_cvt_f32_f16_e32 v18, v29
	v_cvt_f32_f16_sdwa v19, v29 dst_sel:DWORD dst_unused:UNUSED_PAD src0_sel:WORD_1
	v_pk_fma_f32 v[18:19], v[18:19], s[34:35], v[20:21] op_sel_hi:[1,0,1]
	s_nop 0
	v_cvt_pk_f16_f32 v25, v18, v19
	global_store_dwordx4 v[34:35], v[22:25], off offset:256
	s_nop 1
	v_lshl_add_u64 v[22:23], v[140:141], 0, s[4:5]
	v_lshl_add_u64 v[24:25], s[94:95], 0, v[22:23]
	s_waitcnt vmcnt(15)
	v_mov_b64_e32 v[18:19], v[224:225]
	v_mov_b64_e32 v[20:21], v[226:227]
	v_cvt_f32_f16_e32 v26, v18
	v_cvt_f32_f16_sdwa v27, v18 dst_sel:DWORD dst_unused:UNUSED_PAD src0_sel:WORD_1
	v_cvt_f32_f16_e32 v18, v19
	v_cvt_f32_f16_sdwa v19, v19 dst_sel:DWORD dst_unused:UNUSED_PAD src0_sel:WORD_1
	v_pk_fma_f32 v[14:15], v[26:27], s[34:35], v[14:15] op_sel_hi:[1,0,1]
	s_nop 0
	v_cvt_pk_f16_f32 v14, v14, v15
	v_pk_fma_f32 v[16:17], v[18:19], s[34:35], v[16:17] op_sel_hi:[1,0,1]
	v_lshl_add_u64 v[18:19], s[8:9], 0, v[22:23]
	v_cvt_pk_f16_f32 v15, v16, v17
	v_cvt_f32_f16_e32 v16, v20
	v_cvt_f32_f16_sdwa v17, v20 dst_sel:DWORD dst_unused:UNUSED_PAD src0_sel:WORD_1
	v_pk_fma_f32 v[10:11], v[16:17], s[34:35], v[10:11] op_sel_hi:[1,0,1]
	s_nop 0
	v_cvt_pk_f16_f32 v16, v10, v11
	v_cvt_f32_f16_e32 v10, v21
	v_cvt_f32_f16_sdwa v11, v21 dst_sel:DWORD dst_unused:UNUSED_PAD src0_sel:WORD_1
	v_pk_fma_f32 v[10:11], v[10:11], s[34:35], v[12:13] op_sel_hi:[1,0,1]
	s_nop 0
	v_cvt_pk_f16_f32 v17, v10, v11
	s_nop 0
	global_store_dwordx4 v[18:19], v[14:17], off
	s_waitcnt vmcnt(15)
	v_mov_b64_e32 v[10:11], v[228:229]
	v_mov_b64_e32 v[12:13], v[230:231]
	s_nop 0
	v_cvt_f32_f16_e32 v14, v10
	v_cvt_f32_f16_sdwa v15, v10 dst_sel:DWORD dst_unused:UNUSED_PAD src0_sel:WORD_1
	v_cvt_f32_f16_e32 v10, v11
	v_cvt_f32_f16_sdwa v11, v11 dst_sel:DWORD dst_unused:UNUSED_PAD src0_sel:WORD_1
	v_pk_fma_f32 v[6:7], v[14:15], s[34:35], v[6:7] op_sel_hi:[1,0,1]
	s_nop 0
	v_cvt_pk_f16_f32 v6, v6, v7
	v_pk_fma_f32 v[8:9], v[10:11], s[34:35], v[8:9] op_sel_hi:[1,0,1]
	s_nop 0
	v_cvt_pk_f16_f32 v7, v8, v9
	v_cvt_f32_f16_e32 v8, v12
	v_cvt_f32_f16_sdwa v9, v12 dst_sel:DWORD dst_unused:UNUSED_PAD src0_sel:WORD_1
	v_pk_fma_f32 v[2:3], v[8:9], s[34:35], v[2:3] op_sel_hi:[1,0,1]
	s_nop 0
	v_cvt_pk_f16_f32 v8, v2, v3
	v_cvt_f32_f16_e32 v2, v13
	v_cvt_f32_f16_sdwa v3, v13 dst_sel:DWORD dst_unused:UNUSED_PAD src0_sel:WORD_1
	v_pk_fma_f32 v[2:3], v[2:3], s[34:35], v[4:5] op_sel_hi:[1,0,1]
	s_nop 0
	v_cvt_pk_f16_f32 v9, v2, v3
	s_mov_b32 s35, s73
	global_store_dwordx4 v[18:19], v[6:9], off offset:256
	s_cbranch_vccz .LBB0_50
	s_waitcnt vmcnt(0)
	s_cmpk_gt_u32 s46, 0xff
	s_cbranch_scc1 .LBB0_65
	s_barrier

; #define PG8_STAGE(bufoff, gbase, voff) do { _Pragma("unroll") for (int _i = 0; _i < 2; ++_i) \
;         __builtin_amdgcn_global_load_lds((const unsigned*)((const char*)(gbase) + (voff)[_i]), (LAS unsigned*)(lds + (bufoff) + ldsw + _i * 8192), 16, 0, 0); } while (0)
; #define PG8_LDA(dst, b, h) do { _Pragma("unroll") for (int m = 0; m < 4; ++m) _Pragma("unroll") for (int k = 0; k < 2; ++k) dst[m][k] = *(const LAS h16x8*)(lds + PG8_SA(b, h) + aoff + m * 2048 + k * 1024); } while (0)
; #define PG8_LDB(dst, b, h) do { _Pragma("unroll") for (int n = 0; n < 2; ++n) _Pragma("unroll") for (int k = 0; k < 2; ++k) dst[n][k] = *(const LAS h16x8*)(lds + PG8_SB(b, h) + boff + n * 2048 + k * 1024); } while (0)
; #define PG8_MMA(ai, bj, At, Bt_) do { __builtin_amdgcn_s_setprio(1); _Pragma("unroll") for (int m = 0; m < 4; ++m) _Pragma("unroll") for (int n = 0; n < 2; ++n) _Pragma("unroll") for (int k = 0; k < 2; ++k) \
;         acc[ai][bj][m][n] = __builtin_amdgcn_mfma_f32_16x16x32_f16(Bt_[n][k], At[m][k], acc[ai][bj][m][n], 0, 0, 0); __builtin_amdgcn_s_setprio(0); } while (0)
; #define PG8_WAIT_V(n) asm volatile("s_waitcnt vmcnt(" #n ")" ::: "memory")
; template <class Epi, class AMap>
; __device__ __forceinline__ void gemm_phase(LAS unsigned char* lds, const AMap am, const int lda, const h16* Bt, const int ldb, const int M, const int N, const int K, const Epi& E) {
;     ...
;         for (int t = 0; t < nt; t += 2) {
;             const bool last = (t == nt - 2);
;             const char* a1 = cA + (size_t)(t + 1) * kstep;
;             const char* a2 = last ? nA : cA + (size_t)(t + 2) * kstep; const char* b2 = last ? nB : cB + (size_t)(t + 2) * kstep;
;             const char* a3 = a2 + kstep; const char* b3 = b2 + kstep;
;             PG8_LDB(B0, 0, 0); PG8_SCHED; PG8_LDA(At, 0, 0); PG8_STAGE(PG8_SA(1, 1), a1 + hstepA, voffA);
;             PG8_WAIT_L(8); PG8_BAR; PG8_WAIT_L(0); PG8_MMA(0, 0, At, B0); PG8_BAR; PG8_SCHED;
;             PG8_LDB(B1, 0, 1); PG8_STAGE(PG8_SB(0, 0), b2, voffB);
;             PG8_BAR; PG8_WAIT_L(0); PG8_MMA(0, 1, At, B1); PG8_BAR;
;             PG8_LDA(At, 0, 1); PG8_STAGE(PG8_SA(0, 0), a2, voffA);
;             PG8_BAR; PG8_WAIT_L(0); PG8_MMA(1, 0, At, B0); PG8_BAR; PG8_SCHED;
;             PG8_STAGE(PG8_SB(0, 1), b2 + hstepB, voffB);
;             PG8_WAIT_V(6); PG8_BAR; PG8_MMA(1, 1, At, B1); PG8_BAR;
.LBB0_92:
	s_add_u32 s0, vcc_lo, 0xfff80080
	s_addc_u32 s1, vcc_hi, -1
	s_add_i32 s67, 0, 0x10000
	v_add_u32_e32 v78, s67, v169
	ds_read_b128 v[66:69], v78
	ds_read_b128 v[70:73], v78 offset:1024
	ds_read_b128 v[74:77], v78 offset:2048
	ds_read_b128 v[78:81], v78 offset:3072
	s_cmp_eq_u32 s60, 28
	s_cselect_b32 s27, s69, s1
	s_cselect_b32 s26, s29, s0
	s_cselect_b32 s49, s73, s66
	s_cselect_b32 s48, s20, s21
	v_lshl_add_u64 v[192:193], vcc, 0, v[172:173]
	s_add_i32 m0, s81, 0xc000
	ds_read_b128 v[90:93], v195
	ds_read_b128 v[94:97], v195 offset:1024
	ds_read_b128 v[98:101], v195 offset:2048
	ds_read_b128 v[102:105], v195 offset:3072
	ds_read_b128 v[176:179], v195 offset:4096
	ds_read_b128 v[180:183], v195 offset:5120
	ds_read_b128 v[184:187], v195 offset:6144
	ds_read_b128 v[188:191], v195 offset:7168
	global_load_lds_dwordx4 v[192:193], off
	v_lshl_add_u64 v[192:193], vcc, 0, v[174:175]
	s_add_i32 m0, s81, 0xe000
	s_nop 0
	global_load_lds_dwordx4 v[192:193], off
	s_waitcnt lgkmcnt(8)
	s_barrier
	s_waitcnt lgkmcnt(0)
	s_waitcnt lgkmcnt(0)
	v_mfma_f32_16x16x32_f16 v[158:161], v[66:69], v[90:93], v[158:161]
	v_mfma_f32_16x16x32_f16 v[154:157], v[74:77], v[90:93], v[154:157]
	v_mfma_f32_16x16x32_f16 v[142:145], v[66:69], v[98:101], v[142:145]
	v_mfma_f32_16x16x32_f16 v[134:137], v[74:77], v[98:101], v[134:137]
	v_mfma_f32_16x16x32_f16 v[126:129], v[66:69], v[176:179], v[126:129]
	v_mfma_f32_16x16x32_f16 v[118:121], v[74:77], v[176:179], v[118:121]
	v_mfma_f32_16x16x32_f16 v[110:113], v[66:69], v[184:187], v[110:113]
	v_mfma_f32_16x16x32_f16 v[106:109], v[74:77], v[184:187], v[106:109]
	v_mfma_f32_16x16x32_f16 v[158:161], v[70:73], v[94:97], v[158:161]
	v_mfma_f32_16x16x32_f16 v[154:157], v[78:81], v[94:97], v[154:157]
	v_mfma_f32_16x16x32_f16 v[142:145], v[70:73], v[102:105], v[142:145]
	v_mfma_f32_16x16x32_f16 v[134:137], v[78:81], v[102:105], v[134:137]
	v_mfma_f32_16x16x32_f16 v[126:129], v[70:73], v[180:183], v[126:129]
	v_mfma_f32_16x16x32_f16 v[118:121], v[78:81], v[180:183], v[118:121]
	v_mfma_f32_16x16x32_f16 v[110:113], v[70:73], v[188:191], v[110:113]
	v_mfma_f32_16x16x32_f16 v[106:109], v[78:81], v[188:191], v[106:109]
	s_barrier
	s_add_i32 s65, 0, 0x14000
	v_add_u32_e32 v192, s65, v169
	s_add_i32 s0, s67, s64
	ds_read_b128 v[196:199], v192
	ds_read_b128 v[200:203], v192 offset:1024
	ds_read_b128 v[204:207], v192 offset:2048
	ds_read_b128 v[220:223], v192 offset:3072
	v_lshl_add_u64 v[192:193], s[48:49], 0, v[0:1]
	s_mov_b32 m0, s0
	v_lshl_add_u64 v[212:213], s[48:49], 0, v[162:163]
	global_load_lds_dwordx4 v[192:193], off
	s_add_i32 m0, s0, 0x2000
	s_nop 0
	global_load_lds_dwordx4 v[212:213], off
	s_barrier
	s_waitcnt lgkmcnt(0)
	s_waitcnt lgkmcnt(0)
	v_mfma_f32_16x16x32_f16 v[150:153], v[196:199], v[90:93], v[150:153]
	v_mfma_f32_16x16x32_f16 v[90:93], v[204:207], v[90:93], v[146:149]
	v_mfma_f32_16x16x32_f16 v[150:153], v[200:203], v[94:97], v[150:153]
	v_mfma_f32_16x16x32_f16 v[90:93], v[220:223], v[94:97], v[90:93]
	v_mfma_f32_16x16x32_f16 v[94:97], v[196:199], v[98:101], v[138:141]
	v_mfma_f32_16x16x32_f16 v[98:101], v[204:207], v[98:101], v[130:133]
	v_mfma_f32_16x16x32_f16 v[114:117], v[204:207], v[176:179], v[114:117]
	v_mfma_f32_16x16x32_f16 v[86:89], v[196:199], v[184:187], v[86:89]
	v_mfma_f32_16x16x32_f16 v[82:85], v[204:207], v[184:187], v[82:85]
	v_mfma_f32_16x16x32_f16 v[94:97], v[200:203], v[102:105], v[94:97]
	v_mfma_f32_16x16x32_f16 v[98:101], v[220:223], v[102:105], v[98:101]
	v_mfma_f32_16x16x32_f16 v[102:105], v[196:199], v[176:179], v[122:125]
	v_mfma_f32_16x16x32_f16 v[114:117], v[220:223], v[180:183], v[114:117]
	v_mfma_f32_16x16x32_f16 v[86:89], v[200:203], v[188:191], v[86:89]
	v_mfma_f32_16x16x32_f16 v[82:85], v[220:223], v[188:191], v[82:85]
	v_mfma_f32_16x16x32_f16 v[102:105], v[200:203], v[180:183], v[102:105]
	s_mov_b32 m0, s81
	v_lshl_add_u64 v[214:215], s[26:27], 0, v[166:167]
	s_barrier
	ds_read_b128 v[122:125], v195 offset:16384
	ds_read_b128 v[130:133], v195 offset:17408
	ds_read_b128 v[138:141], v195 offset:18432
	ds_read_b128 v[146:149], v195 offset:19456
	ds_read_b128 v[176:179], v195 offset:20480
	ds_read_b128 v[180:183], v195 offset:21504
	ds_read_b128 v[184:187], v195 offset:22528
	ds_read_b128 v[188:191], v195 offset:23552
	global_load_lds_dwordx4 v[214:215], off
	v_lshl_add_u64 v[216:217], s[26:27], 0, v[164:165]
	s_mov_b32 m0, s82
	s_nop 0
	global_load_lds_dwordx4 v[216:217], off
	s_barrier
	s_waitcnt lgkmcnt(0)
	s_waitcnt lgkmcnt(0)
	v_mfma_f32_16x16x32_f16 v[62:65], v[66:69], v[122:125], v[62:65]
	v_mfma_f32_16x16x32_f16 v[58:61], v[74:77], v[122:125], v[58:61]
	v_mfma_f32_16x16x32_f16 v[46:49], v[66:69], v[138:141], v[46:49]
	v_mfma_f32_16x16x32_f16 v[38:41], v[74:77], v[138:141], v[38:41]
	v_mfma_f32_16x16x32_f16 v[30:33], v[66:69], v[176:179], v[30:33]
	v_mfma_f32_16x16x32_f16 v[22:25], v[74:77], v[176:179], v[22:25]
	v_mfma_f32_16x16x32_f16 v[14:17], v[66:69], v[184:187], v[14:17]
	v_mfma_f32_16x16x32_f16 v[10:13], v[74:77], v[184:187], v[10:13]
	v_mfma_f32_16x16x32_f16 v[62:65], v[70:73], v[130:133], v[62:65]
	v_mfma_f32_16x16x32_f16 v[58:61], v[78:81], v[130:133], v[58:61]
	v_mfma_f32_16x16x32_f16 v[46:49], v[70:73], v[146:149], v[46:49]
	v_mfma_f32_16x16x32_f16 v[38:41], v[78:81], v[146:149], v[38:41]
	v_mfma_f32_16x16x32_f16 v[30:33], v[70:73], v[180:183], v[30:33]
	v_mfma_f32_16x16x32_f16 v[22:25], v[78:81], v[180:183], v[22:25]
	v_mfma_f32_16x16x32_f16 v[14:17], v[70:73], v[188:191], v[14:17]
	v_mfma_f32_16x16x32_f16 v[10:13], v[78:81], v[188:191], v[10:13]
	s_barrier
; #define PG8_STAGE(bufoff, gbase, voff) do { _Pragma("unroll") for (int _i = 0; _i < 2; ++_i) \
;         __builtin_amdgcn_global_load_lds((const unsigned*)((const char*)(gbase) + (voff)[_i]), (LAS unsigned*)(lds + (bufoff) + ldsw + _i * 8192), 16, 0, 0); } while (0)
; #define PG8_LDA(dst, b, h) do { _Pragma("unroll") for (int m = 0; m < 4; ++m) _Pragma("unroll") for (int k = 0; k < 2; ++k) dst[m][k] = *(const LAS h16x8*)(lds + PG8_SA(b, h) + aoff + m * 2048 + k * 1024); } while (0)
; #define PG8_LDB(dst, b, h) do { _Pragma("unroll") for (int n = 0; n < 2; ++n) _Pragma("unroll") for (int k = 0; k < 2; ++k) dst[n][k] = *(const LAS h16x8*)(lds + PG8_SB(b, h) + boff + n * 2048 + k * 1024); } while (0)
; #define PG8_MMA(ai, bj, At, Bt_) do { __builtin_amdgcn_s_setprio(1); _Pragma("unroll") for (int m = 0; m < 4; ++m) _Pragma("unroll") for (int n = 0; n < 2; ++n) _Pragma("unroll") for (int k = 0; k < 2; ++k) \
;         acc[ai][bj][m][n] = __builtin_amdgcn_mfma_f32_16x16x32_f16(Bt_[n][k], At[m][k], acc[ai][bj][m][n], 0, 0, 0); __builtin_amdgcn_s_setprio(0); } while (0)
; #define PG8_WAIT_V(n) asm volatile("s_waitcnt vmcnt(" #n ")" ::: "memory")
; #define PG8_WAIT_L(n) asm volatile("s_waitcnt lgkmcnt(" #n ")" ::: "memory")
; #define PG8_BAR __builtin_amdgcn_s_barrier()
; #define PG8_SCHED __builtin_amdgcn_sched_barrier(0)
; template <class Epi, class AMap>
; __device__ __forceinline__ void gemm_phase(LAS unsigned char* lds, const AMap am, const int lda, const h16* Bt, const int ldb, const int M, const int N, const int K, const Epi& E) {
;     ...
;             PG8_BAR; PG8_WAIT_L(0); PG8_MMA(1, 0, At, B0); PG8_BAR; PG8_SCHED;
;             PG8_STAGE(PG8_SB(0, 1), b2 + hstepB, voffB);
;             PG8_WAIT_V(6); PG8_BAR; PG8_MMA(1, 1, At, B1); PG8_BAR;
;             PG8_LDB(B0, 1, 0); PG8_SCHED; PG8_LDA(At, 1, 0); PG8_STAGE(PG8_SA(0, 1), a2 + hstepA, voffA);
;             PG8_WAIT_L(8); PG8_BAR; PG8_WAIT_L(0); PG8_MMA(0, 0, At, B0); PG8_BAR; PG8_SCHED;
;             PG8_LDB(B1, 1, 1); PG8_STAGE(PG8_SB(1, 0), b3, voffB);
;             PG8_BAR; PG8_WAIT_L(0); PG8_MMA(0, 1, At, B1); PG8_BAR;
;             PG8_LDA(At, 1, 1); PG8_STAGE(PG8_SA(1, 0), a3, voffA);
;             PG8_BAR; PG8_WAIT_L(0); PG8_MMA(1, 0, At, B0); PG8_BAR; PG8_SCHED;
	s_add_u32 s0, s48, 0x80000
	s_addc_u32 s1, s49, 0
	s_add_i32 s65, s65, s64
	v_lshl_add_u64 v[66:67], s[0:1], 0, v[0:1]
	s_mov_b32 m0, s65
	s_nop 0
	global_load_lds_dwordx4 v[66:67], off
	v_lshl_add_u64 v[66:67], s[0:1], 0, v[162:163]
	s_add_i32 m0, s65, 0x2000
	s_nop 0
	global_load_lds_dwordx4 v[66:67], off
	s_waitcnt vmcnt(6)
	s_barrier
	v_mfma_f32_16x16x32_f16 v[54:57], v[196:199], v[122:125], v[54:57]
	v_mfma_f32_16x16x32_f16 v[50:53], v[204:207], v[122:125], v[50:53]
	v_mfma_f32_16x16x32_f16 v[42:45], v[196:199], v[138:141], v[42:45]
	v_mfma_f32_16x16x32_f16 v[34:37], v[204:207], v[138:141], v[34:37]
	v_mfma_f32_16x16x32_f16 v[26:29], v[196:199], v[176:179], v[26:29]
	v_mfma_f32_16x16x32_f16 v[18:21], v[204:207], v[176:179], v[18:21]
	v_mfma_f32_16x16x32_f16 v[6:9], v[196:199], v[184:187], v[6:9]
	v_mfma_f32_16x16x32_f16 v[2:5], v[204:207], v[184:187], v[2:5]
	v_mfma_f32_16x16x32_f16 v[54:57], v[200:203], v[130:133], v[54:57]
	v_mfma_f32_16x16x32_f16 v[50:53], v[220:223], v[130:133], v[50:53]
	v_mfma_f32_16x16x32_f16 v[42:45], v[200:203], v[146:149], v[42:45]
	v_mfma_f32_16x16x32_f16 v[34:37], v[220:223], v[146:149], v[34:37]
	v_mfma_f32_16x16x32_f16 v[26:29], v[200:203], v[180:183], v[26:29]
	v_mfma_f32_16x16x32_f16 v[18:21], v[220:223], v[180:183], v[18:21]
	v_mfma_f32_16x16x32_f16 v[6:9], v[200:203], v[188:191], v[6:9]
	v_mfma_f32_16x16x32_f16 v[2:5], v[220:223], v[188:191], v[2:5]
	s_add_i32 s65, 0, 0x18000
	v_add_u32_e32 v78, s65, v169
	s_barrier
	ds_read_b128 v[66:69], v78
	ds_read_b128 v[70:73], v78 offset:1024
	ds_read_b128 v[74:77], v78 offset:2048
	ds_read_b128 v[78:81], v78 offset:3072
	s_add_u32 s0, s26, 0x80000
	s_addc_u32 s1, s27, 0
	s_mov_b32 m0, s83
	v_lshl_add_u64 v[138:139], s[0:1], 0, v[166:167]
	ds_read_b128 v[122:125], v195 offset:32768
	ds_read_b128 v[130:133], v195 offset:33792
	ds_read_b128 v[176:179], v195 offset:34816
	ds_read_b128 v[180:183], v195 offset:35840
	ds_read_b128 v[184:187], v195 offset:36864
	ds_read_b128 v[188:191], v195 offset:37888
	ds_read_b128 v[196:199], v195 offset:38912
	ds_read_b128 v[200:203], v195 offset:39936
	global_load_lds_dwordx4 v[138:139], off
	v_lshl_add_u64 v[138:139], s[0:1], 0, v[164:165]
	s_mov_b32 m0, s50
	s_nop 0
	global_load_lds_dwordx4 v[138:139], off
	s_waitcnt lgkmcnt(8)
	s_barrier
	s_waitcnt lgkmcnt(0)
	s_waitcnt lgkmcnt(0)
	v_mfma_f32_16x16x32_f16 v[138:141], v[66:69], v[122:125], v[158:161]
	v_mfma_f32_16x16x32_f16 v[158:161], v[70:73], v[130:133], v[138:141]
	v_mfma_f32_16x16x32_f16 v[138:141], v[74:77], v[122:125], v[154:157]
	v_mfma_f32_16x16x32_f16 v[154:157], v[78:81], v[130:133], v[138:141]
	v_mfma_f32_16x16x32_f16 v[138:141], v[66:69], v[176:179], v[142:145]
	v_mfma_f32_16x16x32_f16 v[134:137], v[74:77], v[176:179], v[134:137]
	v_mfma_f32_16x16x32_f16 v[126:129], v[66:69], v[184:187], v[126:129]
	v_mfma_f32_16x16x32_f16 v[118:121], v[74:77], v[184:187], v[118:121]
	v_mfma_f32_16x16x32_f16 v[110:113], v[66:69], v[196:199], v[110:113]
	v_mfma_f32_16x16x32_f16 v[106:109], v[74:77], v[196:199], v[106:109]
	v_mfma_f32_16x16x32_f16 v[142:145], v[70:73], v[180:183], v[138:141]
	v_mfma_f32_16x16x32_f16 v[134:137], v[78:81], v[180:183], v[134:137]
	v_mfma_f32_16x16x32_f16 v[126:129], v[70:73], v[188:191], v[126:129]
	v_mfma_f32_16x16x32_f16 v[118:121], v[78:81], v[188:191], v[118:121]
	v_mfma_f32_16x16x32_f16 v[110:113], v[70:73], v[200:203], v[110:113]
	v_mfma_f32_16x16x32_f16 v[106:109], v[78:81], v[200:203], v[106:109]
	s_barrier
	s_add_i32 s26, 0, 0x1c000
	v_add_u32_e32 v138, s26, v169
	s_add_i32 s0, s65, s64
	ds_read_b128 v[204:207], v138
	ds_read_b128 v[220:223], v138 offset:1024
	ds_read_b128 v[224:227], v138 offset:2048
	ds_read_b128 v[228:231], v138 offset:3072
	v_lshl_add_u64 v[138:139], v[192:193], 0, s[92:93]
	s_mov_b32 m0, s0
	s_nop 0
	global_load_lds_dwordx4 v[138:139], off
	v_lshl_add_u64 v[138:139], v[212:213], 0, s[92:93]
	s_add_i32 m0, s0, 0x2000
	s_nop 0
	global_load_lds_dwordx4 v[138:139], off
	s_barrier
	s_waitcnt lgkmcnt(0)
	s_waitcnt lgkmcnt(0)
	v_mfma_f32_16x16x32_f16 v[90:93], v[224:227], v[122:125], v[90:93]
	v_mfma_f32_16x16x32_f16 v[138:141], v[204:207], v[122:125], v[150:153]
	v_mfma_f32_16x16x32_f16 v[146:149], v[228:231], v[130:133], v[90:93]
	v_mfma_f32_16x16x32_f16 v[90:93], v[204:207], v[176:179], v[94:97]
	v_mfma_f32_16x16x32_f16 v[150:153], v[220:223], v[130:133], v[138:141]
	v_mfma_f32_16x16x32_f16 v[138:141], v[220:223], v[180:183], v[90:93]
	v_mfma_f32_16x16x32_f16 v[90:93], v[224:227], v[176:179], v[98:101]
	v_mfma_f32_16x16x32_f16 v[130:133], v[228:231], v[180:183], v[90:93]
	v_mfma_f32_16x16x32_f16 v[90:93], v[204:207], v[184:187], v[102:105]
	v_mfma_f32_16x16x32_f16 v[122:125], v[220:223], v[188:191], v[90:93]
	v_mfma_f32_16x16x32_f16 v[90:93], v[224:227], v[184:187], v[114:117]
	v_mfma_f32_16x16x32_f16 v[86:89], v[204:207], v[196:199], v[86:89]
	v_mfma_f32_16x16x32_f16 v[82:85], v[224:227], v[196:199], v[82:85]
	v_mfma_f32_16x16x32_f16 v[114:117], v[228:231], v[188:191], v[90:93]
	v_mfma_f32_16x16x32_f16 v[86:89], v[220:223], v[200:203], v[86:89]
	v_mfma_f32_16x16x32_f16 v[82:85], v[228:231], v[200:203], v[82:85]
	s_mov_b32 m0, s89
	v_lshl_add_u64 v[192:193], v[214:215], 0, s[92:93]
	s_barrier
	ds_read_b128 v[90:93], v195 offset:49152
	ds_read_b128 v[94:97], v195 offset:50176
	ds_read_b128 v[98:101], v195 offset:51200
	ds_read_b128 v[102:105], v195 offset:52224
	ds_read_b128 v[176:179], v195 offset:53248
	ds_read_b128 v[180:183], v195 offset:54272
	ds_read_b128 v[184:187], v195 offset:55296
	ds_read_b128 v[188:191], v195 offset:56320
	global_load_lds_dwordx4 v[192:193], off
	v_lshl_add_u64 v[192:193], v[216:217], 0, s[92:93]
	s_mov_b32 m0, s35
	s_nop 0
	global_load_lds_dwordx4 v[192:193], off
	s_barrier
; template <int CTRL> __device__ __forceinline__ float dpp_f(float x) { return __int_as_float(__builtin_amdgcn_update_dpp(0, __float_as_int(x), CTRL, 0xF, 0xF, true)); }
; #define PG8_STAGE(bufoff, gbase, voff) do { _Pragma("unroll") for (int _i = 0; _i < 2; ++_i) \
;         __builtin_amdgcn_global_load_lds((const unsigned*)((const char*)(gbase) + (voff)[_i]), (LAS unsigned*)(lds + (bufoff) + ldsw + _i * 8192), 16, 0, 0); } while (0)
; #define PG8_WAIT_V(n) asm volatile("s_waitcnt vmcnt(" #n ")" ::: "memory")
; #define PG8_BAR __builtin_amdgcn_s_barrier()
; template <class Epi, class AMap>
; __device__ __forceinline__ void gemm_phase(LAS unsigned char* lds, const AMap am, const int lda, const h16* Bt, const int ldb, const int M, const int N, const int K, const Epi& E) {
;     ...
;             PG8_BAR; PG8_WAIT_L(0); PG8_MMA(1, 0, At, B0); PG8_BAR; PG8_SCHED;
;             PG8_STAGE(PG8_SB(1, 1), b3 + hstepB, voffB);
;             PG8_WAIT_V(6); PG8_BAR; PG8_MMA(1, 1, At, B1); PG8_BAR;
;         }
;     __device__ __forceinline__ void operator()(const f32x4 (&acc)[2][2][4][2], const Unit& u, int wr, int wc, int fr, int fq) const {
;         const int row0 = u.pm * 256 + wr * 64 + fr, f0 = u.pn * 128 + wc * 32 + 8 * fq;
;         f32x4 w0[2], w1[2], w2[2], bb[2];
; #pragma unroll
;         for (int n = 0; n < 2; ++n) { w0[n] = *(const f32x4*)(cw + f0 + 4 * n); w1[n] = *(const f32x4*)(cw + FF + f0 + 4 * n); w2[n] = *(const f32x4*)(cw + 2 * FF + f0 + 4 * n); bb[n] = *(const f32x4*)(cb + f0 + 4 * n); }
; #pragma unroll
;         for (int ai = 0; ai < 2; ++ai) {
;             f32x4 p1[2], p2[2];
; #pragma unroll
;             for (int n = 0; n < 2; ++n) { p1[n] = (f32x4){0.f, 0.f, 0.f, 0.f}; p2[n] = p1[n]; }
; #pragma unroll
;             for (int m = 0; m < 4; ++m) {
;                 const int row = row0 + ai * 128 + m * 16;
;                 f32x4 r1[2], r2[2], o[2];
; #pragma unroll
;                 for (int n = 0; n < 2; ++n)
; #pragma unroll
;                     for (int e = 0; e < 4; ++e) {
;                         const float g = acc[ai][1][m][n][e];
;                         r1[n][e] = dpp_f<0x121>(g); r2[n][e] = dpp_f<0x122>(g);
;                         const float g1 = fr >= 1 ? r1[n][e] : p1[n][e], g2 = fr >= 2 ? r2[n][e] : p2[n][e];
;                         const float gc = bb[n][e] + g2 * w0[n][e] + g1 * w1[n][e] + g * w2[n][e];
	s_waitcnt lgkmcnt(0)
	s_waitcnt lgkmcnt(0)
	v_mfma_f32_16x16x32_f16 v[62:65], v[66:69], v[90:93], v[62:65]
	v_mfma_f32_16x16x32_f16 v[58:61], v[74:77], v[90:93], v[58:61]
	v_mfma_f32_16x16x32_f16 v[46:49], v[66:69], v[98:101], v[46:49]
	v_mfma_f32_16x16x32_f16 v[38:41], v[74:77], v[98:101], v[38:41]
	v_mfma_f32_16x16x32_f16 v[30:33], v[66:69], v[176:179], v[30:33]
	v_mfma_f32_16x16x32_f16 v[22:25], v[74:77], v[176:179], v[22:25]
	v_mfma_f32_16x16x32_f16 v[14:17], v[66:69], v[184:187], v[14:17]
	v_mfma_f32_16x16x32_f16 v[10:13], v[74:77], v[184:187], v[10:13]
	v_mfma_f32_16x16x32_f16 v[62:65], v[70:73], v[94:97], v[62:65]
	v_mfma_f32_16x16x32_f16 v[58:61], v[78:81], v[94:97], v[58:61]
	v_mfma_f32_16x16x32_f16 v[46:49], v[70:73], v[102:105], v[46:49]
	v_mfma_f32_16x16x32_f16 v[38:41], v[78:81], v[102:105], v[38:41]
	v_mfma_f32_16x16x32_f16 v[30:33], v[70:73], v[180:183], v[30:33]
	v_mfma_f32_16x16x32_f16 v[22:25], v[78:81], v[180:183], v[22:25]
	v_mfma_f32_16x16x32_f16 v[14:17], v[70:73], v[188:191], v[14:17]
	v_mfma_f32_16x16x32_f16 v[10:13], v[78:81], v[188:191], v[10:13]
	s_barrier
	s_add_u32 s0, s48, 0x80080
	s_addc_u32 s1, s49, 0
	s_add_i32 s26, s26, s64
	v_lshl_add_u64 v[66:67], s[0:1], 0, v[0:1]
	s_mov_b32 m0, s26
	s_nop 0
	global_load_lds_dwordx4 v[66:67], off
	v_lshl_add_u64 v[66:67], s[0:1], 0, v[162:163]
	s_add_i32 m0, s26, 0x2000
	s_nop 0
	global_load_lds_dwordx4 v[66:67], off
	s_waitcnt vmcnt(6)
	s_barrier
	v_mfma_f32_16x16x32_f16 v[54:57], v[204:207], v[90:93], v[54:57]
	v_mfma_f32_16x16x32_f16 v[50:53], v[224:227], v[90:93], v[50:53]
	v_mfma_f32_16x16x32_f16 v[42:45], v[204:207], v[98:101], v[42:45]
	v_mfma_f32_16x16x32_f16 v[34:37], v[224:227], v[98:101], v[34:37]
	v_mfma_f32_16x16x32_f16 v[26:29], v[204:207], v[176:179], v[26:29]
	v_mfma_f32_16x16x32_f16 v[18:21], v[224:227], v[176:179], v[18:21]
	v_mfma_f32_16x16x32_f16 v[6:9], v[204:207], v[184:187], v[6:9]
	v_mfma_f32_16x16x32_f16 v[2:5], v[224:227], v[184:187], v[2:5]
	v_mfma_f32_16x16x32_f16 v[54:57], v[220:223], v[94:97], v[54:57]
	v_mfma_f32_16x16x32_f16 v[50:53], v[228:231], v[94:97], v[50:53]
	v_mfma_f32_16x16x32_f16 v[42:45], v[220:223], v[102:105], v[42:45]
	v_mfma_f32_16x16x32_f16 v[34:37], v[228:231], v[102:105], v[34:37]
	v_mfma_f32_16x16x32_f16 v[26:29], v[220:223], v[180:183], v[26:29]
	v_mfma_f32_16x16x32_f16 v[18:21], v[228:231], v[180:183], v[18:21]
	v_mfma_f32_16x16x32_f16 v[6:9], v[220:223], v[188:191], v[6:9]
	v_mfma_f32_16x16x32_f16 v[2:5], v[228:231], v[188:191], v[2:5]
	s_add_i32 s60, s60, 2
	s_add_u32 vcc_lo, vcc_lo, 0x100
	s_addc_u32 vcc_hi, vcc_hi, 0
	s_add_u32 s21, s21, 0x100
	s_addc_u32 s66, s66, 0
	s_cmp_gt_u32 s60, 29
	s_barrier
	s_cbranch_scc0 .LBB0_92
	v_lshl_or_b32 v176, s23, 7, v194
	v_ashrrev_i32_e32 v177, 31, v176
	v_lshlrev_b64 v[66:67], 2, v[176:177]
	v_lshl_add_u64 v[70:71], s[74:75], 0, v[66:67]
	v_lshl_add_u64 v[74:75], s[8:9], 0, v[66:67]
	v_lshl_add_u64 v[78:79], s[70:71], 0, v[66:67]
	v_lshl_add_u64 v[102:103], s[78:79], 0, v[66:67]
	global_load_dwordx4 v[66:69], v[70:71], off offset:16
	global_load_dwordx4 v[90:93], v[70:71], off
	s_nop 0
	global_load_dwordx4 v[70:73], v[74:75], off offset:16
	global_load_dwordx4 v[94:97], v[74:75], off
	s_nop 0
	global_load_dwordx4 v[74:77], v[78:79], off offset:16
	global_load_dwordx4 v[98:101], v[78:79], off
	s_nop 0
	global_load_dwordx4 v[78:81], v[102:103], off offset:16
	s_nop 0
	global_load_dwordx4 v[102:105], v[102:103], off
	s_lshl_b32 s20, s22, 8
	s_add_i32 s20, s20, s51
	v_or_b32_e32 v196, s20, v168
	v_mov_b32_dpp v192, v150 row_ror:1 row_mask:0xf bank_mask:0xf bound_ctrl:1
	v_mov_b32_dpp v190, v150 row_ror:2 row_mask:0xf bank_mask:0xf bound_ctrl:1
	v_mov_b32_dpp v193, v151 row_ror:1 row_mask:0xf bank_mask:0xf bound_ctrl:1
	v_mov_b32_dpp v191, v151 row_ror:2 row_mask:0xf bank_mask:0xf bound_ctrl:1
	v_mov_b32_dpp v188, v152 row_ror:1 row_mask:0xf bank_mask:0xf bound_ctrl:1
	v_mov_b32_dpp v186, v152 row_ror:2 row_mask:0xf bank_mask:0xf bound_ctrl:1
	v_mov_b32_dpp v189, v153 row_ror:1 row_mask:0xf bank_mask:0xf bound_ctrl:1
	v_mov_b32_dpp v187, v153 row_ror:2 row_mask:0xf bank_mask:0xf bound_ctrl:1
	v_mov_b32_dpp v184, v146 row_ror:1 row_mask:0xf bank_mask:0xf bound_ctrl:1
	v_mov_b32_dpp v182, v146 row_ror:2 row_mask:0xf bank_mask:0xf bound_ctrl:1
	v_mov_b32_dpp v185, v147 row_ror:1 row_mask:0xf bank_mask:0xf bound_ctrl:1
	v_mov_b32_dpp v183, v147 row_ror:2 row_mask:0xf bank_mask:0xf bound_ctrl:1
	v_mov_b32_dpp v180, v148 row_ror:1 row_mask:0xf bank_mask:0xf bound_ctrl:1
	v_mov_b32_dpp v178, v148 row_ror:2 row_mask:0xf bank_mask:0xf bound_ctrl:1
	v_mov_b32_dpp v181, v149 row_ror:1 row_mask:0xf bank_mask:0xf bound_ctrl:1
	v_mov_b32_dpp v179, v149 row_ror:2 row_mask:0xf bank_mask:0xf bound_ctrl:1
	s_and_saveexec_b64 s[22:23], s[40:41]
	s_cbranch_execz .LBB0_95
; template <int CTRL> __device__ __forceinline__ float dpp_f(float x) { return __int_as_float(__builtin_amdgcn_update_dpp(0, __float_as_int(x), CTRL, 0xF, 0xF, true)); }
;     __device__ __forceinline__ void operator()(const f32x4 (&acc)[2][2][4][2], const Unit& u, int wr, int wc, int fr, int fq) const {
;     ...
;                     for (int e = 0; e < 4; ++e) {
;                         const float g = acc[ai][1][m][n][e];
;                         r1[n][e] = dpp_f<0x121>(g); r2[n][e] = dpp_f<0x122>(g);
;                         const float g1 = fr >= 1 ? r1[n][e] : p1[n][e], g2 = fr >= 2 ? r2[n][e] : p2[n][e];
;                         const float gc = bb[n][e] + g2 * w0[n][e] + g1 * w1[n][e] + g * w2[n][e];
;                         o[n][e] = gelu_mul(acc[ai][0][m][n][e], gc);
;                     }
;                 if (m > 0 || fr >= 2) *(u32x4*)(ACT + (size_t)row * FF + f0) = pack8(o[0], o[1]);
	s_waitcnt vmcnt(0)
	v_pk_fma_f32 v[198:199], v[90:91], v[190:191], v[102:103]
	v_readlane_b32 s0, v254, 58
	v_pk_fma_f32 v[198:199], v[94:95], v[192:193], v[198:199]
	v_readlane_b32 s1, v254, 59
	v_pk_fma_f32 v[198:199], v[150:151], v[98:99], v[198:199]
	s_nop 0
	v_pk_mul_f32 v[200:201], v[198:199], v[198:199]
	v_pk_mul_f32 v[202:203], v[158:159], v[198:199]
	v_fmamk_f32 v197, v201, 0x3dd2d3e7, v241
	v_mul_f32_e64 v197, v199, -v197
	v_exp_f32_e32 v197, v197
	s_nop 0
	v_add_f32_e32 v197, 1.0, v197
	v_rcp_f32_e32 v201, v197
	v_fmamk_f32 v197, v200, 0x3dd2d3e7, v241
	v_mul_f32_e64 v197, v198, -v197
	v_exp_f32_e32 v197, v197
	s_nop 0
	v_add_f32_e32 v197, 1.0, v197
	v_rcp_f32_e32 v200, v197
	s_nop 0
	v_pk_mul_f32 v[198:199], v[202:203], v[200:201]
	v_pk_fma_f32 v[200:201], v[92:93], v[186:187], v[104:105]
	v_cvt_pk_f16_f32 v198, v198, v199
	v_pk_fma_f32 v[200:201], v[96:97], v[188:189], v[200:201]
	s_nop 0
	v_pk_fma_f32 v[200:201], v[152:153], v[100:101], v[200:201]
	s_nop 0
	v_pk_mul_f32 v[202:203], v[200:201], v[200:201]
	v_pk_mul_f32 v[204:205], v[160:161], v[200:201]
	v_fmamk_f32 v197, v203, 0x3dd2d3e7, v241
	v_mul_f32_e64 v197, v201, -v197
	v_exp_f32_e32 v197, v197
	s_nop 0
	v_add_f32_e32 v197, 1.0, v197
	v_rcp_f32_e32 v203, v197
	v_fmamk_f32 v197, v202, 0x3dd2d3e7, v241
	v_mul_f32_e64 v197, v200, -v197
	v_exp_f32_e32 v197, v197
	s_nop 0
	v_add_f32_e32 v197, 1.0, v197
	v_rcp_f32_e32 v202, v197
	s_nop 0
	v_pk_mul_f32 v[200:201], v[204:205], v[202:203]
	s_nop 0
	v_cvt_pk_f16_f32 v199, v200, v201
	v_pk_fma_f32 v[200:201], v[66:67], v[182:183], v[78:79]
	s_nop 0
	v_pk_fma_f32 v[200:201], v[70:71], v[184:185], v[200:201]
	s_nop 0
	v_pk_fma_f32 v[200:201], v[146:147], v[74:75], v[200:201]
	s_nop 0
	v_pk_mul_f32 v[202:203], v[200:201], v[200:201]
	v_pk_mul_f32 v[204:205], v[154:155], v[200:201]
	v_fmamk_f32 v197, v203, 0x3dd2d3e7, v241
	v_mul_f32_e64 v197, v201, -v197
	v_exp_f32_e32 v197, v197
	s_nop 0
	v_add_f32_e32 v197, 1.0, v197
	v_rcp_f32_e32 v203, v197
	v_fmamk_f32 v197, v202, 0x3dd2d3e7, v241
	v_mul_f32_e64 v197, v200, -v197
	v_exp_f32_e32 v197, v197
	s_nop 0
	v_add_f32_e32 v197, 1.0, v197
	v_rcp_f32_e32 v202, v197
	s_nop 0
	v_pk_mul_f32 v[200:201], v[204:205], v[202:203]
	v_pk_fma_f32 v[202:203], v[68:69], v[178:179], v[80:81]
	v_cvt_pk_f16_f32 v200, v200, v201
	v_pk_fma_f32 v[202:203], v[72:73], v[180:181], v[202:203]
	s_nop 0
	v_pk_fma_f32 v[202:203], v[148:149], v[76:77], v[202:203]
	s_nop 0
	v_pk_mul_f32 v[204:205], v[202:203], v[202:203]
	v_pk_mul_f32 v[206:207], v[156:157], v[202:203]
	v_fmamk_f32 v197, v204, 0x3dd2d3e7, v241
	v_mul_f32_e64 v197, v202, -v197
	v_exp_f32_e32 v197, v197
	s_nop 0
	v_add_f32_e32 v197, 1.0, v197
	v_rcp_f32_e32 v204, v197
	v_fmamk_f32 v197, v205, 0x3dd2d3e7, v241
	v_mul_f32_e64 v197, v203, -v197
	v_exp_f32_e32 v197, v197
	s_nop 0
	v_add_f32_e32 v197, 1.0, v197
	v_rcp_f32_e32 v205, v197
	s_nop 0
	v_pk_mul_f32 v[202:203], v[206:207], v[204:205]
	s_nop 0
	v_cvt_pk_f16_f32 v201, v202, v203
	v_mov_b64_e32 v[202:203], s[0:1]
	v_mad_i64_i32 v[202:203], s[26:27], v196, s13, v[202:203]
	v_lshl_add_u64 v[202:203], v[176:177], 1, v[202:203]
	global_store_dwordx4 v[202:203], v[198:201], off

; #define PG8_STAGE(bufoff, gbase, voff) do { _Pragma("unroll") for (int _i = 0; _i < 2; ++_i) \
;         __builtin_amdgcn_global_load_lds((const unsigned*)((const char*)(gbase) + (voff)[_i]), (LAS unsigned*)(lds + (bufoff) + ldsw + _i * 8192), 16, 0, 0); } while (0)
; #define PG8_LDA(dst, b, h) do { _Pragma("unroll") for (int m = 0; m < 4; ++m) _Pragma("unroll") for (int k = 0; k < 2; ++k) dst[m][k] = *(const LAS h16x8*)(lds + PG8_SA(b, h) + aoff + m * 2048 + k * 1024); } while (0)
; #define PG8_LDB(dst, b, h) do { _Pragma("unroll") for (int n = 0; n < 2; ++n) _Pragma("unroll") for (int k = 0; k < 2; ++k) dst[n][k] = *(const LAS h16x8*)(lds + PG8_SB(b, h) + boff + n * 2048 + k * 1024); } while (0)
; #define PG8_MMA(ai, bj, At, Bt_) do { __builtin_amdgcn_s_setprio(1); _Pragma("unroll") for (int m = 0; m < 4; ++m) _Pragma("unroll") for (int n = 0; n < 2; ++n) _Pragma("unroll") for (int k = 0; k < 2; ++k) \
;         acc[ai][bj][m][n] = __builtin_amdgcn_mfma_f32_16x16x32_f16(Bt_[n][k], At[m][k], acc[ai][bj][m][n], 0, 0, 0); __builtin_amdgcn_s_setprio(0); } while (0)
; #define PG8_WAIT_V(n) asm volatile("s_waitcnt vmcnt(" #n ")" ::: "memory")
; template <class Epi, class AMap>
; __device__ __forceinline__ void gemm_phase(LAS unsigned char* lds, const AMap am, const int lda, const h16* Bt, const int ldb, const int M, const int N, const int K, const Epi& E) {
;     ...
;         for (int t = 0; t < nt; t += 2) {
;             const bool last = (t == nt - 2);
;             const char* a1 = cA + (size_t)(t + 1) * kstep;
;             const char* a2 = last ? nA : cA + (size_t)(t + 2) * kstep; const char* b2 = last ? nB : cB + (size_t)(t + 2) * kstep;
;             const char* a3 = a2 + kstep; const char* b3 = b2 + kstep;
;             PG8_LDB(B0, 0, 0); PG8_SCHED; PG8_LDA(At, 0, 0); PG8_STAGE(PG8_SA(1, 1), a1 + hstepA, voffA);
;             PG8_WAIT_L(8); PG8_BAR; PG8_WAIT_L(0); PG8_MMA(0, 0, At, B0); PG8_BAR; PG8_SCHED;
;             PG8_LDB(B1, 0, 1); PG8_STAGE(PG8_SB(0, 0), b2, voffB);
;             PG8_BAR; PG8_WAIT_L(0); PG8_MMA(0, 1, At, B1); PG8_BAR;
;             PG8_LDA(At, 0, 1); PG8_STAGE(PG8_SA(0, 0), a2, voffA);
;             PG8_BAR; PG8_WAIT_L(0); PG8_MMA(1, 0, At, B0); PG8_BAR; PG8_SCHED;
;             PG8_STAGE(PG8_SB(0, 1), b2 + hstepB, voffB);
;             PG8_WAIT_V(6); PG8_BAR; PG8_MMA(1, 1, At, B1); PG8_BAR;
.LBB0_147:
	s_add_u32 s46, s26, 0xfff80080
	s_addc_u32 s47, s27, -1
	s_add_i32 s60, 0, 0x10000
	v_add_u32_e32 v144, s60, v147
	ds_read_b128 v[140:143], v144
	ds_read_b128 v[150:153], v144 offset:1024
	ds_read_b128 v[154:157], v144 offset:2048
	ds_read_b128 v[158:161], v144 offset:3072
	s_cmp_eq_u32 s51, 28
	s_cselect_b32 s49, s41, s47
	s_cselect_b32 s48, s29, s46
	s_cselect_b32 s47, s1, s50
	s_cselect_b32 s46, s20, s21
	v_lshl_add_u64 v[144:145], s[26:27], 0, v[136:137]
	s_add_i32 m0, s23, 0xc000
	ds_read_b128 v[162:165], v149
	ds_read_b128 v[166:169], v149 offset:1024
	ds_read_b128 v[170:173], v149 offset:2048
	ds_read_b128 v[174:177], v149 offset:3072
	ds_read_b128 v[178:181], v149 offset:4096
	ds_read_b128 v[182:185], v149 offset:5120
	ds_read_b128 v[186:189], v149 offset:6144
	ds_read_b128 v[190:193], v149 offset:7168
	global_load_lds_dwordx4 v[144:145], off
	v_lshl_add_u64 v[144:145], s[26:27], 0, v[138:139]
	s_add_i32 m0, s23, 0xe000
	s_nop 0
	global_load_lds_dwordx4 v[144:145], off
	s_waitcnt lgkmcnt(8)
	s_barrier
	s_waitcnt lgkmcnt(0)
	s_waitcnt lgkmcnt(0)
	v_mfma_f32_16x16x32_f16 v[126:129], v[140:143], v[162:165], v[126:129]
	v_mfma_f32_16x16x32_f16 v[122:125], v[154:157], v[162:165], v[122:125]
	v_mfma_f32_16x16x32_f16 v[110:113], v[140:143], v[170:173], v[110:113]
	v_mfma_f32_16x16x32_f16 v[106:109], v[154:157], v[170:173], v[106:109]
	v_mfma_f32_16x16x32_f16 v[94:97], v[140:143], v[178:181], v[94:97]
	v_mfma_f32_16x16x32_f16 v[90:93], v[154:157], v[178:181], v[90:93]
	v_mfma_f32_16x16x32_f16 v[78:81], v[140:143], v[186:189], v[78:81]
	v_mfma_f32_16x16x32_f16 v[74:77], v[154:157], v[186:189], v[74:77]
	v_mfma_f32_16x16x32_f16 v[126:129], v[150:153], v[166:169], v[126:129]
	v_mfma_f32_16x16x32_f16 v[122:125], v[158:161], v[166:169], v[122:125]
	v_mfma_f32_16x16x32_f16 v[110:113], v[150:153], v[174:177], v[110:113]
	v_mfma_f32_16x16x32_f16 v[106:109], v[158:161], v[174:177], v[106:109]
	v_mfma_f32_16x16x32_f16 v[94:97], v[150:153], v[182:185], v[94:97]
	v_mfma_f32_16x16x32_f16 v[90:93], v[158:161], v[182:185], v[90:93]
	v_mfma_f32_16x16x32_f16 v[78:81], v[150:153], v[190:193], v[78:81]
	v_mfma_f32_16x16x32_f16 v[74:77], v[158:161], v[190:193], v[74:77]
	s_barrier
	s_add_i32 s66, 0, 0x14000
	v_add_u32_e32 v144, s66, v147
	s_add_i32 s60, s60, s64
	ds_read_b128 v[194:197], v144
	ds_read_b128 v[198:201], v144 offset:1024
	ds_read_b128 v[202:205], v144 offset:2048
	ds_read_b128 v[220:223], v144 offset:3072
	v_lshl_add_u64 v[144:145], s[46:47], 0, v[0:1]
	s_mov_b32 m0, s60
	v_lshl_add_u64 v[206:207], s[46:47], 0, v[134:135]
	global_load_lds_dwordx4 v[144:145], off
	s_add_i32 m0, s60, 0x2000
	s_nop 0
	global_load_lds_dwordx4 v[206:207], off
	s_barrier
	s_waitcnt lgkmcnt(0)
	s_waitcnt lgkmcnt(0)
	v_mfma_f32_16x16x32_f16 v[118:121], v[194:197], v[162:165], v[118:121]
	v_mfma_f32_16x16x32_f16 v[114:117], v[202:205], v[162:165], v[114:117]
	v_mfma_f32_16x16x32_f16 v[102:105], v[194:197], v[170:173], v[102:105]
	v_mfma_f32_16x16x32_f16 v[98:101], v[202:205], v[170:173], v[98:101]
	v_mfma_f32_16x16x32_f16 v[86:89], v[194:197], v[178:181], v[86:89]
	v_mfma_f32_16x16x32_f16 v[82:85], v[202:205], v[178:181], v[82:85]
	v_mfma_f32_16x16x32_f16 v[70:73], v[194:197], v[186:189], v[70:73]
	v_mfma_f32_16x16x32_f16 v[66:69], v[202:205], v[186:189], v[66:69]
	v_mfma_f32_16x16x32_f16 v[118:121], v[198:201], v[166:169], v[118:121]
	v_mfma_f32_16x16x32_f16 v[114:117], v[220:223], v[166:169], v[114:117]
	v_mfma_f32_16x16x32_f16 v[102:105], v[198:201], v[174:177], v[102:105]
	v_mfma_f32_16x16x32_f16 v[98:101], v[220:223], v[174:177], v[98:101]
	v_mfma_f32_16x16x32_f16 v[86:89], v[198:201], v[182:185], v[86:89]
	v_mfma_f32_16x16x32_f16 v[82:85], v[220:223], v[182:185], v[82:85]
	v_mfma_f32_16x16x32_f16 v[70:73], v[198:201], v[190:193], v[70:73]
	v_mfma_f32_16x16x32_f16 v[66:69], v[220:223], v[190:193], v[66:69]
	s_mov_b32 m0, s23
	v_lshl_add_u64 v[212:213], s[48:49], 0, v[130:131]
	s_barrier
	ds_read_b128 v[162:165], v149 offset:16384
	ds_read_b128 v[166:169], v149 offset:17408
	ds_read_b128 v[170:173], v149 offset:18432
	ds_read_b128 v[174:177], v149 offset:19456
	ds_read_b128 v[178:181], v149 offset:20480
	ds_read_b128 v[182:185], v149 offset:21504
	ds_read_b128 v[186:189], v149 offset:22528
	ds_read_b128 v[190:193], v149 offset:23552
	global_load_lds_dwordx4 v[212:213], off
	v_lshl_add_u64 v[214:215], s[48:49], 0, v[132:133]
	s_mov_b32 m0, s71
	s_nop 0
	global_load_lds_dwordx4 v[214:215], off
	s_barrier
	s_waitcnt lgkmcnt(0)
	s_waitcnt lgkmcnt(0)
	v_mfma_f32_16x16x32_f16 v[62:65], v[140:143], v[162:165], v[62:65]
	v_mfma_f32_16x16x32_f16 v[58:61], v[154:157], v[162:165], v[58:61]
	v_mfma_f32_16x16x32_f16 v[46:49], v[140:143], v[170:173], v[46:49]
	v_mfma_f32_16x16x32_f16 v[42:45], v[154:157], v[170:173], v[42:45]
	v_mfma_f32_16x16x32_f16 v[30:33], v[140:143], v[178:181], v[30:33]
	v_mfma_f32_16x16x32_f16 v[26:29], v[154:157], v[178:181], v[26:29]
	v_mfma_f32_16x16x32_f16 v[14:17], v[140:143], v[186:189], v[14:17]
	v_mfma_f32_16x16x32_f16 v[10:13], v[154:157], v[186:189], v[10:13]
	v_mfma_f32_16x16x32_f16 v[62:65], v[150:153], v[166:169], v[62:65]
	v_mfma_f32_16x16x32_f16 v[58:61], v[158:161], v[166:169], v[58:61]
	v_mfma_f32_16x16x32_f16 v[46:49], v[150:153], v[174:177], v[46:49]
	v_mfma_f32_16x16x32_f16 v[42:45], v[158:161], v[174:177], v[42:45]
	v_mfma_f32_16x16x32_f16 v[30:33], v[150:153], v[182:185], v[30:33]
	v_mfma_f32_16x16x32_f16 v[26:29], v[158:161], v[182:185], v[26:29]
	v_mfma_f32_16x16x32_f16 v[14:17], v[150:153], v[190:193], v[14:17]
	v_mfma_f32_16x16x32_f16 v[10:13], v[158:161], v[190:193], v[10:13]
	s_barrier
; #define PG8_STAGE(bufoff, gbase, voff) do { _Pragma("unroll") for (int _i = 0; _i < 2; ++_i) \
;         __builtin_amdgcn_global_load_lds((const unsigned*)((const char*)(gbase) + (voff)[_i]), (LAS unsigned*)(lds + (bufoff) + ldsw + _i * 8192), 16, 0, 0); } while (0)
; #define PG8_LDA(dst, b, h) do { _Pragma("unroll") for (int m = 0; m < 4; ++m) _Pragma("unroll") for (int k = 0; k < 2; ++k) dst[m][k] = *(const LAS h16x8*)(lds + PG8_SA(b, h) + aoff + m * 2048 + k * 1024); } while (0)
; #define PG8_LDB(dst, b, h) do { _Pragma("unroll") for (int n = 0; n < 2; ++n) _Pragma("unroll") for (int k = 0; k < 2; ++k) dst[n][k] = *(const LAS h16x8*)(lds + PG8_SB(b, h) + boff + n * 2048 + k * 1024); } while (0)
; #define PG8_MMA(ai, bj, At, Bt_) do { __builtin_amdgcn_s_setprio(1); _Pragma("unroll") for (int m = 0; m < 4; ++m) _Pragma("unroll") for (int n = 0; n < 2; ++n) _Pragma("unroll") for (int k = 0; k < 2; ++k) \
;         acc[ai][bj][m][n] = __builtin_amdgcn_mfma_f32_16x16x32_f16(Bt_[n][k], At[m][k], acc[ai][bj][m][n], 0, 0, 0); __builtin_amdgcn_s_setprio(0); } while (0)
; #define PG8_WAIT_V(n) asm volatile("s_waitcnt vmcnt(" #n ")" ::: "memory")
; #define PG8_WAIT_L(n) asm volatile("s_waitcnt lgkmcnt(" #n ")" ::: "memory")
; #define PG8_BAR __builtin_amdgcn_s_barrier()
; #define PG8_SCHED __builtin_amdgcn_sched_barrier(0)
; template <class Epi, class AMap>
; __device__ __forceinline__ void gemm_phase(LAS unsigned char* lds, const AMap am, const int lda, const h16* Bt, const int ldb, const int M, const int N, const int K, const Epi& E) {
;     ...
;             PG8_BAR; PG8_WAIT_L(0); PG8_MMA(1, 0, At, B0); PG8_BAR; PG8_SCHED;
;             PG8_STAGE(PG8_SB(0, 1), b2 + hstepB, voffB);
;             PG8_WAIT_V(6); PG8_BAR; PG8_MMA(1, 1, At, B1); PG8_BAR;
;             PG8_LDB(B0, 1, 0); PG8_SCHED; PG8_LDA(At, 1, 0); PG8_STAGE(PG8_SA(0, 1), a2 + hstepA, voffA);
;             PG8_WAIT_L(8); PG8_BAR; PG8_WAIT_L(0); PG8_MMA(0, 0, At, B0); PG8_BAR; PG8_SCHED;
;             PG8_LDB(B1, 1, 1); PG8_STAGE(PG8_SB(1, 0), b3, voffB);
;             PG8_BAR; PG8_WAIT_L(0); PG8_MMA(0, 1, At, B1); PG8_BAR;
;             PG8_LDA(At, 1, 1); PG8_STAGE(PG8_SA(1, 0), a3, voffA);
;             PG8_BAR; PG8_WAIT_L(0); PG8_MMA(1, 0, At, B0); PG8_BAR; PG8_SCHED;
	s_add_u32 s78, s46, 0x80000
	s_addc_u32 s79, s47, 0
	s_add_i32 s60, s66, s64
	v_lshl_add_u64 v[140:141], s[78:79], 0, v[0:1]
	s_mov_b32 m0, s60
	s_nop 0
	global_load_lds_dwordx4 v[140:141], off
	v_lshl_add_u64 v[140:141], s[78:79], 0, v[134:135]
	s_add_i32 m0, s60, 0x2000
	s_nop 0
	global_load_lds_dwordx4 v[140:141], off
	s_waitcnt vmcnt(6)
	s_barrier
	v_mfma_f32_16x16x32_f16 v[54:57], v[194:197], v[162:165], v[54:57]
	v_mfma_f32_16x16x32_f16 v[50:53], v[202:205], v[162:165], v[50:53]
	v_mfma_f32_16x16x32_f16 v[38:41], v[194:197], v[170:173], v[38:41]
	v_mfma_f32_16x16x32_f16 v[34:37], v[202:205], v[170:173], v[34:37]
	v_mfma_f32_16x16x32_f16 v[22:25], v[194:197], v[178:181], v[22:25]
	v_mfma_f32_16x16x32_f16 v[18:21], v[202:205], v[178:181], v[18:21]
	v_mfma_f32_16x16x32_f16 v[6:9], v[194:197], v[186:189], v[6:9]
	v_mfma_f32_16x16x32_f16 v[2:5], v[202:205], v[186:189], v[2:5]
	v_mfma_f32_16x16x32_f16 v[54:57], v[198:201], v[166:169], v[54:57]
	v_mfma_f32_16x16x32_f16 v[50:53], v[220:223], v[166:169], v[50:53]
	v_mfma_f32_16x16x32_f16 v[38:41], v[198:201], v[174:177], v[38:41]
	v_mfma_f32_16x16x32_f16 v[34:37], v[220:223], v[174:177], v[34:37]
	v_mfma_f32_16x16x32_f16 v[22:25], v[198:201], v[182:185], v[22:25]
	v_mfma_f32_16x16x32_f16 v[18:21], v[220:223], v[182:185], v[18:21]
	v_mfma_f32_16x16x32_f16 v[6:9], v[198:201], v[190:193], v[6:9]
	v_mfma_f32_16x16x32_f16 v[2:5], v[220:223], v[190:193], v[2:5]
	s_add_i32 s60, 0, 0x18000
	v_add_u32_e32 v158, s60, v147
	s_barrier
	ds_read_b128 v[140:143], v158
	ds_read_b128 v[150:153], v158 offset:1024
	ds_read_b128 v[154:157], v158 offset:2048
	ds_read_b128 v[158:161], v158 offset:3072
	s_add_u32 s48, s48, 0x80000
	s_addc_u32 s49, s49, 0
	s_mov_b32 m0, s72
	v_lshl_add_u64 v[194:195], s[48:49], 0, v[130:131]
	ds_read_b128 v[162:165], v149 offset:32768
	ds_read_b128 v[166:169], v149 offset:33792
	ds_read_b128 v[170:173], v149 offset:34816
	ds_read_b128 v[174:177], v149 offset:35840
	ds_read_b128 v[178:181], v149 offset:36864
	ds_read_b128 v[182:185], v149 offset:37888
	ds_read_b128 v[186:189], v149 offset:38912
	ds_read_b128 v[190:193], v149 offset:39936
	global_load_lds_dwordx4 v[194:195], off
	v_lshl_add_u64 v[194:195], s[48:49], 0, v[132:133]
	s_mov_b32 m0, s73
	s_nop 0
	global_load_lds_dwordx4 v[194:195], off
	s_waitcnt lgkmcnt(8)
	s_barrier
	s_waitcnt lgkmcnt(0)
	s_waitcnt lgkmcnt(0)
	v_mfma_f32_16x16x32_f16 v[126:129], v[140:143], v[162:165], v[126:129]
	v_mfma_f32_16x16x32_f16 v[122:125], v[154:157], v[162:165], v[122:125]
	v_mfma_f32_16x16x32_f16 v[110:113], v[140:143], v[170:173], v[110:113]
	v_mfma_f32_16x16x32_f16 v[106:109], v[154:157], v[170:173], v[106:109]
	v_mfma_f32_16x16x32_f16 v[94:97], v[140:143], v[178:181], v[94:97]
	v_mfma_f32_16x16x32_f16 v[90:93], v[154:157], v[178:181], v[90:93]
	v_mfma_f32_16x16x32_f16 v[78:81], v[140:143], v[186:189], v[78:81]
	v_mfma_f32_16x16x32_f16 v[74:77], v[154:157], v[186:189], v[74:77]
	v_mfma_f32_16x16x32_f16 v[126:129], v[150:153], v[166:169], v[126:129]
	v_mfma_f32_16x16x32_f16 v[122:125], v[158:161], v[166:169], v[122:125]
	v_mfma_f32_16x16x32_f16 v[110:113], v[150:153], v[174:177], v[110:113]
	v_mfma_f32_16x16x32_f16 v[106:109], v[158:161], v[174:177], v[106:109]
	v_mfma_f32_16x16x32_f16 v[94:97], v[150:153], v[182:185], v[94:97]
	v_mfma_f32_16x16x32_f16 v[90:93], v[158:161], v[182:185], v[90:93]
	v_mfma_f32_16x16x32_f16 v[78:81], v[150:153], v[190:193], v[78:81]
	v_mfma_f32_16x16x32_f16 v[74:77], v[158:161], v[190:193], v[74:77]
	s_barrier
	s_add_i32 s48, 0, 0x1c000
	s_add_i32 s49, s60, s64
	v_add_u32_e32 v216, s48, v147
	v_lshl_add_u64 v[144:145], v[144:145], 0, s[92:93]
	s_mov_b32 m0, s49
	ds_read_b128 v[194:197], v216
	ds_read_b128 v[198:201], v216 offset:1024
	ds_read_b128 v[202:205], v216 offset:2048
	ds_read_b128 v[220:223], v216 offset:3072
	global_load_lds_dwordx4 v[144:145], off
	v_lshl_add_u64 v[144:145], v[206:207], 0, s[92:93]
	s_add_i32 m0, s49, 0x2000
	s_nop 0
	global_load_lds_dwordx4 v[144:145], off
	s_barrier
	s_waitcnt lgkmcnt(0)
	s_waitcnt lgkmcnt(0)
	v_mfma_f32_16x16x32_f16 v[118:121], v[194:197], v[162:165], v[118:121]
	v_mfma_f32_16x16x32_f16 v[114:117], v[202:205], v[162:165], v[114:117]
	v_mfma_f32_16x16x32_f16 v[102:105], v[194:197], v[170:173], v[102:105]
	v_mfma_f32_16x16x32_f16 v[98:101], v[202:205], v[170:173], v[98:101]
	v_mfma_f32_16x16x32_f16 v[86:89], v[194:197], v[178:181], v[86:89]
	v_mfma_f32_16x16x32_f16 v[82:85], v[202:205], v[178:181], v[82:85]
	v_mfma_f32_16x16x32_f16 v[70:73], v[194:197], v[186:189], v[70:73]
	v_mfma_f32_16x16x32_f16 v[66:69], v[202:205], v[186:189], v[66:69]
	v_mfma_f32_16x16x32_f16 v[118:121], v[198:201], v[166:169], v[118:121]
	v_mfma_f32_16x16x32_f16 v[114:117], v[220:223], v[166:169], v[114:117]
	v_mfma_f32_16x16x32_f16 v[102:105], v[198:201], v[174:177], v[102:105]
	v_mfma_f32_16x16x32_f16 v[98:101], v[220:223], v[174:177], v[98:101]
	v_mfma_f32_16x16x32_f16 v[86:89], v[198:201], v[182:185], v[86:89]
	v_mfma_f32_16x16x32_f16 v[82:85], v[220:223], v[182:185], v[82:85]
	v_mfma_f32_16x16x32_f16 v[70:73], v[198:201], v[190:193], v[70:73]
	v_mfma_f32_16x16x32_f16 v[66:69], v[220:223], v[190:193], v[66:69]
	s_mov_b32 m0, s74
	v_lshl_add_u64 v[144:145], v[212:213], 0, s[92:93]
	s_barrier
	ds_read_b128 v[162:165], v149 offset:49152
	ds_read_b128 v[166:169], v149 offset:50176
	ds_read_b128 v[170:173], v149 offset:51200
	ds_read_b128 v[174:177], v149 offset:52224
	ds_read_b128 v[178:181], v149 offset:53248
	ds_read_b128 v[182:185], v149 offset:54272
	ds_read_b128 v[186:189], v149 offset:55296
	ds_read_b128 v[190:193], v149 offset:56320
	global_load_lds_dwordx4 v[144:145], off
	v_lshl_add_u64 v[144:145], v[214:215], 0, s[92:93]
	s_mov_b32 m0, s75
	s_nop 0
	global_load_lds_dwordx4 v[144:145], off
	s_barrier
; #define PG8_STAGE(bufoff, gbase, voff) do { _Pragma("unroll") for (int _i = 0; _i < 2; ++_i) \
;         __builtin_amdgcn_global_load_lds((const unsigned*)((const char*)(gbase) + (voff)[_i]), (LAS unsigned*)(lds + (bufoff) + ldsw + _i * 8192), 16, 0, 0); } while (0)
; #define PG8_MMA(ai, bj, At, Bt_) do { __builtin_amdgcn_s_setprio(1); _Pragma("unroll") for (int m = 0; m < 4; ++m) _Pragma("unroll") for (int n = 0; n < 2; ++n) _Pragma("unroll") for (int k = 0; k < 2; ++k) \
;         acc[ai][bj][m][n] = __builtin_amdgcn_mfma_f32_16x16x32_f16(Bt_[n][k], At[m][k], acc[ai][bj][m][n], 0, 0, 0); __builtin_amdgcn_s_setprio(0); } while (0)
; #define PG8_WAIT_V(n) asm volatile("s_waitcnt vmcnt(" #n ")" ::: "memory")
; #define PG8_WAIT_L(n) asm volatile("s_waitcnt lgkmcnt(" #n ")" ::: "memory")
; #define PG8_BAR __builtin_amdgcn_s_barrier()
; #define PG8_SCHED __builtin_amdgcn_sched_barrier(0)
; template <class Epi, class AMap>
; __device__ __forceinline__ void gemm_phase(LAS unsigned char* lds, const AMap am, const int lda, const h16* Bt, const int ldb, const int M, const int N, const int K, const Epi& E) {
;     ...
;             PG8_BAR; PG8_WAIT_L(0); PG8_MMA(1, 0, At, B0); PG8_BAR; PG8_SCHED;
;             PG8_STAGE(PG8_SB(1, 1), b3 + hstepB, voffB);
;             PG8_WAIT_V(6); PG8_BAR; PG8_MMA(1, 1, At, B1); PG8_BAR;
;         }
;     __device__ __forceinline__ void operator()(const f32x4 (&acc)[2][2][4][2], const Unit& u, int wr, int wc, int fr, int fq) const {
;         EPI_ROWS_PERM
; #pragma unroll
;         for (int ai = 0; ai < 2; ++ai)
; #pragma unroll
;             for (int m = 0; m < 4; ++m) { const size_t off = (size_t)(row0 + ai * 128 + m * 16) * DM + colt;
; #pragma unroll
;                 for (int bj = 0; bj < 2; ++bj) {
;                     const h16x8 x = *(const h16x8*)(X + off + bj * 128);
;                     f32x4 o0, o1;
; #pragma unroll
;                     for (int e = 0; e < 4; ++e) { o0[e] = (float)x[e] * ALPHA + acc[ai][bj][m][0][e]; o1[e] = (float)x[4 + e] * ALPHA + acc[ai][bj][m][1][e]; }
;                     *(u32x4*)(PRE + off + bj * 128) = pack8(o0, o1); } }
	s_waitcnt lgkmcnt(0)
	s_waitcnt lgkmcnt(0)
	v_mfma_f32_16x16x32_f16 v[62:65], v[140:143], v[162:165], v[62:65]
	v_mfma_f32_16x16x32_f16 v[58:61], v[154:157], v[162:165], v[58:61]
	v_mfma_f32_16x16x32_f16 v[46:49], v[140:143], v[170:173], v[46:49]
	v_mfma_f32_16x16x32_f16 v[42:45], v[154:157], v[170:173], v[42:45]
	v_mfma_f32_16x16x32_f16 v[30:33], v[140:143], v[178:181], v[30:33]
	v_mfma_f32_16x16x32_f16 v[26:29], v[154:157], v[178:181], v[26:29]
	v_mfma_f32_16x16x32_f16 v[14:17], v[140:143], v[186:189], v[14:17]
	v_mfma_f32_16x16x32_f16 v[10:13], v[154:157], v[186:189], v[10:13]
	v_mfma_f32_16x16x32_f16 v[62:65], v[150:153], v[166:169], v[62:65]
	v_mfma_f32_16x16x32_f16 v[58:61], v[158:161], v[166:169], v[58:61]
	v_mfma_f32_16x16x32_f16 v[46:49], v[150:153], v[174:177], v[46:49]
	v_mfma_f32_16x16x32_f16 v[42:45], v[158:161], v[174:177], v[42:45]
	v_mfma_f32_16x16x32_f16 v[30:33], v[150:153], v[182:185], v[30:33]
	v_mfma_f32_16x16x32_f16 v[26:29], v[158:161], v[182:185], v[26:29]
	v_mfma_f32_16x16x32_f16 v[14:17], v[150:153], v[190:193], v[14:17]
	v_mfma_f32_16x16x32_f16 v[10:13], v[158:161], v[190:193], v[10:13]
	s_barrier
	s_add_u32 s46, s46, 0x80080
	s_addc_u32 s47, s47, 0
	s_add_i32 s48, s48, s64
	v_lshl_add_u64 v[140:141], s[46:47], 0, v[0:1]
	s_mov_b32 m0, s48
	s_nop 0
	global_load_lds_dwordx4 v[140:141], off
	v_lshl_add_u64 v[140:141], s[46:47], 0, v[134:135]
	s_add_i32 m0, s48, 0x2000
	s_nop 0
	global_load_lds_dwordx4 v[140:141], off
	s_waitcnt vmcnt(6)
	s_barrier
	v_mfma_f32_16x16x32_f16 v[54:57], v[194:197], v[162:165], v[54:57]
	v_mfma_f32_16x16x32_f16 v[50:53], v[202:205], v[162:165], v[50:53]
	v_mfma_f32_16x16x32_f16 v[38:41], v[194:197], v[170:173], v[38:41]
	v_mfma_f32_16x16x32_f16 v[34:37], v[202:205], v[170:173], v[34:37]
	v_mfma_f32_16x16x32_f16 v[22:25], v[194:197], v[178:181], v[22:25]
	v_mfma_f32_16x16x32_f16 v[18:21], v[202:205], v[178:181], v[18:21]
	v_mfma_f32_16x16x32_f16 v[6:9], v[194:197], v[186:189], v[6:9]
	v_mfma_f32_16x16x32_f16 v[2:5], v[202:205], v[186:189], v[2:5]
	v_mfma_f32_16x16x32_f16 v[54:57], v[198:201], v[166:169], v[54:57]
	v_mfma_f32_16x16x32_f16 v[50:53], v[220:223], v[166:169], v[50:53]
	v_mfma_f32_16x16x32_f16 v[38:41], v[198:201], v[174:177], v[38:41]
	v_mfma_f32_16x16x32_f16 v[34:37], v[220:223], v[174:177], v[34:37]
	v_mfma_f32_16x16x32_f16 v[22:25], v[198:201], v[182:185], v[22:25]
	v_mfma_f32_16x16x32_f16 v[18:21], v[220:223], v[182:185], v[18:21]
	v_mfma_f32_16x16x32_f16 v[6:9], v[198:201], v[190:193], v[6:9]
	v_mfma_f32_16x16x32_f16 v[2:5], v[220:223], v[190:193], v[2:5]
	s_add_i32 s51, s51, 2
	s_add_u32 s26, s26, 0x100
	s_addc_u32 s27, s27, 0
	s_add_u32 s21, s21, 0x100
	s_addc_u32 s50, s50, 0
	s_cmp_gt_u32 s51, 29
	s_barrier
	s_cbranch_scc0 .LBB0_147
	v_lshl_add_u32 v144, s22, 8, v146
	v_lshl_or_b32 v142, s35, 8, v148
	v_ashrrev_i32_e32 v145, 31, v144
	v_ashrrev_i32_e32 v143, 31, v142
	v_lshlrev_b64 v[140:141], 11, v[144:145]
	v_lshl_add_u64 v[140:141], v[140:141], 0, v[142:143]
	v_lshlrev_b64 v[140:141], 1, v[140:141]
	v_lshl_add_u64 v[154:155], s[94:95], 0, v[140:141]
	s_mov_b32 s101, 0
	global_load_dwordx4 v[158:161], v[154:155], off
	global_load_dwordx4 v[162:165], v[154:155], off offset:256
	s_mov_b32 s100, 0x10000
	v_lshl_add_u64 v[232:233], v[154:155], 0, s[100:101]
	global_load_dwordx4 v[166:169], v[232:233], off
	global_load_dwordx4 v[170:173], v[232:233], off offset:256
	s_mov_b32 s100, 0x20000
	v_lshl_add_u64 v[232:233], v[154:155], 0, s[100:101]
	global_load_dwordx4 v[174:177], v[232:233], off
	global_load_dwordx4 v[178:181], v[232:233], off offset:256
	s_mov_b32 s100, 0x30000
	v_lshl_add_u64 v[232:233], v[154:155], 0, s[100:101]
	global_load_dwordx4 v[182:185], v[232:233], off
	global_load_dwordx4 v[186:189], v[232:233], off offset:256
	s_mov_b32 s100, 0x80000
	v_lshl_add_u64 v[232:233], v[154:155], 0, s[100:101]
	global_load_dwordx4 v[190:193], v[232:233], off
	global_load_dwordx4 v[194:197], v[232:233], off offset:256
	s_mov_b32 s100, 0x90000
	v_lshl_add_u64 v[232:233], v[154:155], 0, s[100:101]
	global_load_dwordx4 v[198:201], v[232:233], off
	global_load_dwordx4 v[202:205], v[232:233], off offset:256
	s_mov_b32 s100, 0xa0000
	v_lshl_add_u64 v[232:233], v[154:155], 0, s[100:101]
	global_load_dwordx4 v[212:215], v[232:233], off
	global_load_dwordx4 v[220:223], v[232:233], off offset:256
	s_mov_b32 s100, 0xb0000
	v_lshl_add_u64 v[232:233], v[154:155], 0, s[100:101]
	global_load_dwordx4 v[224:227], v[232:233], off
	global_load_dwordx4 v[228:231], v[232:233], off offset:256
	s_mov_b64 s[2:3], 0xb0000
	s_and_b64 vcc, exec, s[38:39]
	s_mov_b32 s22, s40
	s_mov_b64 s[46:47], s[44:45]
	s_mov_b64 s[26:27], s[42:43]
	s_movk_i32 s66, 0x80
	s_waitcnt vmcnt(15)
	v_mov_b64_e32 v[150:151], v[158:159]
	v_mov_b64_e32 v[152:153], v[160:161]
	v_cvt_f32_f16_e32 v156, v150
	v_cvt_f32_f16_sdwa v157, v150 dst_sel:DWORD dst_unused:UNUSED_PAD src0_sel:WORD_1
	v_cvt_f32_f16_e32 v150, v151
	v_cvt_f32_f16_sdwa v151, v151 dst_sel:DWORD dst_unused:UNUSED_PAD src0_sel:WORD_1
	v_pk_fma_f32 v[126:127], v[156:157], s[34:35], v[126:127] op_sel_hi:[1,0,1]
	s_nop 0
	v_cvt_pk_f16_f32 v126, v126, v127
	v_pk_fma_f32 v[128:129], v[150:151], s[34:35], v[128:129] op_sel_hi:[1,0,1]
	v_lshl_add_u64 v[150:151], s[4:5], 0, v[140:141]
	v_cvt_pk_f16_f32 v127, v128, v129
	v_cvt_f32_f16_e32 v128, v152
	v_cvt_f32_f16_sdwa v129, v152 dst_sel:DWORD dst_unused:UNUSED_PAD src0_sel:WORD_1
	v_pk_fma_f32 v[122:123], v[128:129], s[34:35], v[122:123] op_sel_hi:[1,0,1]
	s_nop 0
	v_cvt_pk_f16_f32 v128, v122, v123
	v_cvt_f32_f16_e32 v122, v153
	v_cvt_f32_f16_sdwa v123, v153 dst_sel:DWORD dst_unused:UNUSED_PAD src0_sel:WORD_1
	v_pk_fma_f32 v[122:123], v[122:123], s[34:35], v[124:125] op_sel_hi:[1,0,1]
	s_nop 0
	v_cvt_pk_f16_f32 v129, v122, v123
	s_nop 0
	global_store_dwordx4 v[150:151], v[126:129], off
	s_waitcnt vmcnt(15)
;     __device__ __forceinline__ void operator()(const f32x4 (&acc)[2][2][4][2], const Unit& u, int wr, int wc, int fr, int fq) const {
;     ...
;             for (int m = 0; m < 4; ++m) { const size_t off = (size_t)(row0 + ai * 128 + m * 16) * DM + colt;
; #pragma unroll
;                 for (int bj = 0; bj < 2; ++bj) {
;                     const h16x8 x = *(const h16x8*)(X + off + bj * 128);
;                     f32x4 o0, o1;
; #pragma unroll
;                     for (int e = 0; e < 4; ++e) { o0[e] = (float)x[e] * ALPHA + acc[ai][bj][m][0][e]; o1[e] = (float)x[4 + e] * ALPHA + acc[ai][bj][m][1][e]; }
;                     *(u32x4*)(PRE + off + bj * 128) = pack8(o0, o1); } }
	v_mov_b64_e32 v[122:123], v[162:163]
	v_mov_b64_e32 v[124:125], v[164:165]
	s_nop 0
	v_cvt_f32_f16_e32 v126, v122
	v_cvt_f32_f16_sdwa v127, v122 dst_sel:DWORD dst_unused:UNUSED_PAD src0_sel:WORD_1
	v_cvt_f32_f16_e32 v122, v123
	v_cvt_f32_f16_sdwa v123, v123 dst_sel:DWORD dst_unused:UNUSED_PAD src0_sel:WORD_1
	v_pk_fma_f32 v[118:119], v[126:127], s[34:35], v[118:119] op_sel_hi:[1,0,1]
	s_nop 0
	v_cvt_pk_f16_f32 v118, v118, v119
	v_pk_fma_f32 v[120:121], v[122:123], s[34:35], v[120:121] op_sel_hi:[1,0,1]
	s_nop 0
	v_cvt_pk_f16_f32 v119, v120, v121
	v_cvt_f32_f16_e32 v120, v124
	v_cvt_f32_f16_sdwa v121, v124 dst_sel:DWORD dst_unused:UNUSED_PAD src0_sel:WORD_1
	v_pk_fma_f32 v[114:115], v[120:121], s[34:35], v[114:115] op_sel_hi:[1,0,1]
	s_nop 0
	v_cvt_pk_f16_f32 v120, v114, v115
	v_cvt_f32_f16_e32 v114, v125
	v_cvt_f32_f16_sdwa v115, v125 dst_sel:DWORD dst_unused:UNUSED_PAD src0_sel:WORD_1
	v_pk_fma_f32 v[114:115], v[114:115], s[34:35], v[116:117] op_sel_hi:[1,0,1]
	s_nop 0
	v_cvt_pk_f16_f32 v121, v114, v115
	v_or_b32_e32 v114, 16, v144
	v_ashrrev_i32_e32 v115, 31, v114
	v_lshlrev_b64 v[114:115], 11, v[114:115]
	v_lshl_add_u64 v[114:115], v[114:115], 0, v[142:143]
	global_store_dwordx4 v[150:151], v[118:121], off offset:256
	s_nop 1
	v_lshlrev_b64 v[118:119], 1, v[114:115]
	v_lshl_add_u64 v[120:121], s[94:95], 0, v[118:119]
	s_waitcnt vmcnt(15)
	v_mov_b64_e32 v[114:115], v[166:167]
	v_mov_b64_e32 v[116:117], v[168:169]
	v_cvt_f32_f16_e32 v122, v114
	v_cvt_f32_f16_sdwa v123, v114 dst_sel:DWORD dst_unused:UNUSED_PAD src0_sel:WORD_1
	v_cvt_f32_f16_e32 v114, v115
	v_cvt_f32_f16_sdwa v115, v115 dst_sel:DWORD dst_unused:UNUSED_PAD src0_sel:WORD_1
	v_pk_fma_f32 v[110:111], v[122:123], s[34:35], v[110:111] op_sel_hi:[1,0,1]
	s_nop 0
	v_cvt_pk_f16_f32 v110, v110, v111
	v_pk_fma_f32 v[112:113], v[114:115], s[34:35], v[112:113] op_sel_hi:[1,0,1]
	v_lshl_add_u64 v[114:115], s[4:5], 0, v[118:119]
	v_cvt_pk_f16_f32 v111, v112, v113
	v_cvt_f32_f16_e32 v112, v116
	v_cvt_f32_f16_sdwa v113, v116 dst_sel:DWORD dst_unused:UNUSED_PAD src0_sel:WORD_1
	v_pk_fma_f32 v[106:107], v[112:113], s[34:35], v[106:107] op_sel_hi:[1,0,1]
	s_nop 0
	v_cvt_pk_f16_f32 v112, v106, v107
	v_cvt_f32_f16_e32 v106, v117
	v_cvt_f32_f16_sdwa v107, v117 dst_sel:DWORD dst_unused:UNUSED_PAD src0_sel:WORD_1
	v_pk_fma_f32 v[106:107], v[106:107], s[34:35], v[108:109] op_sel_hi:[1,0,1]
	s_nop 0
	v_cvt_pk_f16_f32 v113, v106, v107
	s_nop 0
	global_store_dwordx4 v[114:115], v[110:113], off
	s_waitcnt vmcnt(15)
	v_mov_b64_e32 v[106:107], v[170:171]
	v_mov_b64_e32 v[108:109], v[172:173]
	s_nop 0
	v_cvt_f32_f16_e32 v110, v106
	v_cvt_f32_f16_sdwa v111, v106 dst_sel:DWORD dst_unused:UNUSED_PAD src0_sel:WORD_1
	v_cvt_f32_f16_e32 v106, v107
	v_cvt_f32_f16_sdwa v107, v107 dst_sel:DWORD dst_unused:UNUSED_PAD src0_sel:WORD_1
	v_pk_fma_f32 v[102:103], v[110:111], s[34:35], v[102:103] op_sel_hi:[1,0,1]
	s_nop 0
	v_cvt_pk_f16_f32 v102, v102, v103
	v_pk_fma_f32 v[104:105], v[106:107], s[34:35], v[104:105] op_sel_hi:[1,0,1]
	s_nop 0
	v_cvt_pk_f16_f32 v103, v104, v105
	v_cvt_f32_f16_e32 v104, v108
	v_cvt_f32_f16_sdwa v105, v108 dst_sel:DWORD dst_unused:UNUSED_PAD src0_sel:WORD_1
	v_pk_fma_f32 v[98:99], v[104:105], s[34:35], v[98:99] op_sel_hi:[1,0,1]
	s_nop 0
	v_cvt_pk_f16_f32 v104, v98, v99
	v_cvt_f32_f16_e32 v98, v109
	v_cvt_f32_f16_sdwa v99, v109 dst_sel:DWORD dst_unused:UNUSED_PAD src0_sel:WORD_1
	v_pk_fma_f32 v[98:99], v[98:99], s[34:35], v[100:101] op_sel_hi:[1,0,1]
	s_nop 0
	v_cvt_pk_f16_f32 v105, v98, v99
	v_or_b32_e32 v98, 32, v144
	v_ashrrev_i32_e32 v99, 31, v98
	v_lshlrev_b64 v[98:99], 11, v[98:99]
	v_lshl_add_u64 v[98:99], v[98:99], 0, v[142:143]
	global_store_dwordx4 v[114:115], v[102:105], off offset:256
	s_nop 1
	v_lshlrev_b64 v[102:103], 1, v[98:99]
	v_lshl_add_u64 v[104:105], s[94:95], 0, v[102:103]
	s_waitcnt vmcnt(15)
	v_mov_b64_e32 v[98:99], v[174:175]
	v_mov_b64_e32 v[100:101], v[176:177]
	v_cvt_f32_f16_e32 v106, v98
	v_cvt_f32_f16_sdwa v107, v98 dst_sel:DWORD dst_unused:UNUSED_PAD src0_sel:WORD_1
	v_cvt_f32_f16_e32 v98, v99
	v_cvt_f32_f16_sdwa v99, v99 dst_sel:DWORD dst_unused:UNUSED_PAD src0_sel:WORD_1
	v_pk_fma_f32 v[94:95], v[106:107], s[34:35], v[94:95] op_sel_hi:[1,0,1]
	s_nop 0
	v_cvt_pk_f16_f32 v94, v94, v95
	v_pk_fma_f32 v[96:97], v[98:99], s[34:35], v[96:97] op_sel_hi:[1,0,1]
	v_lshl_add_u64 v[98:99], s[4:5], 0, v[102:103]
	v_cvt_pk_f16_f32 v95, v96, v97
	v_cvt_f32_f16_e32 v96, v100
	v_cvt_f32_f16_sdwa v97, v100 dst_sel:DWORD dst_unused:UNUSED_PAD src0_sel:WORD_1
	v_pk_fma_f32 v[90:91], v[96:97], s[34:35], v[90:91] op_sel_hi:[1,0,1]
	s_nop 0
	v_cvt_pk_f16_f32 v96, v90, v91
	v_cvt_f32_f16_e32 v90, v101
	v_cvt_f32_f16_sdwa v91, v101 dst_sel:DWORD dst_unused:UNUSED_PAD src0_sel:WORD_1
	v_pk_fma_f32 v[90:91], v[90:91], s[34:35], v[92:93] op_sel_hi:[1,0,1]
	s_nop 0
	v_cvt_pk_f16_f32 v97, v90, v91
	s_nop 0
	global_store_dwordx4 v[98:99], v[94:97], off
	s_waitcnt vmcnt(15)
	v_mov_b64_e32 v[90:91], v[178:179]
	v_mov_b64_e32 v[92:93], v[180:181]
	s_nop 0
	v_cvt_f32_f16_e32 v94, v90
	v_cvt_f32_f16_sdwa v95, v90 dst_sel:DWORD dst_unused:UNUSED_PAD src0_sel:WORD_1
	v_cvt_f32_f16_e32 v90, v91
	v_cvt_f32_f16_sdwa v91, v91 dst_sel:DWORD dst_unused:UNUSED_PAD src0_sel:WORD_1
	v_pk_fma_f32 v[86:87], v[94:95], s[34:35], v[86:87] op_sel_hi:[1,0,1]
	s_nop 0
	v_cvt_pk_f16_f32 v86, v86, v87
	v_pk_fma_f32 v[88:89], v[90:91], s[34:35], v[88:89] op_sel_hi:[1,0,1]
	s_nop 0
	v_cvt_pk_f16_f32 v87, v88, v89
	v_cvt_f32_f16_e32 v88, v92
	v_cvt_f32_f16_sdwa v89, v92 dst_sel:DWORD dst_unused:UNUSED_PAD src0_sel:WORD_1
	v_pk_fma_f32 v[82:83], v[88:89], s[34:35], v[82:83] op_sel_hi:[1,0,1]
	s_nop 0
	v_cvt_pk_f16_f32 v88, v82, v83
	v_cvt_f32_f16_e32 v82, v93
	v_cvt_f32_f16_sdwa v83, v93 dst_sel:DWORD dst_unused:UNUSED_PAD src0_sel:WORD_1
	v_pk_fma_f32 v[82:83], v[82:83], s[34:35], v[84:85] op_sel_hi:[1,0,1]
	s_nop 0
	v_cvt_pk_f16_f32 v89, v82, v83
	v_or_b32_e32 v82, 48, v144
	v_ashrrev_i32_e32 v83, 31, v82
	v_lshlrev_b64 v[82:83], 11, v[82:83]
	v_lshl_add_u64 v[82:83], v[82:83], 0, v[142:143]
	global_store_dwordx4 v[98:99], v[86:89], off offset:256
	s_nop 1
	v_lshlrev_b64 v[86:87], 1, v[82:83]
	v_lshl_add_u64 v[88:89], s[94:95], 0, v[86:87]
	s_waitcnt vmcnt(15)
;     __device__ __forceinline__ void operator()(const f32x4 (&acc)[2][2][4][2], const Unit& u, int wr, int wc, int fr, int fq) const {
;     ...
;             for (int m = 0; m < 4; ++m) { const size_t off = (size_t)(row0 + ai * 128 + m * 16) * DM + colt;
; #pragma unroll
;                 for (int bj = 0; bj < 2; ++bj) {
;                     const h16x8 x = *(const h16x8*)(X + off + bj * 128);
;                     f32x4 o0, o1;
; #pragma unroll
;                     for (int e = 0; e < 4; ++e) { o0[e] = (float)x[e] * ALPHA + acc[ai][bj][m][0][e]; o1[e] = (float)x[4 + e] * ALPHA + acc[ai][bj][m][1][e]; }
;                     *(u32x4*)(PRE + off + bj * 128) = pack8(o0, o1); } }
	v_mov_b64_e32 v[82:83], v[182:183]
	v_mov_b64_e32 v[84:85], v[184:185]
	v_cvt_f32_f16_e32 v90, v82
	v_cvt_f32_f16_sdwa v91, v82 dst_sel:DWORD dst_unused:UNUSED_PAD src0_sel:WORD_1
	v_cvt_f32_f16_e32 v82, v83
	v_cvt_f32_f16_sdwa v83, v83 dst_sel:DWORD dst_unused:UNUSED_PAD src0_sel:WORD_1
	v_pk_fma_f32 v[78:79], v[90:91], s[34:35], v[78:79] op_sel_hi:[1,0,1]
	s_nop 0
	v_cvt_pk_f16_f32 v78, v78, v79
	v_pk_fma_f32 v[80:81], v[82:83], s[34:35], v[80:81] op_sel_hi:[1,0,1]
	v_lshl_add_u64 v[82:83], s[4:5], 0, v[86:87]
	v_cvt_pk_f16_f32 v79, v80, v81
	v_cvt_f32_f16_e32 v80, v84
	v_cvt_f32_f16_sdwa v81, v84 dst_sel:DWORD dst_unused:UNUSED_PAD src0_sel:WORD_1
	v_pk_fma_f32 v[74:75], v[80:81], s[34:35], v[74:75] op_sel_hi:[1,0,1]
	s_nop 0
	v_cvt_pk_f16_f32 v80, v74, v75
	v_cvt_f32_f16_e32 v74, v85
	v_cvt_f32_f16_sdwa v75, v85 dst_sel:DWORD dst_unused:UNUSED_PAD src0_sel:WORD_1
	v_pk_fma_f32 v[74:75], v[74:75], s[34:35], v[76:77] op_sel_hi:[1,0,1]
	s_nop 0
	v_cvt_pk_f16_f32 v81, v74, v75
	s_nop 0
	global_store_dwordx4 v[82:83], v[78:81], off
	s_waitcnt vmcnt(15)
	v_mov_b64_e32 v[74:75], v[186:187]
	v_mov_b64_e32 v[76:77], v[188:189]
	s_nop 0
	v_cvt_f32_f16_e32 v78, v74
	v_cvt_f32_f16_sdwa v79, v74 dst_sel:DWORD dst_unused:UNUSED_PAD src0_sel:WORD_1
	v_cvt_f32_f16_e32 v74, v75
	v_cvt_f32_f16_sdwa v75, v75 dst_sel:DWORD dst_unused:UNUSED_PAD src0_sel:WORD_1
	v_pk_fma_f32 v[70:71], v[78:79], s[34:35], v[70:71] op_sel_hi:[1,0,1]
	s_nop 0
	v_cvt_pk_f16_f32 v70, v70, v71
	v_pk_fma_f32 v[72:73], v[74:75], s[34:35], v[72:73] op_sel_hi:[1,0,1]
	s_nop 0
	v_cvt_pk_f16_f32 v71, v72, v73
	v_cvt_f32_f16_e32 v72, v76
	v_cvt_f32_f16_sdwa v73, v76 dst_sel:DWORD dst_unused:UNUSED_PAD src0_sel:WORD_1
	v_pk_fma_f32 v[66:67], v[72:73], s[34:35], v[66:67] op_sel_hi:[1,0,1]
	s_nop 0
	v_cvt_pk_f16_f32 v72, v66, v67
	v_cvt_f32_f16_e32 v66, v77
	v_cvt_f32_f16_sdwa v67, v77 dst_sel:DWORD dst_unused:UNUSED_PAD src0_sel:WORD_1
	v_pk_fma_f32 v[66:67], v[66:67], s[34:35], v[68:69] op_sel_hi:[1,0,1]
	s_nop 0
	v_cvt_pk_f16_f32 v73, v66, v67
	global_store_dwordx4 v[82:83], v[70:73], off offset:256
	s_nop 1
	v_lshl_add_u64 v[70:71], v[140:141], 0, s[16:17]
	v_lshl_add_u64 v[72:73], s[94:95], 0, v[70:71]
	s_waitcnt vmcnt(15)
	v_mov_b64_e32 v[66:67], v[190:191]
	v_mov_b64_e32 v[68:69], v[192:193]
	v_cvt_f32_f16_e32 v74, v66
	v_cvt_f32_f16_sdwa v75, v66 dst_sel:DWORD dst_unused:UNUSED_PAD src0_sel:WORD_1
	v_cvt_f32_f16_e32 v66, v67
	v_cvt_f32_f16_sdwa v67, v67 dst_sel:DWORD dst_unused:UNUSED_PAD src0_sel:WORD_1
	v_pk_fma_f32 v[62:63], v[74:75], s[34:35], v[62:63] op_sel_hi:[1,0,1]
	s_nop 0
	v_cvt_pk_f16_f32 v62, v62, v63
	v_pk_fma_f32 v[64:65], v[66:67], s[34:35], v[64:65] op_sel_hi:[1,0,1]
	v_lshl_add_u64 v[66:67], s[4:5], 0, v[70:71]
	v_cvt_pk_f16_f32 v63, v64, v65
	v_cvt_f32_f16_e32 v64, v68
	v_cvt_f32_f16_sdwa v65, v68 dst_sel:DWORD dst_unused:UNUSED_PAD src0_sel:WORD_1
	v_pk_fma_f32 v[58:59], v[64:65], s[34:35], v[58:59] op_sel_hi:[1,0,1]
	s_nop 0
	v_cvt_pk_f16_f32 v64, v58, v59
	v_cvt_f32_f16_e32 v58, v69
	v_cvt_f32_f16_sdwa v59, v69 dst_sel:DWORD dst_unused:UNUSED_PAD src0_sel:WORD_1
	v_pk_fma_f32 v[58:59], v[58:59], s[34:35], v[60:61] op_sel_hi:[1,0,1]
	s_nop 0
	v_cvt_pk_f16_f32 v65, v58, v59
	s_nop 0
	global_store_dwordx4 v[66:67], v[62:65], off
	s_waitcnt vmcnt(15)
	v_mov_b64_e32 v[58:59], v[194:195]
	v_mov_b64_e32 v[60:61], v[196:197]
	s_nop 0
	v_cvt_f32_f16_e32 v62, v58
	v_cvt_f32_f16_sdwa v63, v58 dst_sel:DWORD dst_unused:UNUSED_PAD src0_sel:WORD_1
	v_cvt_f32_f16_e32 v58, v59
	v_cvt_f32_f16_sdwa v59, v59 dst_sel:DWORD dst_unused:UNUSED_PAD src0_sel:WORD_1
	v_pk_fma_f32 v[54:55], v[62:63], s[34:35], v[54:55] op_sel_hi:[1,0,1]
	s_nop 0
	v_cvt_pk_f16_f32 v54, v54, v55
	v_pk_fma_f32 v[56:57], v[58:59], s[34:35], v[56:57] op_sel_hi:[1,0,1]
	s_nop 0
	v_cvt_pk_f16_f32 v55, v56, v57
	v_cvt_f32_f16_e32 v56, v60
	v_cvt_f32_f16_sdwa v57, v60 dst_sel:DWORD dst_unused:UNUSED_PAD src0_sel:WORD_1
	v_pk_fma_f32 v[50:51], v[56:57], s[34:35], v[50:51] op_sel_hi:[1,0,1]
	s_nop 0
	v_cvt_pk_f16_f32 v56, v50, v51
	v_cvt_f32_f16_e32 v50, v61
	v_cvt_f32_f16_sdwa v51, v61 dst_sel:DWORD dst_unused:UNUSED_PAD src0_sel:WORD_1
	v_pk_fma_f32 v[50:51], v[50:51], s[34:35], v[52:53] op_sel_hi:[1,0,1]
	s_nop 0
	v_cvt_pk_f16_f32 v57, v50, v51
	global_store_dwordx4 v[66:67], v[54:57], off offset:256
	s_nop 1
	v_lshl_add_u64 v[54:55], v[140:141], 0, s[18:19]
	v_lshl_add_u64 v[56:57], s[94:95], 0, v[54:55]
	s_waitcnt vmcnt(15)
	v_mov_b64_e32 v[50:51], v[198:199]
	v_mov_b64_e32 v[52:53], v[200:201]
	v_cvt_f32_f16_e32 v58, v50
	v_cvt_f32_f16_sdwa v59, v50 dst_sel:DWORD dst_unused:UNUSED_PAD src0_sel:WORD_1
	v_cvt_f32_f16_e32 v50, v51
	v_cvt_f32_f16_sdwa v51, v51 dst_sel:DWORD dst_unused:UNUSED_PAD src0_sel:WORD_1
	v_pk_fma_f32 v[46:47], v[58:59], s[34:35], v[46:47] op_sel_hi:[1,0,1]
	s_nop 0
	v_cvt_pk_f16_f32 v46, v46, v47
	v_pk_fma_f32 v[48:49], v[50:51], s[34:35], v[48:49] op_sel_hi:[1,0,1]
	v_lshl_add_u64 v[50:51], s[4:5], 0, v[54:55]
	v_cvt_pk_f16_f32 v47, v48, v49
	v_cvt_f32_f16_e32 v48, v52
	v_cvt_f32_f16_sdwa v49, v52 dst_sel:DWORD dst_unused:UNUSED_PAD src0_sel:WORD_1
	v_pk_fma_f32 v[42:43], v[48:49], s[34:35], v[42:43] op_sel_hi:[1,0,1]
	s_nop 0
	v_cvt_pk_f16_f32 v48, v42, v43
	v_cvt_f32_f16_e32 v42, v53
	v_cvt_f32_f16_sdwa v43, v53 dst_sel:DWORD dst_unused:UNUSED_PAD src0_sel:WORD_1
	v_pk_fma_f32 v[42:43], v[42:43], s[34:35], v[44:45] op_sel_hi:[1,0,1]
	s_nop 0
	v_cvt_pk_f16_f32 v49, v42, v43
	s_nop 0
	global_store_dwordx4 v[50:51], v[46:49], off
	s_waitcnt vmcnt(15)
; #define PG8_WAIT_V(n) asm volatile("s_waitcnt vmcnt(" #n ")" ::: "memory")
; #define PG8_BAR __builtin_amdgcn_s_barrier()
; template <class Epi, class AMap>
; __device__ __forceinline__ void gemm_phase(LAS unsigned char* lds, const AMap am, const int lda, const h16* Bt, const int ldb, const int M, const int N, const int K, const Epi& E) {
;     ...
;         if (!has_next) break;
; #pragma unroll
;         for (int a = 0; a < 2; ++a)
; #pragma unroll
;             for (int b = 0; b < 2; ++b)
; #pragma unroll
;                 for (int m = 0; m < 4; ++m)
; #pragma unroll
;                     for (int n = 0; n < 2; ++n) acc[a][b][m][n] = (f32x4){0.f, 0.f, 0.f, 0.f};
;         cur = nxt; cA = nA; cB = nB; ++ui;
;     }
;     PG8_WAIT_V(0);
;     if (wr == 0) PG8_BAR;
;     PG8_BAR;
;     __device__ __forceinline__ void operator()(const f32x4 (&acc)[2][2][4][2], const Unit& u, int wr, int wc, int fr, int fq) const {
;     ...
;             for (int m = 0; m < 4; ++m) { const size_t off = (size_t)(row0 + ai * 128 + m * 16) * DM + colt;
; #pragma unroll
;                 for (int bj = 0; bj < 2; ++bj) {
;                     const h16x8 x = *(const h16x8*)(X + off + bj * 128);
;                     f32x4 o0, o1;
; #pragma unroll
;                     for (int e = 0; e < 4; ++e) { o0[e] = (float)x[e] * ALPHA + acc[ai][bj][m][0][e]; o1[e] = (float)x[4 + e] * ALPHA + acc[ai][bj][m][1][e]; }
;                     *(u32x4*)(PRE + off + bj * 128) = pack8(o0, o1); } }
	v_mov_b64_e32 v[42:43], v[202:203]
	v_mov_b64_e32 v[44:45], v[204:205]
	s_nop 0
	v_cvt_f32_f16_e32 v46, v42
	v_cvt_f32_f16_sdwa v47, v42 dst_sel:DWORD dst_unused:UNUSED_PAD src0_sel:WORD_1
	v_cvt_f32_f16_e32 v42, v43
	v_cvt_f32_f16_sdwa v43, v43 dst_sel:DWORD dst_unused:UNUSED_PAD src0_sel:WORD_1
	v_pk_fma_f32 v[38:39], v[46:47], s[34:35], v[38:39] op_sel_hi:[1,0,1]
	s_nop 0
	v_cvt_pk_f16_f32 v38, v38, v39
	v_pk_fma_f32 v[40:41], v[42:43], s[34:35], v[40:41] op_sel_hi:[1,0,1]
	s_nop 0
	v_cvt_pk_f16_f32 v39, v40, v41
	v_cvt_f32_f16_e32 v40, v44
	v_cvt_f32_f16_sdwa v41, v44 dst_sel:DWORD dst_unused:UNUSED_PAD src0_sel:WORD_1
	v_pk_fma_f32 v[34:35], v[40:41], s[34:35], v[34:35] op_sel_hi:[1,0,1]
	s_nop 0
	v_cvt_pk_f16_f32 v40, v34, v35
	v_cvt_f32_f16_e32 v34, v45
	v_cvt_f32_f16_sdwa v35, v45 dst_sel:DWORD dst_unused:UNUSED_PAD src0_sel:WORD_1
	v_pk_fma_f32 v[34:35], v[34:35], s[34:35], v[36:37] op_sel_hi:[1,0,1]
	s_nop 0
	v_cvt_pk_f16_f32 v41, v34, v35
	global_store_dwordx4 v[50:51], v[38:41], off offset:256
	s_nop 1
	v_lshl_add_u64 v[38:39], v[140:141], 0, s[8:9]
	v_lshl_add_u64 v[40:41], s[94:95], 0, v[38:39]
	s_waitcnt vmcnt(15)
	v_mov_b64_e32 v[34:35], v[212:213]
	v_mov_b64_e32 v[36:37], v[214:215]
	v_cvt_f32_f16_e32 v42, v34
	v_cvt_f32_f16_sdwa v43, v34 dst_sel:DWORD dst_unused:UNUSED_PAD src0_sel:WORD_1
	v_cvt_f32_f16_e32 v34, v35
	v_cvt_f32_f16_sdwa v35, v35 dst_sel:DWORD dst_unused:UNUSED_PAD src0_sel:WORD_1
	v_pk_fma_f32 v[30:31], v[42:43], s[34:35], v[30:31] op_sel_hi:[1,0,1]
	s_nop 0
	v_cvt_pk_f16_f32 v30, v30, v31
	v_pk_fma_f32 v[32:33], v[34:35], s[34:35], v[32:33] op_sel_hi:[1,0,1]
	v_lshl_add_u64 v[34:35], s[4:5], 0, v[38:39]
	v_cvt_pk_f16_f32 v31, v32, v33
	v_cvt_f32_f16_e32 v32, v36
	v_cvt_f32_f16_sdwa v33, v36 dst_sel:DWORD dst_unused:UNUSED_PAD src0_sel:WORD_1
	v_pk_fma_f32 v[26:27], v[32:33], s[34:35], v[26:27] op_sel_hi:[1,0,1]
	s_nop 0
	v_cvt_pk_f16_f32 v32, v26, v27
	v_cvt_f32_f16_e32 v26, v37
	v_cvt_f32_f16_sdwa v27, v37 dst_sel:DWORD dst_unused:UNUSED_PAD src0_sel:WORD_1
	v_pk_fma_f32 v[26:27], v[26:27], s[34:35], v[28:29] op_sel_hi:[1,0,1]
	s_nop 0
	v_cvt_pk_f16_f32 v33, v26, v27
	s_nop 0
	global_store_dwordx4 v[34:35], v[30:33], off
	s_waitcnt vmcnt(15)
	v_mov_b64_e32 v[26:27], v[220:221]
	v_mov_b64_e32 v[28:29], v[222:223]
	s_nop 0
	v_cvt_f32_f16_e32 v30, v26
	v_cvt_f32_f16_sdwa v31, v26 dst_sel:DWORD dst_unused:UNUSED_PAD src0_sel:WORD_1
	v_cvt_f32_f16_e32 v26, v27
	v_cvt_f32_f16_sdwa v27, v27 dst_sel:DWORD dst_unused:UNUSED_PAD src0_sel:WORD_1
	v_pk_fma_f32 v[22:23], v[30:31], s[34:35], v[22:23] op_sel_hi:[1,0,1]
	s_nop 0
	v_cvt_pk_f16_f32 v22, v22, v23
	v_pk_fma_f32 v[24:25], v[26:27], s[34:35], v[24:25] op_sel_hi:[1,0,1]
	s_nop 0
	v_cvt_pk_f16_f32 v23, v24, v25
	v_cvt_f32_f16_e32 v24, v28
	v_cvt_f32_f16_sdwa v25, v28 dst_sel:DWORD dst_unused:UNUSED_PAD src0_sel:WORD_1
	v_pk_fma_f32 v[18:19], v[24:25], s[34:35], v[18:19] op_sel_hi:[1,0,1]
	s_nop 0
	v_cvt_pk_f16_f32 v24, v18, v19
	v_cvt_f32_f16_e32 v18, v29
	v_cvt_f32_f16_sdwa v19, v29 dst_sel:DWORD dst_unused:UNUSED_PAD src0_sel:WORD_1
	v_pk_fma_f32 v[18:19], v[18:19], s[34:35], v[20:21] op_sel_hi:[1,0,1]
	s_nop 0
	v_cvt_pk_f16_f32 v25, v18, v19
	global_store_dwordx4 v[34:35], v[22:25], off offset:256
	s_nop 1
	v_lshl_add_u64 v[22:23], v[140:141], 0, s[2:3]
	v_lshl_add_u64 v[24:25], s[94:95], 0, v[22:23]
	s_waitcnt vmcnt(15)
	v_mov_b64_e32 v[18:19], v[224:225]
	v_mov_b64_e32 v[20:21], v[226:227]
	v_cvt_f32_f16_e32 v26, v18
	v_cvt_f32_f16_sdwa v27, v18 dst_sel:DWORD dst_unused:UNUSED_PAD src0_sel:WORD_1
	v_cvt_f32_f16_e32 v18, v19
	v_cvt_f32_f16_sdwa v19, v19 dst_sel:DWORD dst_unused:UNUSED_PAD src0_sel:WORD_1
	v_pk_fma_f32 v[14:15], v[26:27], s[34:35], v[14:15] op_sel_hi:[1,0,1]
	s_nop 0
	v_cvt_pk_f16_f32 v14, v14, v15
	v_pk_fma_f32 v[16:17], v[18:19], s[34:35], v[16:17] op_sel_hi:[1,0,1]
	v_lshl_add_u64 v[18:19], s[4:5], 0, v[22:23]
	v_cvt_pk_f16_f32 v15, v16, v17
	v_cvt_f32_f16_e32 v16, v20
	v_cvt_f32_f16_sdwa v17, v20 dst_sel:DWORD dst_unused:UNUSED_PAD src0_sel:WORD_1
	v_pk_fma_f32 v[10:11], v[16:17], s[34:35], v[10:11] op_sel_hi:[1,0,1]
	s_nop 0
	v_cvt_pk_f16_f32 v16, v10, v11
	v_cvt_f32_f16_e32 v10, v21
	v_cvt_f32_f16_sdwa v11, v21 dst_sel:DWORD dst_unused:UNUSED_PAD src0_sel:WORD_1
	v_pk_fma_f32 v[10:11], v[10:11], s[34:35], v[12:13] op_sel_hi:[1,0,1]
	s_nop 0
	v_cvt_pk_f16_f32 v17, v10, v11
	s_nop 0
	global_store_dwordx4 v[18:19], v[14:17], off
	s_waitcnt vmcnt(15)
	v_mov_b64_e32 v[10:11], v[228:229]
	v_mov_b64_e32 v[12:13], v[230:231]
	s_nop 0
	v_cvt_f32_f16_e32 v14, v10
	v_cvt_f32_f16_sdwa v15, v10 dst_sel:DWORD dst_unused:UNUSED_PAD src0_sel:WORD_1
	v_cvt_f32_f16_e32 v10, v11
	v_cvt_f32_f16_sdwa v11, v11 dst_sel:DWORD dst_unused:UNUSED_PAD src0_sel:WORD_1
	v_pk_fma_f32 v[6:7], v[14:15], s[34:35], v[6:7] op_sel_hi:[1,0,1]
	s_nop 0
	v_cvt_pk_f16_f32 v6, v6, v7
	v_pk_fma_f32 v[8:9], v[10:11], s[34:35], v[8:9] op_sel_hi:[1,0,1]
	s_nop 0
	v_cvt_pk_f16_f32 v7, v8, v9
	v_cvt_f32_f16_e32 v8, v12
	v_cvt_f32_f16_sdwa v9, v12 dst_sel:DWORD dst_unused:UNUSED_PAD src0_sel:WORD_1
	v_pk_fma_f32 v[2:3], v[8:9], s[34:35], v[2:3] op_sel_hi:[1,0,1]
	s_nop 0
	v_cvt_pk_f16_f32 v8, v2, v3
	v_cvt_f32_f16_e32 v2, v13
	v_cvt_f32_f16_sdwa v3, v13 dst_sel:DWORD dst_unused:UNUSED_PAD src0_sel:WORD_1
	v_pk_fma_f32 v[2:3], v[2:3], s[34:35], v[4:5] op_sel_hi:[1,0,1]
	s_nop 0
	v_cvt_pk_f16_f32 v9, v2, v3
	s_mov_b32 s35, s0
	global_store_dwordx4 v[18:19], v[6:9], off offset:256
	s_cbranch_vccz .LBB0_140
	s_waitcnt vmcnt(0)
	s_cmpk_gt_u32 s62, 0xff
	s_cbranch_scc1 .LBB0_151
	s_barrier

; #define PG8_STAGE(bufoff, gbase, voff) do { _Pragma("unroll") for (int _i = 0; _i < 2; ++_i) \
;         __builtin_amdgcn_global_load_lds((const unsigned*)((const char*)(gbase) + (voff)[_i]), (LAS unsigned*)(lds + (bufoff) + ldsw + _i * 8192), 16, 0, 0); } while (0)
; #define PG8_LDA(dst, b, h) do { _Pragma("unroll") for (int m = 0; m < 4; ++m) _Pragma("unroll") for (int k = 0; k < 2; ++k) dst[m][k] = *(const LAS h16x8*)(lds + PG8_SA(b, h) + aoff + m * 2048 + k * 1024); } while (0)
; #define PG8_LDB(dst, b, h) do { _Pragma("unroll") for (int n = 0; n < 2; ++n) _Pragma("unroll") for (int k = 0; k < 2; ++k) dst[n][k] = *(const LAS h16x8*)(lds + PG8_SB(b, h) + boff + n * 2048 + k * 1024); } while (0)
; #define PG8_MMA(ai, bj, At, Bt_) do { __builtin_amdgcn_s_setprio(1); _Pragma("unroll") for (int m = 0; m < 4; ++m) _Pragma("unroll") for (int n = 0; n < 2; ++n) _Pragma("unroll") for (int k = 0; k < 2; ++k) \
;         acc[ai][bj][m][n] = __builtin_amdgcn_mfma_f32_16x16x32_f16(Bt_[n][k], At[m][k], acc[ai][bj][m][n], 0, 0, 0); __builtin_amdgcn_s_setprio(0); } while (0)
; #define PG8_WAIT_V(n) asm volatile("s_waitcnt vmcnt(" #n ")" ::: "memory")
; template <class Epi, class AMap>
; __device__ __forceinline__ void gemm_phase(LAS unsigned char* lds, const AMap am, const int lda, const h16* Bt, const int ldb, const int M, const int N, const int K, const Epi& E) {
;     ...
;         for (int t = 0; t < nt; t += 2) {
;             const bool last = (t == nt - 2);
;             const char* a1 = cA + (size_t)(t + 1) * kstep;
;             const char* a2 = last ? nA : cA + (size_t)(t + 2) * kstep; const char* b2 = last ? nB : cB + (size_t)(t + 2) * kstep;
;             const char* a3 = a2 + kstep; const char* b3 = b2 + kstep;
;             PG8_LDB(B0, 0, 0); PG8_SCHED; PG8_LDA(At, 0, 0); PG8_STAGE(PG8_SA(1, 1), a1 + hstepA, voffA);
;             PG8_WAIT_L(8); PG8_BAR; PG8_WAIT_L(0); PG8_MMA(0, 0, At, B0); PG8_BAR; PG8_SCHED;
;             PG8_LDB(B1, 0, 1); PG8_STAGE(PG8_SB(0, 0), b2, voffB);
;             PG8_BAR; PG8_WAIT_L(0); PG8_MMA(0, 1, At, B1); PG8_BAR;
;             PG8_LDA(At, 0, 1); PG8_STAGE(PG8_SA(0, 0), a2, voffA);
;             PG8_BAR; PG8_WAIT_L(0); PG8_MMA(1, 0, At, B0); PG8_BAR; PG8_SCHED;
;             PG8_STAGE(PG8_SB(0, 1), b2 + hstepB, voffB);
;             PG8_WAIT_V(6); PG8_BAR; PG8_MMA(1, 1, At, B1); PG8_BAR;
.LBB0_268:
	s_add_u32 s42, s40, 0xfff80080
	s_addc_u32 s43, s41, -1
	s_add_i32 s45, 0, 0x10000
	v_add_u32_e32 v0, s45, v149
	ds_read_b128 v[142:145], v0
	ds_read_b128 v[154:157], v0 offset:1024
	ds_read_b128 v[158:161], v0 offset:2048
	ds_read_b128 v[162:165], v0 offset:3072
	s_cmp_eq_u32 s35, 28
	s_cselect_b32 s49, s23, s43
	s_cselect_b32 s48, s27, s42
	s_cselect_b32 s43, s1, s29
	s_cselect_b32 s42, s20, s21
	v_lshl_add_u64 v[146:147], s[40:41], 0, v[138:139]
	s_add_i32 m0, s72, 0xc000
	ds_read_b128 v[166:169], v153
	ds_read_b128 v[170:173], v153 offset:1024
	ds_read_b128 v[174:177], v153 offset:2048
	ds_read_b128 v[178:181], v153 offset:3072
	ds_read_b128 v[182:185], v153 offset:4096
	ds_read_b128 v[186:189], v153 offset:5120
	ds_read_b128 v[190:193], v153 offset:6144
	ds_read_b128 v[194:197], v153 offset:7168
	global_load_lds_dwordx4 v[146:147], off
	v_lshl_add_u64 v[146:147], s[40:41], 0, v[140:141]
	s_add_i32 m0, s72, 0xe000
	s_nop 0
	global_load_lds_dwordx4 v[146:147], off
	s_waitcnt lgkmcnt(8)
	s_barrier
	s_waitcnt lgkmcnt(0)
	s_waitcnt lgkmcnt(0)
	v_mfma_f32_16x16x32_f16 v[126:129], v[142:145], v[166:169], v[126:129]
	v_mfma_f32_16x16x32_f16 v[122:125], v[158:161], v[166:169], v[122:125]
	v_mfma_f32_16x16x32_f16 v[110:113], v[142:145], v[174:177], v[110:113]
	v_mfma_f32_16x16x32_f16 v[106:109], v[158:161], v[174:177], v[106:109]
	v_mfma_f32_16x16x32_f16 v[94:97], v[142:145], v[182:185], v[94:97]
	v_mfma_f32_16x16x32_f16 v[90:93], v[158:161], v[182:185], v[90:93]
	v_mfma_f32_16x16x32_f16 v[78:81], v[142:145], v[190:193], v[78:81]
	v_mfma_f32_16x16x32_f16 v[74:77], v[158:161], v[190:193], v[74:77]
	v_mfma_f32_16x16x32_f16 v[126:129], v[154:157], v[170:173], v[126:129]
	v_mfma_f32_16x16x32_f16 v[122:125], v[162:165], v[170:173], v[122:125]
	v_mfma_f32_16x16x32_f16 v[110:113], v[154:157], v[178:181], v[110:113]
	v_mfma_f32_16x16x32_f16 v[106:109], v[162:165], v[178:181], v[106:109]
	v_mfma_f32_16x16x32_f16 v[94:97], v[154:157], v[186:189], v[94:97]
	v_mfma_f32_16x16x32_f16 v[90:93], v[162:165], v[186:189], v[90:93]
	v_mfma_f32_16x16x32_f16 v[78:81], v[154:157], v[194:197], v[78:81]
	v_mfma_f32_16x16x32_f16 v[74:77], v[162:165], v[194:197], v[74:77]
	s_barrier
	s_add_i32 s60, 0, 0x14000
	s_add_i32 s45, s45, s65
	v_add_u32_e32 v0, s60, v149
	v_lshl_add_u64 v[146:147], s[42:43], 0, v[132:133]
	s_mov_b32 m0, s45
	ds_read_b128 v[198:201], v0
	ds_read_b128 v[202:205], v0 offset:1024
	ds_read_b128 v[220:223], v0 offset:2048
	ds_read_b128 v[224:227], v0 offset:3072
	global_load_lds_dwordx4 v[146:147], off
	v_lshl_add_u64 v[206:207], s[42:43], 0, v[136:137]
	s_add_i32 m0, s45, 0x2000
	s_nop 0
	global_load_lds_dwordx4 v[206:207], off
	s_barrier
	s_waitcnt lgkmcnt(0)
	s_waitcnt lgkmcnt(0)
	v_mfma_f32_16x16x32_f16 v[118:121], v[198:201], v[166:169], v[118:121]
	v_mfma_f32_16x16x32_f16 v[114:117], v[220:223], v[166:169], v[114:117]
	v_mfma_f32_16x16x32_f16 v[102:105], v[198:201], v[174:177], v[102:105]
	v_mfma_f32_16x16x32_f16 v[98:101], v[220:223], v[174:177], v[98:101]
	v_mfma_f32_16x16x32_f16 v[86:89], v[198:201], v[182:185], v[86:89]
	v_mfma_f32_16x16x32_f16 v[82:85], v[220:223], v[182:185], v[82:85]
	v_mfma_f32_16x16x32_f16 v[70:73], v[198:201], v[190:193], v[70:73]
	v_mfma_f32_16x16x32_f16 v[66:69], v[220:223], v[190:193], v[66:69]
	v_mfma_f32_16x16x32_f16 v[118:121], v[202:205], v[170:173], v[118:121]
	v_mfma_f32_16x16x32_f16 v[114:117], v[224:227], v[170:173], v[114:117]
	v_mfma_f32_16x16x32_f16 v[102:105], v[202:205], v[178:181], v[102:105]
	v_mfma_f32_16x16x32_f16 v[98:101], v[224:227], v[178:181], v[98:101]
	v_mfma_f32_16x16x32_f16 v[86:89], v[202:205], v[186:189], v[86:89]
	v_mfma_f32_16x16x32_f16 v[82:85], v[224:227], v[186:189], v[82:85]
	v_mfma_f32_16x16x32_f16 v[70:73], v[202:205], v[194:197], v[70:73]
	v_mfma_f32_16x16x32_f16 v[66:69], v[224:227], v[194:197], v[66:69]
	s_mov_b32 m0, s72
	v_lshl_add_u64 v[212:213], s[48:49], 0, v[130:131]
	s_barrier
	ds_read_b128 v[166:169], v153 offset:16384
	ds_read_b128 v[170:173], v153 offset:17408
	ds_read_b128 v[174:177], v153 offset:18432
	ds_read_b128 v[178:181], v153 offset:19456
	ds_read_b128 v[182:185], v153 offset:20480
	ds_read_b128 v[186:189], v153 offset:21504
	ds_read_b128 v[190:193], v153 offset:22528
	ds_read_b128 v[194:197], v153 offset:23552
	global_load_lds_dwordx4 v[212:213], off
	v_lshl_add_u64 v[228:229], s[48:49], 0, v[134:135]
	s_mov_b32 m0, s73
	s_nop 0
	global_load_lds_dwordx4 v[228:229], off
	s_barrier
	s_waitcnt lgkmcnt(0)
	s_waitcnt lgkmcnt(0)
	v_mfma_f32_16x16x32_f16 v[62:65], v[142:145], v[166:169], v[62:65]
	v_mfma_f32_16x16x32_f16 v[58:61], v[158:161], v[166:169], v[58:61]
	v_mfma_f32_16x16x32_f16 v[46:49], v[142:145], v[174:177], v[46:49]
	v_mfma_f32_16x16x32_f16 v[42:45], v[158:161], v[174:177], v[42:45]
	v_mfma_f32_16x16x32_f16 v[30:33], v[142:145], v[182:185], v[30:33]
	v_mfma_f32_16x16x32_f16 v[26:29], v[158:161], v[182:185], v[26:29]
	v_mfma_f32_16x16x32_f16 v[14:17], v[142:145], v[190:193], v[14:17]
	v_mfma_f32_16x16x32_f16 v[10:13], v[158:161], v[190:193], v[10:13]
	v_mfma_f32_16x16x32_f16 v[62:65], v[154:157], v[170:173], v[62:65]
	v_mfma_f32_16x16x32_f16 v[58:61], v[162:165], v[170:173], v[58:61]
	v_mfma_f32_16x16x32_f16 v[46:49], v[154:157], v[178:181], v[46:49]
	v_mfma_f32_16x16x32_f16 v[42:45], v[162:165], v[178:181], v[42:45]
	v_mfma_f32_16x16x32_f16 v[30:33], v[154:157], v[186:189], v[30:33]
	v_mfma_f32_16x16x32_f16 v[26:29], v[162:165], v[186:189], v[26:29]
	v_mfma_f32_16x16x32_f16 v[14:17], v[154:157], v[194:197], v[14:17]
	v_mfma_f32_16x16x32_f16 v[10:13], v[162:165], v[194:197], v[10:13]
	s_barrier
; #define PG8_STAGE(bufoff, gbase, voff) do { _Pragma("unroll") for (int _i = 0; _i < 2; ++_i) \
;         __builtin_amdgcn_global_load_lds((const unsigned*)((const char*)(gbase) + (voff)[_i]), (LAS unsigned*)(lds + (bufoff) + ldsw + _i * 8192), 16, 0, 0); } while (0)
; #define PG8_LDA(dst, b, h) do { _Pragma("unroll") for (int m = 0; m < 4; ++m) _Pragma("unroll") for (int k = 0; k < 2; ++k) dst[m][k] = *(const LAS h16x8*)(lds + PG8_SA(b, h) + aoff + m * 2048 + k * 1024); } while (0)
; #define PG8_LDB(dst, b, h) do { _Pragma("unroll") for (int n = 0; n < 2; ++n) _Pragma("unroll") for (int k = 0; k < 2; ++k) dst[n][k] = *(const LAS h16x8*)(lds + PG8_SB(b, h) + boff + n * 2048 + k * 1024); } while (0)
; #define PG8_MMA(ai, bj, At, Bt_) do { __builtin_amdgcn_s_setprio(1); _Pragma("unroll") for (int m = 0; m < 4; ++m) _Pragma("unroll") for (int n = 0; n < 2; ++n) _Pragma("unroll") for (int k = 0; k < 2; ++k) \
;         acc[ai][bj][m][n] = __builtin_amdgcn_mfma_f32_16x16x32_f16(Bt_[n][k], At[m][k], acc[ai][bj][m][n], 0, 0, 0); __builtin_amdgcn_s_setprio(0); } while (0)
; #define PG8_WAIT_V(n) asm volatile("s_waitcnt vmcnt(" #n ")" ::: "memory")
; #define PG8_WAIT_L(n) asm volatile("s_waitcnt lgkmcnt(" #n ")" ::: "memory")
; #define PG8_BAR __builtin_amdgcn_s_barrier()
; #define PG8_SCHED __builtin_amdgcn_sched_barrier(0)
; template <class Epi, class AMap>
; __device__ __forceinline__ void gemm_phase(LAS unsigned char* lds, const AMap am, const int lda, const h16* Bt, const int ldb, const int M, const int N, const int K, const Epi& E) {
;     ...
;             PG8_BAR; PG8_WAIT_L(0); PG8_MMA(1, 0, At, B0); PG8_BAR; PG8_SCHED;
;             PG8_STAGE(PG8_SB(0, 1), b2 + hstepB, voffB);
;             PG8_WAIT_V(6); PG8_BAR; PG8_MMA(1, 1, At, B1); PG8_BAR;
;             PG8_LDB(B0, 1, 0); PG8_SCHED; PG8_LDA(At, 1, 0); PG8_STAGE(PG8_SA(0, 1), a2 + hstepA, voffA);
;             PG8_WAIT_L(8); PG8_BAR; PG8_WAIT_L(0); PG8_MMA(0, 0, At, B0); PG8_BAR; PG8_SCHED;
;             PG8_LDB(B1, 1, 1); PG8_STAGE(PG8_SB(1, 0), b3, voffB);
;             PG8_BAR; PG8_WAIT_L(0); PG8_MMA(0, 1, At, B1); PG8_BAR;
;             PG8_LDA(At, 1, 1); PG8_STAGE(PG8_SA(1, 0), a3, voffA);
	s_add_u32 s50, s42, 0x80000
	s_addc_u32 s51, s43, 0
	s_add_i32 s45, s60, s65
	v_lshl_add_u64 v[142:143], s[50:51], 0, v[132:133]
	s_mov_b32 m0, s45
	s_nop 0
	global_load_lds_dwordx4 v[142:143], off
	v_lshl_add_u64 v[142:143], s[50:51], 0, v[136:137]
	s_add_i32 m0, s45, 0x2000
	s_nop 0
	global_load_lds_dwordx4 v[142:143], off
	s_waitcnt vmcnt(6)
	s_barrier
	v_mfma_f32_16x16x32_f16 v[54:57], v[198:201], v[166:169], v[54:57]
	v_mfma_f32_16x16x32_f16 v[50:53], v[220:223], v[166:169], v[50:53]
	v_mfma_f32_16x16x32_f16 v[38:41], v[198:201], v[174:177], v[38:41]
	v_mfma_f32_16x16x32_f16 v[34:37], v[220:223], v[174:177], v[34:37]
	v_mfma_f32_16x16x32_f16 v[22:25], v[198:201], v[182:185], v[22:25]
	v_mfma_f32_16x16x32_f16 v[18:21], v[220:223], v[182:185], v[18:21]
	v_mfma_f32_16x16x32_f16 v[6:9], v[198:201], v[190:193], v[6:9]
	v_mfma_f32_16x16x32_f16 v[2:5], v[220:223], v[190:193], v[2:5]
	v_mfma_f32_16x16x32_f16 v[54:57], v[202:205], v[170:173], v[54:57]
	v_mfma_f32_16x16x32_f16 v[50:53], v[224:227], v[170:173], v[50:53]
	v_mfma_f32_16x16x32_f16 v[38:41], v[202:205], v[178:181], v[38:41]
	v_mfma_f32_16x16x32_f16 v[34:37], v[224:227], v[178:181], v[34:37]
	v_mfma_f32_16x16x32_f16 v[22:25], v[202:205], v[186:189], v[22:25]
	v_mfma_f32_16x16x32_f16 v[18:21], v[224:227], v[186:189], v[18:21]
	v_mfma_f32_16x16x32_f16 v[6:9], v[202:205], v[194:197], v[6:9]
	v_mfma_f32_16x16x32_f16 v[2:5], v[224:227], v[194:197], v[2:5]
	s_add_i32 s45, 0, 0x18000
	v_add_u32_e32 v0, s45, v149
	s_barrier
	ds_read_b128 v[142:145], v0
	ds_read_b128 v[154:157], v0 offset:1024
	ds_read_b128 v[158:161], v0 offset:2048
	ds_read_b128 v[162:165], v0 offset:3072
	s_add_u32 s48, s48, 0x80000
	s_addc_u32 s49, s49, 0
	s_mov_b32 m0, s74
	v_lshl_add_u64 v[198:199], s[48:49], 0, v[130:131]
	ds_read_b128 v[166:169], v153 offset:32768
	ds_read_b128 v[170:173], v153 offset:33792
	ds_read_b128 v[174:177], v153 offset:34816
	ds_read_b128 v[178:181], v153 offset:35840
	ds_read_b128 v[182:185], v153 offset:36864
	ds_read_b128 v[186:189], v153 offset:37888
	ds_read_b128 v[190:193], v153 offset:38912
	ds_read_b128 v[194:197], v153 offset:39936
	global_load_lds_dwordx4 v[198:199], off
	v_lshl_add_u64 v[198:199], s[48:49], 0, v[134:135]
	s_mov_b32 m0, s75
	s_nop 0
	global_load_lds_dwordx4 v[198:199], off
	s_waitcnt lgkmcnt(8)
	s_barrier
	s_waitcnt lgkmcnt(0)
	s_waitcnt lgkmcnt(0)
	v_mfma_f32_16x16x32_f16 v[126:129], v[142:145], v[166:169], v[126:129]
	v_mfma_f32_16x16x32_f16 v[122:125], v[158:161], v[166:169], v[122:125]
	v_mfma_f32_16x16x32_f16 v[110:113], v[142:145], v[174:177], v[110:113]
	v_mfma_f32_16x16x32_f16 v[106:109], v[158:161], v[174:177], v[106:109]
	v_mfma_f32_16x16x32_f16 v[94:97], v[142:145], v[182:185], v[94:97]
	v_mfma_f32_16x16x32_f16 v[90:93], v[158:161], v[182:185], v[90:93]
	v_mfma_f32_16x16x32_f16 v[78:81], v[142:145], v[190:193], v[78:81]
	v_mfma_f32_16x16x32_f16 v[74:77], v[158:161], v[190:193], v[74:77]
	v_mfma_f32_16x16x32_f16 v[126:129], v[154:157], v[170:173], v[126:129]
	v_mfma_f32_16x16x32_f16 v[122:125], v[162:165], v[170:173], v[122:125]
	v_mfma_f32_16x16x32_f16 v[110:113], v[154:157], v[178:181], v[110:113]
	v_mfma_f32_16x16x32_f16 v[106:109], v[162:165], v[178:181], v[106:109]
	v_mfma_f32_16x16x32_f16 v[94:97], v[154:157], v[186:189], v[94:97]
	v_mfma_f32_16x16x32_f16 v[90:93], v[162:165], v[186:189], v[90:93]
	v_mfma_f32_16x16x32_f16 v[78:81], v[154:157], v[194:197], v[78:81]
	v_mfma_f32_16x16x32_f16 v[74:77], v[162:165], v[194:197], v[74:77]
	s_barrier
	s_add_i32 s48, 0, 0x1c000
	s_add_i32 s45, s45, s65
	v_add_u32_e32 v0, s48, v149
	v_lshl_add_u64 v[146:147], v[146:147], 0, s[92:93]
	s_mov_b32 m0, s45
	ds_read_b128 v[198:201], v0
	ds_read_b128 v[202:205], v0 offset:1024
	ds_read_b128 v[220:223], v0 offset:2048
	ds_read_b128 v[224:227], v0 offset:3072
	global_load_lds_dwordx4 v[146:147], off
	v_lshl_add_u64 v[146:147], v[206:207], 0, s[92:93]
	s_add_i32 m0, s45, 0x2000
	s_nop 0
	global_load_lds_dwordx4 v[146:147], off
	s_barrier
	s_waitcnt lgkmcnt(0)
	s_waitcnt lgkmcnt(0)
	v_mfma_f32_16x16x32_f16 v[118:121], v[198:201], v[166:169], v[118:121]
	v_mfma_f32_16x16x32_f16 v[114:117], v[220:223], v[166:169], v[114:117]
	v_mfma_f32_16x16x32_f16 v[102:105], v[198:201], v[174:177], v[102:105]
	v_mfma_f32_16x16x32_f16 v[98:101], v[220:223], v[174:177], v[98:101]
	v_mfma_f32_16x16x32_f16 v[86:89], v[198:201], v[182:185], v[86:89]
	v_mfma_f32_16x16x32_f16 v[82:85], v[220:223], v[182:185], v[82:85]
	v_mfma_f32_16x16x32_f16 v[70:73], v[198:201], v[190:193], v[70:73]
	v_mfma_f32_16x16x32_f16 v[66:69], v[220:223], v[190:193], v[66:69]
	v_mfma_f32_16x16x32_f16 v[118:121], v[202:205], v[170:173], v[118:121]
	v_mfma_f32_16x16x32_f16 v[114:117], v[224:227], v[170:173], v[114:117]
	v_mfma_f32_16x16x32_f16 v[102:105], v[202:205], v[178:181], v[102:105]
	v_mfma_f32_16x16x32_f16 v[98:101], v[224:227], v[178:181], v[98:101]
	v_mfma_f32_16x16x32_f16 v[86:89], v[202:205], v[186:189], v[86:89]
	v_mfma_f32_16x16x32_f16 v[82:85], v[224:227], v[186:189], v[82:85]
	v_mfma_f32_16x16x32_f16 v[70:73], v[202:205], v[194:197], v[70:73]
	v_mfma_f32_16x16x32_f16 v[66:69], v[224:227], v[194:197], v[66:69]
	s_mov_b32 m0, s77
	v_lshl_add_u64 v[146:147], v[212:213], 0, s[92:93]
	s_barrier
; #define PG8_STAGE(bufoff, gbase, voff) do { _Pragma("unroll") for (int _i = 0; _i < 2; ++_i) \
;         __builtin_amdgcn_global_load_lds((const unsigned*)((const char*)(gbase) + (voff)[_i]), (LAS unsigned*)(lds + (bufoff) + ldsw + _i * 8192), 16, 0, 0); } while (0)
; #define PG8_LDA(dst, b, h) do { _Pragma("unroll") for (int m = 0; m < 4; ++m) _Pragma("unroll") for (int k = 0; k < 2; ++k) dst[m][k] = *(const LAS h16x8*)(lds + PG8_SA(b, h) + aoff + m * 2048 + k * 1024); } while (0)
; #define PG8_WAIT_V(n) asm volatile("s_waitcnt vmcnt(" #n ")" ::: "memory")
; #define PG8_BAR __builtin_amdgcn_s_barrier()
; template <class Epi, class AMap>
; __device__ __forceinline__ void gemm_phase(LAS unsigned char* lds, const AMap am, const int lda, const h16* Bt, const int ldb, const int M, const int N, const int K, const Epi& E) {
;     ...
;             PG8_LDA(At, 1, 1); PG8_STAGE(PG8_SA(1, 0), a3, voffA);
;             PG8_BAR; PG8_WAIT_L(0); PG8_MMA(1, 0, At, B0); PG8_BAR; PG8_SCHED;
;             PG8_STAGE(PG8_SB(1, 1), b3 + hstepB, voffB);
;             PG8_WAIT_V(6); PG8_BAR; PG8_MMA(1, 1, At, B1); PG8_BAR;
;         }
;     __device__ __forceinline__ void operator()(const f32x4 (&acc)[2][2][4][2], const Unit& u, int wr, int wc, int fr, int fq) const {
;         const int row0 = u.pm * 256 + wr * 64 + fr; const int part = u.pn >> 3; const int colt = (u.pn & 7) * 256 + wc * 32 + 8 * fq;
; #pragma unroll
;         for (int ai = 0; ai < 2; ++ai)
; #pragma unroll
;             for (int m = 0; m < 4; ++m) { const int row = row0 + ai * 128 + m * 16;
; #pragma unroll
;                 for (int bj = 0; bj < 2; ++bj) { const int c = colt + bj * 128;
;                     if (part == 0) *(u32x4*)(Qb + (size_t)row * DM + c) = pack8(acc[ai][bj][m][0] * QSCALE, acc[ai][bj][m][1] * QSCALE);
;                     else if (part == 1) *(u32x4*)(Kb + (size_t)row * DM + c) = pack8(acc[ai][bj][m][0], acc[ai][bj][m][1]);
;                     else {
;                         const int b = row >> 13, t = row & 8191, hd = c >> 8, dv = c & 255;
;                         const int pos = (t & ~12) | ((t & 4) << 1) | ((t & 8) >> 1);
;                         h16* vp = Vt + ((size_t)((b * 8 + hd) * 256 + dv)) * SEQ + pos;
; #pragma unroll
;                         for (int j = 0; j < 4; ++j) { vp[(size_t)j * SEQ] = (h16)acc[ai][bj][m][0][j]; vp[(size_t)(4 + j) * SEQ] = (h16)acc[ai][bj][m][1][j]; }
	ds_read_b128 v[166:169], v153 offset:49152
	ds_read_b128 v[170:173], v153 offset:50176
	ds_read_b128 v[174:177], v153 offset:51200
	ds_read_b128 v[178:181], v153 offset:52224
	ds_read_b128 v[182:185], v153 offset:53248
	ds_read_b128 v[186:189], v153 offset:54272
	ds_read_b128 v[190:193], v153 offset:55296
	ds_read_b128 v[194:197], v153 offset:56320
	global_load_lds_dwordx4 v[146:147], off
	v_lshl_add_u64 v[146:147], v[228:229], 0, s[92:93]
	s_mov_b32 m0, s78
	s_nop 0
	global_load_lds_dwordx4 v[146:147], off
	s_barrier
	s_waitcnt lgkmcnt(0)
	s_waitcnt lgkmcnt(0)
	v_mfma_f32_16x16x32_f16 v[62:65], v[142:145], v[166:169], v[62:65]
	v_mfma_f32_16x16x32_f16 v[58:61], v[158:161], v[166:169], v[58:61]
	v_mfma_f32_16x16x32_f16 v[46:49], v[142:145], v[174:177], v[46:49]
	v_mfma_f32_16x16x32_f16 v[42:45], v[158:161], v[174:177], v[42:45]
	v_mfma_f32_16x16x32_f16 v[30:33], v[142:145], v[182:185], v[30:33]
	v_mfma_f32_16x16x32_f16 v[26:29], v[158:161], v[182:185], v[26:29]
	v_mfma_f32_16x16x32_f16 v[14:17], v[142:145], v[190:193], v[14:17]
	v_mfma_f32_16x16x32_f16 v[10:13], v[158:161], v[190:193], v[10:13]
	v_mfma_f32_16x16x32_f16 v[62:65], v[154:157], v[170:173], v[62:65]
	v_mfma_f32_16x16x32_f16 v[58:61], v[162:165], v[170:173], v[58:61]
	v_mfma_f32_16x16x32_f16 v[46:49], v[154:157], v[178:181], v[46:49]
	v_mfma_f32_16x16x32_f16 v[42:45], v[162:165], v[178:181], v[42:45]
	v_mfma_f32_16x16x32_f16 v[30:33], v[154:157], v[186:189], v[30:33]
	v_mfma_f32_16x16x32_f16 v[26:29], v[162:165], v[186:189], v[26:29]
	v_mfma_f32_16x16x32_f16 v[14:17], v[154:157], v[194:197], v[14:17]
	v_mfma_f32_16x16x32_f16 v[10:13], v[162:165], v[194:197], v[10:13]
	s_barrier
	s_add_u32 s42, s42, 0x80080
	s_addc_u32 s43, s43, 0
	s_add_i32 s45, s48, s65
	v_lshl_add_u64 v[142:143], s[42:43], 0, v[132:133]
	s_mov_b32 m0, s45
	s_nop 0
	global_load_lds_dwordx4 v[142:143], off
	v_lshl_add_u64 v[142:143], s[42:43], 0, v[136:137]
	s_add_i32 m0, s45, 0x2000
	s_nop 0
	global_load_lds_dwordx4 v[142:143], off
	s_waitcnt vmcnt(6)
	s_barrier
	v_mfma_f32_16x16x32_f16 v[54:57], v[198:201], v[166:169], v[54:57]
	v_mfma_f32_16x16x32_f16 v[50:53], v[220:223], v[166:169], v[50:53]
	v_mfma_f32_16x16x32_f16 v[38:41], v[198:201], v[174:177], v[38:41]
	v_mfma_f32_16x16x32_f16 v[34:37], v[220:223], v[174:177], v[34:37]
	v_mfma_f32_16x16x32_f16 v[22:25], v[198:201], v[182:185], v[22:25]
	v_mfma_f32_16x16x32_f16 v[18:21], v[220:223], v[182:185], v[18:21]
	v_mfma_f32_16x16x32_f16 v[6:9], v[198:201], v[190:193], v[6:9]
	v_mfma_f32_16x16x32_f16 v[2:5], v[220:223], v[190:193], v[2:5]
	v_mfma_f32_16x16x32_f16 v[54:57], v[202:205], v[170:173], v[54:57]
	v_mfma_f32_16x16x32_f16 v[50:53], v[224:227], v[170:173], v[50:53]
	v_mfma_f32_16x16x32_f16 v[38:41], v[202:205], v[178:181], v[38:41]
	v_mfma_f32_16x16x32_f16 v[34:37], v[224:227], v[178:181], v[34:37]
	v_mfma_f32_16x16x32_f16 v[22:25], v[202:205], v[186:189], v[22:25]
	v_mfma_f32_16x16x32_f16 v[18:21], v[224:227], v[186:189], v[18:21]
	v_mfma_f32_16x16x32_f16 v[6:9], v[202:205], v[194:197], v[6:9]
	v_mfma_f32_16x16x32_f16 v[2:5], v[224:227], v[194:197], v[2:5]
	s_add_i32 s35, s35, 2
	s_add_u32 s40, s40, 0x100
	s_addc_u32 s41, s41, 0
	s_add_u32 s21, s21, 0x100
	s_addc_u32 s29, s29, 0
	s_cmp_gt_u32 s35, 29
	s_barrier
	s_cbranch_scc0 .LBB0_268
	s_lshl_b32 s1, s26, 8
	s_add_i32 s20, s1, s76
	s_lshl_b32 s1, s22, 8
	s_and_b32 s1, s1, 0x700
	s_cmp_gt_u32 s22, 7
	s_cselect_b64 s[26:27], -1, 0
	s_and_b32 s21, s22, -8
	v_or_b32_e32 v142, s20, v148
	s_cmp_lg_u32 s21, 8
	s_cselect_b64 s[22:23], -1, 0
	s_ashr_i32 s20, s20, 2
	v_ashrrev_i32_e32 v143, 31, v142
	v_or_b32_e32 v154, s1, v150
	s_and_b32 s35, s20, 0xfffff800
	v_and_or_b32 v155, v142, s5, v151
	v_lshlrev_b64 v[144:145], 12, v[142:143]
	s_mov_b64 s[40:41], -1
	s_and_b64 vcc, exec, s[26:27]
	s_cbranch_vccz .LBB0_275
	s_and_b64 vcc, exec, s[22:23]
	s_cbranch_vccz .LBB0_272
	v_or_b32_e32 v146, s35, v154
	v_ashrrev_i32_e32 v147, 31, v146
	v_lshlrev_b64 v[146:147], 14, v[146:147]
	v_lshl_add_u64 v[146:147], s[30:31], 0, v[146:147]
	v_lshlrev_b32_e32 v0, 1, v155
	v_lshl_add_u64 v[146:147], v[146:147], 0, v[0:1]
	v_cvt_f16_f32_e32 v0, v126
	v_add_co_u32_e32 v156, vcc, 0x10000, v146
	s_mov_b64 s[40:41], 0
	global_store_short v[146:147], v0, off
	v_cvt_f16_f32_e32 v0, v122
	v_addc_co_u32_e32 v157, vcc, 0, v147, vcc
	global_store_short v[156:157], v0, off
	v_cvt_f16_f32_e32 v0, v127
	v_add_co_u32_e32 v156, vcc, 0x4000, v146
	s_nop 1
	v_addc_co_u32_e32 v157, vcc, 0, v147, vcc
	global_store_short v[156:157], v0, off
	v_cvt_f16_f32_e32 v0, v123
	v_add_co_u32_e32 v156, vcc, 0x14000, v146
	s_nop 1
	v_addc_co_u32_e32 v157, vcc, 0, v147, vcc
	global_store_short v[156:157], v0, off
	v_cvt_f16_f32_e32 v0, v128
	v_add_co_u32_e32 v156, vcc, 0x8000, v146
	s_nop 1
	v_addc_co_u32_e32 v157, vcc, 0, v147, vcc
	global_store_short v[156:157], v0, off
	v_cvt_f16_f32_e32 v0, v124
	v_add_co_u32_e32 v156, vcc, 0x18000, v146
	s_nop 1
	v_addc_co_u32_e32 v157, vcc, 0, v147, vcc
	global_store_short v[156:157], v0, off
	v_cvt_f16_f32_e32 v0, v129
	v_add_co_u32_e32 v156, vcc, 0xc000, v146
	s_nop 1
	v_addc_co_u32_e32 v157, vcc, 0, v147, vcc
	global_store_short v[156:157], v0, off
	v_cvt_f16_f32_e32 v0, v125
	v_add_co_u32_e32 v146, vcc, 0x1c000, v146
	s_nop 1
	v_addc_co_u32_e32 v147, vcc, 0, v147, vcc
	global_store_short v[146:147], v0, off

; #define PG8_STAGE(bufoff, gbase, voff) do { _Pragma("unroll") for (int _i = 0; _i < 2; ++_i) \
;         __builtin_amdgcn_global_load_lds((const unsigned*)((const char*)(gbase) + (voff)[_i]), (LAS unsigned*)(lds + (bufoff) + ldsw + _i * 8192), 16, 0, 0); } while (0)
; #define PG8_LDA(dst, b, h) do { _Pragma("unroll") for (int m = 0; m < 4; ++m) _Pragma("unroll") for (int k = 0; k < 2; ++k) dst[m][k] = *(const LAS h16x8*)(lds + PG8_SA(b, h) + aoff + m * 2048 + k * 1024); } while (0)
; #define PG8_LDB(dst, b, h) do { _Pragma("unroll") for (int n = 0; n < 2; ++n) _Pragma("unroll") for (int k = 0; k < 2; ++k) dst[n][k] = *(const LAS h16x8*)(lds + PG8_SB(b, h) + boff + n * 2048 + k * 1024); } while (0)
; #define PG8_MMA(ai, bj, At, Bt_) do { __builtin_amdgcn_s_setprio(1); _Pragma("unroll") for (int m = 0; m < 4; ++m) _Pragma("unroll") for (int n = 0; n < 2; ++n) _Pragma("unroll") for (int k = 0; k < 2; ++k) \
;         acc[ai][bj][m][n] = __builtin_amdgcn_mfma_f32_16x16x32_f16(Bt_[n][k], At[m][k], acc[ai][bj][m][n], 0, 0, 0); __builtin_amdgcn_s_setprio(0); } while (0)
; #define PG8_WAIT_L(n) asm volatile("s_waitcnt lgkmcnt(" #n ")" ::: "memory")
; #define PG8_BAR __builtin_amdgcn_s_barrier()
; #define PG8_SCHED __builtin_amdgcn_sched_barrier(0)
; template <class Epi, class AMap>
; __device__ __forceinline__ void gemm_phase(LAS unsigned char* lds, const AMap am, const int lda, const h16* Bt, const int ldb, const int M, const int N, const int K, const Epi& E) {
;     ...
;         for (int t = 0; t < nt; t += 2) {
;             const bool last = (t == nt - 2);
;             const char* a1 = cA + (size_t)(t + 1) * kstep;
;             const char* a2 = last ? nA : cA + (size_t)(t + 2) * kstep; const char* b2 = last ? nB : cB + (size_t)(t + 2) * kstep;
;             const char* a3 = a2 + kstep; const char* b3 = b2 + kstep;
;             PG8_LDB(B0, 0, 0); PG8_SCHED; PG8_LDA(At, 0, 0); PG8_STAGE(PG8_SA(1, 1), a1 + hstepA, voffA);
;             PG8_WAIT_L(8); PG8_BAR; PG8_WAIT_L(0); PG8_MMA(0, 0, At, B0); PG8_BAR; PG8_SCHED;
;             PG8_LDB(B1, 0, 1); PG8_STAGE(PG8_SB(0, 0), b2, voffB);
;             PG8_BAR; PG8_WAIT_L(0); PG8_MMA(0, 1, At, B1); PG8_BAR;
;             PG8_LDA(At, 0, 1); PG8_STAGE(PG8_SA(0, 0), a2, voffA);
;             PG8_BAR; PG8_WAIT_L(0); PG8_MMA(1, 0, At, B0); PG8_BAR; PG8_SCHED;
.LBB0_621:
	s_add_i32 s51, s26, 2
	s_add_u32 s0, s22, 0x100
	s_addc_u32 s1, s23, 0
	s_add_i32 s60, 0, 0x10000
	v_add_u32_e32 v152, s60, v155
	ds_read_b128 v[90:93], v152
	ds_read_b128 v[94:97], v152 offset:1024
	ds_read_b128 v[148:151], v152 offset:2048
	ds_read_b128 v[158:161], v152 offset:3072
	s_cmp_eq_u32 s82, s26
	s_cselect_b32 s26, s21, s29
	s_cselect_b32 s49, s65, s1
	s_cselect_b32 s48, s64, s0
	s_cselect_b32 s27, s20, s45
	v_lshl_add_u64 v[152:153], s[22:23], 0, v[144:145]
	s_add_i32 m0, s76, 0xc000
	ds_read_b128 v[162:165], v157
	ds_read_b128 v[166:169], v157 offset:1024
	ds_read_b128 v[170:173], v157 offset:2048
	ds_read_b128 v[174:177], v157 offset:3072
	ds_read_b128 v[178:181], v157 offset:4096
	ds_read_b128 v[182:185], v157 offset:5120
	ds_read_b128 v[186:189], v157 offset:6144
	ds_read_b128 v[190:193], v157 offset:7168
	global_load_lds_dwordx4 v[152:153], off
	v_lshl_add_u64 v[152:153], s[22:23], 0, v[146:147]
	s_add_i32 m0, s76, 0xe000
	s_nop 0
	global_load_lds_dwordx4 v[152:153], off
	s_waitcnt lgkmcnt(8)
	s_barrier
	s_waitcnt lgkmcnt(0)
	s_waitcnt lgkmcnt(0)
	v_mfma_f32_16x16x32_f16 v[130:133], v[90:93], v[162:165], v[130:133]
	v_mfma_f32_16x16x32_f16 v[134:137], v[148:151], v[162:165], v[134:137]
	v_mfma_f32_16x16x32_f16 v[126:129], v[90:93], v[170:173], v[126:129]
	v_mfma_f32_16x16x32_f16 v[122:125], v[148:151], v[170:173], v[122:125]
	v_mfma_f32_16x16x32_f16 v[118:121], v[90:93], v[178:181], v[118:121]
	v_mfma_f32_16x16x32_f16 v[114:117], v[148:151], v[178:181], v[114:117]
	v_mfma_f32_16x16x32_f16 v[110:113], v[90:93], v[186:189], v[110:113]
	v_mfma_f32_16x16x32_f16 v[106:109], v[148:151], v[186:189], v[106:109]
	v_mfma_f32_16x16x32_f16 v[130:133], v[94:97], v[166:169], v[130:133]
	v_mfma_f32_16x16x32_f16 v[134:137], v[158:161], v[166:169], v[134:137]
	v_mfma_f32_16x16x32_f16 v[126:129], v[94:97], v[174:177], v[126:129]
	v_mfma_f32_16x16x32_f16 v[122:125], v[158:161], v[174:177], v[122:125]
	v_mfma_f32_16x16x32_f16 v[118:121], v[94:97], v[182:185], v[118:121]
	v_mfma_f32_16x16x32_f16 v[114:117], v[158:161], v[182:185], v[114:117]
	v_mfma_f32_16x16x32_f16 v[110:113], v[94:97], v[190:193], v[110:113]
	v_mfma_f32_16x16x32_f16 v[106:109], v[158:161], v[190:193], v[106:109]
	s_barrier
	s_add_i32 s62, 0, 0x14000
	v_add_u32_e32 v152, s62, v155
	s_add_i32 s22, s60, s73
	ds_read_b128 v[194:197], v152
	ds_read_b128 v[198:201], v152 offset:1024
	ds_read_b128 v[202:205], v152 offset:2048
	ds_read_b128 v[220:223], v152 offset:3072
	v_lshl_add_u64 v[152:153], s[26:27], 0, v[0:1]
	s_mov_b32 m0, s22
	v_lshl_add_u64 v[206:207], s[26:27], 0, v[142:143]
	global_load_lds_dwordx4 v[152:153], off
	s_add_i32 m0, s22, 0x2000
	s_nop 0
	global_load_lds_dwordx4 v[206:207], off
	s_barrier
	s_waitcnt lgkmcnt(0)
	s_waitcnt lgkmcnt(0)
	v_mfma_f32_16x16x32_f16 v[62:65], v[194:197], v[162:165], v[62:65]
	v_mfma_f32_16x16x32_f16 v[58:61], v[202:205], v[162:165], v[58:61]
	v_mfma_f32_16x16x32_f16 v[54:57], v[194:197], v[170:173], v[54:57]
	v_mfma_f32_16x16x32_f16 v[50:53], v[202:205], v[170:173], v[50:53]
	v_mfma_f32_16x16x32_f16 v[46:49], v[194:197], v[178:181], v[46:49]
	v_mfma_f32_16x16x32_f16 v[42:45], v[202:205], v[178:181], v[42:45]
	v_mfma_f32_16x16x32_f16 v[38:41], v[194:197], v[186:189], v[38:41]
	v_mfma_f32_16x16x32_f16 v[34:37], v[202:205], v[186:189], v[34:37]
	v_mfma_f32_16x16x32_f16 v[62:65], v[198:201], v[166:169], v[62:65]
	v_mfma_f32_16x16x32_f16 v[58:61], v[220:223], v[166:169], v[58:61]
	v_mfma_f32_16x16x32_f16 v[54:57], v[198:201], v[174:177], v[54:57]
	v_mfma_f32_16x16x32_f16 v[50:53], v[220:223], v[174:177], v[50:53]
	v_mfma_f32_16x16x32_f16 v[46:49], v[198:201], v[182:185], v[46:49]
	v_mfma_f32_16x16x32_f16 v[42:45], v[220:223], v[182:185], v[42:45]
	v_mfma_f32_16x16x32_f16 v[38:41], v[198:201], v[190:193], v[38:41]
	v_mfma_f32_16x16x32_f16 v[34:37], v[220:223], v[190:193], v[34:37]
	s_mov_b32 m0, s76
	v_lshl_add_u64 v[212:213], s[48:49], 0, v[138:139]
	s_barrier
	ds_read_b128 v[162:165], v157 offset:16384
	ds_read_b128 v[166:169], v157 offset:17408
	ds_read_b128 v[170:173], v157 offset:18432
	ds_read_b128 v[174:177], v157 offset:19456
	ds_read_b128 v[178:181], v157 offset:20480
	ds_read_b128 v[182:185], v157 offset:21504
	ds_read_b128 v[186:189], v157 offset:22528
	ds_read_b128 v[190:193], v157 offset:23552
	global_load_lds_dwordx4 v[212:213], off
	v_lshl_add_u64 v[224:225], s[48:49], 0, v[140:141]
	s_mov_b32 m0, s77
	s_nop 0
	global_load_lds_dwordx4 v[224:225], off
	s_barrier
	s_waitcnt lgkmcnt(0)
	s_waitcnt lgkmcnt(0)
	v_mfma_f32_16x16x32_f16 v[102:105], v[90:93], v[162:165], v[102:105]
	v_mfma_f32_16x16x32_f16 v[98:101], v[148:151], v[162:165], v[98:101]
	v_mfma_f32_16x16x32_f16 v[86:89], v[90:93], v[170:173], v[86:89]
	v_mfma_f32_16x16x32_f16 v[82:85], v[148:151], v[170:173], v[82:85]
	v_mfma_f32_16x16x32_f16 v[78:81], v[90:93], v[178:181], v[78:81]
	v_mfma_f32_16x16x32_f16 v[74:77], v[148:151], v[178:181], v[74:77]
	v_mfma_f32_16x16x32_f16 v[70:73], v[90:93], v[186:189], v[70:73]
	v_mfma_f32_16x16x32_f16 v[66:69], v[148:151], v[186:189], v[66:69]
	v_mfma_f32_16x16x32_f16 v[102:105], v[94:97], v[166:169], v[102:105]
	v_mfma_f32_16x16x32_f16 v[98:101], v[158:161], v[166:169], v[98:101]
	v_mfma_f32_16x16x32_f16 v[86:89], v[94:97], v[174:177], v[86:89]
	v_mfma_f32_16x16x32_f16 v[82:85], v[158:161], v[174:177], v[82:85]
	v_mfma_f32_16x16x32_f16 v[78:81], v[94:97], v[182:185], v[78:81]
	v_mfma_f32_16x16x32_f16 v[74:77], v[158:161], v[182:185], v[74:77]
	v_mfma_f32_16x16x32_f16 v[70:73], v[94:97], v[190:193], v[70:73]
	v_mfma_f32_16x16x32_f16 v[66:69], v[158:161], v[190:193], v[66:69]
	s_barrier
; #define PG8_STAGE(bufoff, gbase, voff) do { _Pragma("unroll") for (int _i = 0; _i < 2; ++_i) \
;         __builtin_amdgcn_global_load_lds((const unsigned*)((const char*)(gbase) + (voff)[_i]), (LAS unsigned*)(lds + (bufoff) + ldsw + _i * 8192), 16, 0, 0); } while (0)
; #define PG8_LDA(dst, b, h) do { _Pragma("unroll") for (int m = 0; m < 4; ++m) _Pragma("unroll") for (int k = 0; k < 2; ++k) dst[m][k] = *(const LAS h16x8*)(lds + PG8_SA(b, h) + aoff + m * 2048 + k * 1024); } while (0)
; #define PG8_LDB(dst, b, h) do { _Pragma("unroll") for (int n = 0; n < 2; ++n) _Pragma("unroll") for (int k = 0; k < 2; ++k) dst[n][k] = *(const LAS h16x8*)(lds + PG8_SB(b, h) + boff + n * 2048 + k * 1024); } while (0)
; #define PG8_MMA(ai, bj, At, Bt_) do { __builtin_amdgcn_s_setprio(1); _Pragma("unroll") for (int m = 0; m < 4; ++m) _Pragma("unroll") for (int n = 0; n < 2; ++n) _Pragma("unroll") for (int k = 0; k < 2; ++k) \
;         acc[ai][bj][m][n] = __builtin_amdgcn_mfma_f32_16x16x32_f16(Bt_[n][k], At[m][k], acc[ai][bj][m][n], 0, 0, 0); __builtin_amdgcn_s_setprio(0); } while (0)
; #define PG8_WAIT_V(n) asm volatile("s_waitcnt vmcnt(" #n ")" ::: "memory")
; #define PG8_WAIT_L(n) asm volatile("s_waitcnt lgkmcnt(" #n ")" ::: "memory")
; #define PG8_BAR __builtin_amdgcn_s_barrier()
; #define PG8_SCHED __builtin_amdgcn_sched_barrier(0)
; template <class Epi, class AMap>
; __device__ __forceinline__ void gemm_phase(LAS unsigned char* lds, const AMap am, const int lda, const h16* Bt, const int ldb, const int M, const int N, const int K, const Epi& E) {
;     ...
;             PG8_STAGE(PG8_SB(0, 1), b2 + hstepB, voffB);
;             PG8_WAIT_V(6); PG8_BAR; PG8_MMA(1, 1, At, B1); PG8_BAR;
;             PG8_LDB(B0, 1, 0); PG8_SCHED; PG8_LDA(At, 1, 0); PG8_STAGE(PG8_SA(0, 1), a2 + hstepA, voffA);
;             PG8_WAIT_L(8); PG8_BAR; PG8_WAIT_L(0); PG8_MMA(0, 0, At, B0); PG8_BAR; PG8_SCHED;
;             PG8_LDB(B1, 1, 1); PG8_STAGE(PG8_SB(1, 0), b3, voffB);
;             PG8_BAR; PG8_WAIT_L(0); PG8_MMA(0, 1, At, B1); PG8_BAR;
	s_add_u32 s22, s26, 0x10000
	s_addc_u32 s23, s27, 0
	s_add_i32 s60, s62, s73
	v_lshl_add_u64 v[90:91], s[22:23], 0, v[0:1]
	s_mov_b32 m0, s60
	s_nop 0
	global_load_lds_dwordx4 v[90:91], off
	v_lshl_add_u64 v[90:91], s[22:23], 0, v[142:143]
	s_add_i32 m0, s60, 0x2000
	s_nop 0
	global_load_lds_dwordx4 v[90:91], off
	s_waitcnt vmcnt(6)
	s_barrier
	v_mfma_f32_16x16x32_f16 v[30:33], v[194:197], v[162:165], v[30:33]
	v_mfma_f32_16x16x32_f16 v[26:29], v[202:205], v[162:165], v[26:29]
	v_mfma_f32_16x16x32_f16 v[22:25], v[194:197], v[170:173], v[22:25]
	v_mfma_f32_16x16x32_f16 v[18:21], v[202:205], v[170:173], v[18:21]
	v_mfma_f32_16x16x32_f16 v[14:17], v[194:197], v[178:181], v[14:17]
	v_mfma_f32_16x16x32_f16 v[10:13], v[202:205], v[178:181], v[10:13]
	v_mfma_f32_16x16x32_f16 v[6:9], v[194:197], v[186:189], v[6:9]
	v_mfma_f32_16x16x32_f16 v[2:5], v[202:205], v[186:189], v[2:5]
	v_mfma_f32_16x16x32_f16 v[30:33], v[198:201], v[166:169], v[30:33]
	v_mfma_f32_16x16x32_f16 v[26:29], v[220:223], v[166:169], v[26:29]
	v_mfma_f32_16x16x32_f16 v[22:25], v[198:201], v[174:177], v[22:25]
	v_mfma_f32_16x16x32_f16 v[18:21], v[220:223], v[174:177], v[18:21]
	v_mfma_f32_16x16x32_f16 v[14:17], v[198:201], v[182:185], v[14:17]
	v_mfma_f32_16x16x32_f16 v[10:13], v[220:223], v[182:185], v[10:13]
	v_mfma_f32_16x16x32_f16 v[6:9], v[198:201], v[190:193], v[6:9]
	v_mfma_f32_16x16x32_f16 v[2:5], v[220:223], v[190:193], v[2:5]
	s_add_i32 s60, 0, 0x18000
	v_add_u32_e32 v158, s60, v155
	s_barrier
	ds_read_b128 v[90:93], v158
	ds_read_b128 v[94:97], v158 offset:1024
	ds_read_b128 v[148:151], v158 offset:2048
	ds_read_b128 v[158:161], v158 offset:3072
	s_add_u32 s22, s48, 0x1c0000
	s_addc_u32 s23, s49, 0
	s_mov_b32 m0, s78
	v_lshl_add_u64 v[194:195], s[22:23], 0, v[138:139]
	ds_read_b128 v[162:165], v157 offset:32768
	ds_read_b128 v[166:169], v157 offset:33792
	ds_read_b128 v[170:173], v157 offset:34816
	ds_read_b128 v[174:177], v157 offset:35840
	ds_read_b128 v[178:181], v157 offset:36864
	ds_read_b128 v[182:185], v157 offset:37888
	ds_read_b128 v[186:189], v157 offset:38912
	ds_read_b128 v[190:193], v157 offset:39936
	global_load_lds_dwordx4 v[194:195], off
	v_lshl_add_u64 v[194:195], s[22:23], 0, v[140:141]
	s_mov_b32 m0, s79
	s_nop 0
	global_load_lds_dwordx4 v[194:195], off
	s_waitcnt lgkmcnt(8)
	s_barrier
	s_waitcnt lgkmcnt(0)
	s_waitcnt lgkmcnt(0)
	v_mfma_f32_16x16x32_f16 v[130:133], v[90:93], v[162:165], v[130:133]
	v_mfma_f32_16x16x32_f16 v[134:137], v[148:151], v[162:165], v[134:137]
	v_mfma_f32_16x16x32_f16 v[126:129], v[90:93], v[170:173], v[126:129]
	v_mfma_f32_16x16x32_f16 v[122:125], v[148:151], v[170:173], v[122:125]
	v_mfma_f32_16x16x32_f16 v[118:121], v[90:93], v[178:181], v[118:121]
	v_mfma_f32_16x16x32_f16 v[114:117], v[148:151], v[178:181], v[114:117]
	v_mfma_f32_16x16x32_f16 v[110:113], v[90:93], v[186:189], v[110:113]
	v_mfma_f32_16x16x32_f16 v[106:109], v[148:151], v[186:189], v[106:109]
	v_mfma_f32_16x16x32_f16 v[130:133], v[94:97], v[166:169], v[130:133]
	v_mfma_f32_16x16x32_f16 v[134:137], v[158:161], v[166:169], v[134:137]
	v_mfma_f32_16x16x32_f16 v[126:129], v[94:97], v[174:177], v[126:129]
	v_mfma_f32_16x16x32_f16 v[122:125], v[158:161], v[174:177], v[122:125]
	v_mfma_f32_16x16x32_f16 v[118:121], v[94:97], v[182:185], v[118:121]
	v_mfma_f32_16x16x32_f16 v[114:117], v[158:161], v[182:185], v[114:117]
	v_mfma_f32_16x16x32_f16 v[110:113], v[94:97], v[190:193], v[110:113]
	v_mfma_f32_16x16x32_f16 v[106:109], v[158:161], v[190:193], v[106:109]
	s_barrier
	s_add_i32 s48, 0, 0x1c000
	s_add_i32 s22, s60, s73
	v_add_u32_e32 v214, s48, v155
	v_lshl_add_u64 v[152:153], v[152:153], 0, s[92:93]
	s_mov_b32 m0, s22
	ds_read_b128 v[194:197], v214
	ds_read_b128 v[198:201], v214 offset:1024
	ds_read_b128 v[202:205], v214 offset:2048
	ds_read_b128 v[220:223], v214 offset:3072
	global_load_lds_dwordx4 v[152:153], off
	v_lshl_add_u64 v[152:153], v[206:207], 0, s[92:93]
	s_add_i32 m0, s22, 0x2000
	s_nop 0
	global_load_lds_dwordx4 v[152:153], off
	s_barrier
; #define PG8_STAGE(bufoff, gbase, voff) do { _Pragma("unroll") for (int _i = 0; _i < 2; ++_i) \
;         __builtin_amdgcn_global_load_lds((const unsigned*)((const char*)(gbase) + (voff)[_i]), (LAS unsigned*)(lds + (bufoff) + ldsw + _i * 8192), 16, 0, 0); } while (0)
; #define PG8_LDA(dst, b, h) do { _Pragma("unroll") for (int m = 0; m < 4; ++m) _Pragma("unroll") for (int k = 0; k < 2; ++k) dst[m][k] = *(const LAS h16x8*)(lds + PG8_SA(b, h) + aoff + m * 2048 + k * 1024); } while (0)
; #define PG8_MMA(ai, bj, At, Bt_) do { __builtin_amdgcn_s_setprio(1); _Pragma("unroll") for (int m = 0; m < 4; ++m) _Pragma("unroll") for (int n = 0; n < 2; ++n) _Pragma("unroll") for (int k = 0; k < 2; ++k) \
;         acc[ai][bj][m][n] = __builtin_amdgcn_mfma_f32_16x16x32_f16(Bt_[n][k], At[m][k], acc[ai][bj][m][n], 0, 0, 0); __builtin_amdgcn_s_setprio(0); } while (0)
; #define PG8_WAIT_V(n) asm volatile("s_waitcnt vmcnt(" #n ")" ::: "memory")
; #define PG8_WAIT_L(n) asm volatile("s_waitcnt lgkmcnt(" #n ")" ::: "memory")
; #define PG8_BAR __builtin_amdgcn_s_barrier()
; #define PG8_SCHED __builtin_amdgcn_sched_barrier(0)
; template <class Epi, class AMap>
; __device__ __forceinline__ void gemm_phase(LAS unsigned char* lds, const AMap am, const int lda, const h16* Bt, const int ldb, const int M, const int N, const int K, const Epi& E) {
;     ...
;             PG8_BAR; PG8_WAIT_L(0); PG8_MMA(0, 1, At, B1); PG8_BAR;
;             PG8_LDA(At, 1, 1); PG8_STAGE(PG8_SA(1, 0), a3, voffA);
;             PG8_BAR; PG8_WAIT_L(0); PG8_MMA(1, 0, At, B0); PG8_BAR; PG8_SCHED;
;             PG8_STAGE(PG8_SB(1, 1), b3 + hstepB, voffB);
;             PG8_WAIT_V(6); PG8_BAR; PG8_MMA(1, 1, At, B1); PG8_BAR;
	s_waitcnt lgkmcnt(0)
	s_waitcnt lgkmcnt(0)
	v_mfma_f32_16x16x32_f16 v[62:65], v[194:197], v[162:165], v[62:65]
	v_mfma_f32_16x16x32_f16 v[58:61], v[202:205], v[162:165], v[58:61]
	v_mfma_f32_16x16x32_f16 v[54:57], v[194:197], v[170:173], v[54:57]
	v_mfma_f32_16x16x32_f16 v[50:53], v[202:205], v[170:173], v[50:53]
	v_mfma_f32_16x16x32_f16 v[46:49], v[194:197], v[178:181], v[46:49]
	v_mfma_f32_16x16x32_f16 v[42:45], v[202:205], v[178:181], v[42:45]
	v_mfma_f32_16x16x32_f16 v[38:41], v[194:197], v[186:189], v[38:41]
	v_mfma_f32_16x16x32_f16 v[34:37], v[202:205], v[186:189], v[34:37]
	v_mfma_f32_16x16x32_f16 v[62:65], v[198:201], v[166:169], v[62:65]
	v_mfma_f32_16x16x32_f16 v[58:61], v[220:223], v[166:169], v[58:61]
	v_mfma_f32_16x16x32_f16 v[54:57], v[198:201], v[174:177], v[54:57]
	v_mfma_f32_16x16x32_f16 v[50:53], v[220:223], v[174:177], v[50:53]
	v_mfma_f32_16x16x32_f16 v[46:49], v[198:201], v[182:185], v[46:49]
	v_mfma_f32_16x16x32_f16 v[42:45], v[220:223], v[182:185], v[42:45]
	v_mfma_f32_16x16x32_f16 v[38:41], v[198:201], v[190:193], v[38:41]
	v_mfma_f32_16x16x32_f16 v[34:37], v[220:223], v[190:193], v[34:37]
	s_mov_b32 m0, s80
	v_lshl_add_u64 v[152:153], v[212:213], 0, s[92:93]
	s_barrier
	ds_read_b128 v[162:165], v157 offset:49152
	ds_read_b128 v[166:169], v157 offset:50176
	ds_read_b128 v[170:173], v157 offset:51200
	ds_read_b128 v[174:177], v157 offset:52224
	ds_read_b128 v[178:181], v157 offset:53248
	ds_read_b128 v[182:185], v157 offset:54272
	ds_read_b128 v[186:189], v157 offset:55296
	ds_read_b128 v[190:193], v157 offset:56320
	global_load_lds_dwordx4 v[152:153], off
	v_lshl_add_u64 v[152:153], v[224:225], 0, s[92:93]
	s_mov_b32 m0, s81
	s_nop 0
	global_load_lds_dwordx4 v[152:153], off
	s_barrier
	s_waitcnt lgkmcnt(0)
	s_waitcnt lgkmcnt(0)
	v_mfma_f32_16x16x32_f16 v[102:105], v[90:93], v[162:165], v[102:105]
	v_mfma_f32_16x16x32_f16 v[98:101], v[148:151], v[162:165], v[98:101]
	v_mfma_f32_16x16x32_f16 v[86:89], v[90:93], v[170:173], v[86:89]
	v_mfma_f32_16x16x32_f16 v[82:85], v[148:151], v[170:173], v[82:85]
	v_mfma_f32_16x16x32_f16 v[78:81], v[90:93], v[178:181], v[78:81]
	v_mfma_f32_16x16x32_f16 v[74:77], v[148:151], v[178:181], v[74:77]
	v_mfma_f32_16x16x32_f16 v[70:73], v[90:93], v[186:189], v[70:73]
	v_mfma_f32_16x16x32_f16 v[66:69], v[148:151], v[186:189], v[66:69]
	v_mfma_f32_16x16x32_f16 v[102:105], v[94:97], v[166:169], v[102:105]
	v_mfma_f32_16x16x32_f16 v[98:101], v[158:161], v[166:169], v[98:101]
	v_mfma_f32_16x16x32_f16 v[86:89], v[94:97], v[174:177], v[86:89]
	v_mfma_f32_16x16x32_f16 v[82:85], v[158:161], v[174:177], v[82:85]
	v_mfma_f32_16x16x32_f16 v[78:81], v[94:97], v[182:185], v[78:81]
	v_mfma_f32_16x16x32_f16 v[74:77], v[158:161], v[182:185], v[74:77]
	v_mfma_f32_16x16x32_f16 v[70:73], v[94:97], v[190:193], v[70:73]
	v_mfma_f32_16x16x32_f16 v[66:69], v[158:161], v[190:193], v[66:69]
	s_barrier
	s_add_u32 s22, s26, 0x10080
	s_addc_u32 s23, s27, 0
	s_add_i32 s26, s48, s73
	v_lshl_add_u64 v[90:91], s[22:23], 0, v[0:1]
	s_mov_b32 m0, s26
	s_nop 0
	global_load_lds_dwordx4 v[90:91], off
	v_lshl_add_u64 v[90:91], s[22:23], 0, v[142:143]
	s_add_i32 m0, s26, 0x2000
	s_nop 0
	global_load_lds_dwordx4 v[90:91], off
	s_waitcnt vmcnt(6)
	s_barrier
	v_mfma_f32_16x16x32_f16 v[30:33], v[194:197], v[162:165], v[30:33]
	v_mfma_f32_16x16x32_f16 v[26:29], v[202:205], v[162:165], v[26:29]
	v_mfma_f32_16x16x32_f16 v[22:25], v[194:197], v[170:173], v[22:25]
	v_mfma_f32_16x16x32_f16 v[18:21], v[202:205], v[170:173], v[18:21]
	v_mfma_f32_16x16x32_f16 v[14:17], v[194:197], v[178:181], v[14:17]
	v_mfma_f32_16x16x32_f16 v[10:13], v[202:205], v[178:181], v[10:13]
	v_mfma_f32_16x16x32_f16 v[6:9], v[194:197], v[186:189], v[6:9]
	v_mfma_f32_16x16x32_f16 v[2:5], v[202:205], v[186:189], v[2:5]
	v_mfma_f32_16x16x32_f16 v[30:33], v[198:201], v[166:169], v[30:33]
	v_mfma_f32_16x16x32_f16 v[26:29], v[220:223], v[166:169], v[26:29]
	v_mfma_f32_16x16x32_f16 v[22:25], v[198:201], v[174:177], v[22:25]
	v_mfma_f32_16x16x32_f16 v[18:21], v[220:223], v[174:177], v[18:21]
	v_mfma_f32_16x16x32_f16 v[14:17], v[198:201], v[182:185], v[14:17]
	v_mfma_f32_16x16x32_f16 v[10:13], v[220:223], v[182:185], v[10:13]
	v_mfma_f32_16x16x32_f16 v[6:9], v[198:201], v[190:193], v[6:9]
	v_mfma_f32_16x16x32_f16 v[2:5], v[220:223], v[190:193], v[2:5]
	s_add_u32 s29, s29, 0x100
	s_addc_u32 s45, s45, 0
	s_cmp_ge_i32 s51, s24
	s_mov_b64 s[22:23], s[0:1]
	s_mov_b32 s26, s51
	s_barrier
	s_cbranch_scc0 .LBB0_621
	s_branch .LBB0_610

; #define PG8_STAGE(bufoff, gbase, voff) do { _Pragma("unroll") for (int _i = 0; _i < 2; ++_i) \
;         __builtin_amdgcn_global_load_lds((const unsigned*)((const char*)(gbase) + (voff)[_i]), (LAS unsigned*)(lds + (bufoff) + ldsw + _i * 8192), 16, 0, 0); } while (0)
; #define PG8_LDA(dst, b, h) do { _Pragma("unroll") for (int m = 0; m < 4; ++m) _Pragma("unroll") for (int k = 0; k < 2; ++k) dst[m][k] = *(const LAS h16x8*)(lds + PG8_SA(b, h) + aoff + m * 2048 + k * 1024); } while (0)
; #define PG8_LDB(dst, b, h) do { _Pragma("unroll") for (int n = 0; n < 2; ++n) _Pragma("unroll") for (int k = 0; k < 2; ++k) dst[n][k] = *(const LAS h16x8*)(lds + PG8_SB(b, h) + boff + n * 2048 + k * 1024); } while (0)
; #define PG8_MMA(ai, bj, At, Bt_) do { __builtin_amdgcn_s_setprio(1); _Pragma("unroll") for (int m = 0; m < 4; ++m) _Pragma("unroll") for (int n = 0; n < 2; ++n) _Pragma("unroll") for (int k = 0; k < 2; ++k) \
;         acc[ai][bj][m][n] = __builtin_amdgcn_mfma_f32_16x16x32_f16(Bt_[n][k], At[m][k], acc[ai][bj][m][n], 0, 0, 0); __builtin_amdgcn_s_setprio(0); } while (0)
; #define PG8_WAIT_L(n) asm volatile("s_waitcnt lgkmcnt(" #n ")" ::: "memory")
; #define PG8_BAR __builtin_amdgcn_s_barrier()
; #define PG8_SCHED __builtin_amdgcn_sched_barrier(0)
; template <class Epi, class AMap>
; __device__ __forceinline__ void gemm_phase(LAS unsigned char* lds, const AMap am, const int lda, const h16* Bt, const int ldb, const int M, const int N, const int K, const Epi& E) {
;     ...
;         for (int t = 0; t < nt; t += 2) {
;             const bool last = (t == nt - 2);
;             const char* a1 = cA + (size_t)(t + 1) * kstep;
;             const char* a2 = last ? nA : cA + (size_t)(t + 2) * kstep; const char* b2 = last ? nB : cB + (size_t)(t + 2) * kstep;
;             const char* a3 = a2 + kstep; const char* b3 = b2 + kstep;
;             PG8_LDB(B0, 0, 0); PG8_SCHED; PG8_LDA(At, 0, 0); PG8_STAGE(PG8_SA(1, 1), a1 + hstepA, voffA);
;             PG8_WAIT_L(8); PG8_BAR; PG8_WAIT_L(0); PG8_MMA(0, 0, At, B0); PG8_BAR; PG8_SCHED;
;             PG8_LDB(B1, 0, 1); PG8_STAGE(PG8_SB(0, 0), b2, voffB);
;             PG8_BAR; PG8_WAIT_L(0); PG8_MMA(0, 1, At, B1); PG8_BAR;
;             PG8_LDA(At, 0, 1); PG8_STAGE(PG8_SA(0, 0), a2, voffA);
;             PG8_BAR; PG8_WAIT_L(0); PG8_MMA(1, 0, At, B0); PG8_BAR; PG8_SCHED;
.LBB0_644:
	s_add_i32 s51, s26, 2
	s_add_u32 s0, s22, 0x100
	s_addc_u32 s1, s23, 0
	s_add_i32 s60, 0, 0x10000
	v_add_u32_e32 v152, s60, v203
	ds_read_b128 v[130:133], v152
	ds_read_b128 v[134:137], v152 offset:1024
	ds_read_b128 v[138:141], v152 offset:2048
	ds_read_b128 v[152:155], v152 offset:3072
	s_cmp_eq_u32 s80, s26
	s_cselect_b32 s26, s21, s29
	s_cselect_b32 s49, s47, s1
	s_cselect_b32 s48, s46, s0
	s_cselect_b32 s27, s20, s45
	v_lshl_add_u64 v[188:189], s[22:23], 0, v[148:149]
	s_add_i32 m0, s74, 0xc000
	ds_read_b128 v[156:159], v205
	ds_read_b128 v[160:163], v205 offset:1024
	ds_read_b128 v[164:167], v205 offset:2048
	ds_read_b128 v[168:171], v205 offset:3072
	ds_read_b128 v[172:175], v205 offset:4096
	ds_read_b128 v[176:179], v205 offset:5120
	ds_read_b128 v[180:183], v205 offset:6144
	ds_read_b128 v[184:187], v205 offset:7168
	global_load_lds_dwordx4 v[188:189], off
	v_lshl_add_u64 v[188:189], s[22:23], 0, v[150:151]
	s_add_i32 m0, s74, 0xe000
	s_nop 0
	global_load_lds_dwordx4 v[188:189], off
	s_waitcnt lgkmcnt(8)
	s_barrier
	s_waitcnt lgkmcnt(0)
	s_waitcnt lgkmcnt(0)
	v_mfma_f32_16x16x32_f16 v[122:125], v[130:133], v[156:159], v[122:125]
	v_mfma_f32_16x16x32_f16 v[126:129], v[138:141], v[156:159], v[126:129]
	v_mfma_f32_16x16x32_f16 v[110:113], v[130:133], v[164:167], v[110:113]
	v_mfma_f32_16x16x32_f16 v[106:109], v[138:141], v[164:167], v[106:109]
	v_mfma_f32_16x16x32_f16 v[94:97], v[130:133], v[172:175], v[94:97]
	v_mfma_f32_16x16x32_f16 v[90:93], v[138:141], v[172:175], v[90:93]
	v_mfma_f32_16x16x32_f16 v[78:81], v[130:133], v[180:183], v[78:81]
	v_mfma_f32_16x16x32_f16 v[74:77], v[138:141], v[180:183], v[74:77]
	v_mfma_f32_16x16x32_f16 v[122:125], v[134:137], v[160:163], v[122:125]
	v_mfma_f32_16x16x32_f16 v[126:129], v[152:155], v[160:163], v[126:129]
	v_mfma_f32_16x16x32_f16 v[110:113], v[134:137], v[168:171], v[110:113]
	v_mfma_f32_16x16x32_f16 v[106:109], v[152:155], v[168:171], v[106:109]
	v_mfma_f32_16x16x32_f16 v[94:97], v[134:137], v[176:179], v[94:97]
	v_mfma_f32_16x16x32_f16 v[90:93], v[152:155], v[176:179], v[90:93]
	v_mfma_f32_16x16x32_f16 v[78:81], v[134:137], v[184:187], v[78:81]
	v_mfma_f32_16x16x32_f16 v[74:77], v[152:155], v[184:187], v[74:77]
	s_barrier
	s_add_i32 s62, 0, 0x14000
	v_add_u32_e32 v200, s62, v203
	s_add_i32 s22, s60, s71
	ds_read_b128 v[188:191], v200
	ds_read_b128 v[192:195], v200 offset:1024
	ds_read_b128 v[196:199], v200 offset:2048
	ds_read_b128 v[220:223], v200 offset:3072
	v_lshl_add_u64 v[200:201], s[26:27], 0, v[0:1]
	s_mov_b32 m0, s22
	v_lshl_add_u64 v[206:207], s[26:27], 0, v[146:147]
	global_load_lds_dwordx4 v[200:201], off
	s_add_i32 m0, s22, 0x2000
	s_nop 0
	global_load_lds_dwordx4 v[206:207], off
	s_barrier
	s_waitcnt lgkmcnt(0)
	s_waitcnt lgkmcnt(0)
	v_mfma_f32_16x16x32_f16 v[118:121], v[188:191], v[156:159], v[118:121]
	v_mfma_f32_16x16x32_f16 v[114:117], v[196:199], v[156:159], v[114:117]
	v_mfma_f32_16x16x32_f16 v[102:105], v[188:191], v[164:167], v[102:105]
	v_mfma_f32_16x16x32_f16 v[98:101], v[196:199], v[164:167], v[98:101]
	v_mfma_f32_16x16x32_f16 v[86:89], v[188:191], v[172:175], v[86:89]
	v_mfma_f32_16x16x32_f16 v[82:85], v[196:199], v[172:175], v[82:85]
	v_mfma_f32_16x16x32_f16 v[70:73], v[188:191], v[180:183], v[70:73]
	v_mfma_f32_16x16x32_f16 v[66:69], v[196:199], v[180:183], v[66:69]
	v_mfma_f32_16x16x32_f16 v[118:121], v[192:195], v[160:163], v[118:121]
	v_mfma_f32_16x16x32_f16 v[114:117], v[220:223], v[160:163], v[114:117]
	v_mfma_f32_16x16x32_f16 v[102:105], v[192:195], v[168:171], v[102:105]
	v_mfma_f32_16x16x32_f16 v[98:101], v[220:223], v[168:171], v[98:101]
	v_mfma_f32_16x16x32_f16 v[86:89], v[192:195], v[176:179], v[86:89]
	v_mfma_f32_16x16x32_f16 v[82:85], v[220:223], v[176:179], v[82:85]
	v_mfma_f32_16x16x32_f16 v[70:73], v[192:195], v[184:187], v[70:73]
	v_mfma_f32_16x16x32_f16 v[66:69], v[220:223], v[184:187], v[66:69]
	s_mov_b32 m0, s74
	v_lshl_add_u64 v[212:213], s[48:49], 0, v[142:143]
	s_barrier
	ds_read_b128 v[156:159], v205 offset:16384
	ds_read_b128 v[160:163], v205 offset:17408
	ds_read_b128 v[164:167], v205 offset:18432
	ds_read_b128 v[168:171], v205 offset:19456
	ds_read_b128 v[172:175], v205 offset:20480
	ds_read_b128 v[176:179], v205 offset:21504
	ds_read_b128 v[180:183], v205 offset:22528
	ds_read_b128 v[184:187], v205 offset:23552
	global_load_lds_dwordx4 v[212:213], off
	v_lshl_add_u64 v[224:225], s[48:49], 0, v[144:145]
	s_mov_b32 m0, s75
	s_nop 0
	global_load_lds_dwordx4 v[224:225], off
	s_barrier
	s_waitcnt lgkmcnt(0)
	s_waitcnt lgkmcnt(0)
	v_mfma_f32_16x16x32_f16 v[62:65], v[130:133], v[156:159], v[62:65]
	v_mfma_f32_16x16x32_f16 v[58:61], v[138:141], v[156:159], v[58:61]
	v_mfma_f32_16x16x32_f16 v[46:49], v[130:133], v[164:167], v[46:49]
	v_mfma_f32_16x16x32_f16 v[42:45], v[138:141], v[164:167], v[42:45]
	v_mfma_f32_16x16x32_f16 v[30:33], v[130:133], v[172:175], v[30:33]
	v_mfma_f32_16x16x32_f16 v[26:29], v[138:141], v[172:175], v[26:29]
	v_mfma_f32_16x16x32_f16 v[14:17], v[130:133], v[180:183], v[14:17]
	v_mfma_f32_16x16x32_f16 v[10:13], v[138:141], v[180:183], v[10:13]
	v_mfma_f32_16x16x32_f16 v[62:65], v[134:137], v[160:163], v[62:65]
	v_mfma_f32_16x16x32_f16 v[58:61], v[152:155], v[160:163], v[58:61]
	v_mfma_f32_16x16x32_f16 v[46:49], v[134:137], v[168:171], v[46:49]
	v_mfma_f32_16x16x32_f16 v[42:45], v[152:155], v[168:171], v[42:45]
	v_mfma_f32_16x16x32_f16 v[30:33], v[134:137], v[176:179], v[30:33]
	v_mfma_f32_16x16x32_f16 v[26:29], v[152:155], v[176:179], v[26:29]
	v_mfma_f32_16x16x32_f16 v[14:17], v[134:137], v[184:187], v[14:17]
	v_mfma_f32_16x16x32_f16 v[10:13], v[152:155], v[184:187], v[10:13]
	s_barrier
; #define PG8_STAGE(bufoff, gbase, voff) do { _Pragma("unroll") for (int _i = 0; _i < 2; ++_i) \
;         __builtin_amdgcn_global_load_lds((const unsigned*)((const char*)(gbase) + (voff)[_i]), (LAS unsigned*)(lds + (bufoff) + ldsw + _i * 8192), 16, 0, 0); } while (0)
; #define PG8_LDA(dst, b, h) do { _Pragma("unroll") for (int m = 0; m < 4; ++m) _Pragma("unroll") for (int k = 0; k < 2; ++k) dst[m][k] = *(const LAS h16x8*)(lds + PG8_SA(b, h) + aoff + m * 2048 + k * 1024); } while (0)
; #define PG8_LDB(dst, b, h) do { _Pragma("unroll") for (int n = 0; n < 2; ++n) _Pragma("unroll") for (int k = 0; k < 2; ++k) dst[n][k] = *(const LAS h16x8*)(lds + PG8_SB(b, h) + boff + n * 2048 + k * 1024); } while (0)
; #define PG8_MMA(ai, bj, At, Bt_) do { __builtin_amdgcn_s_setprio(1); _Pragma("unroll") for (int m = 0; m < 4; ++m) _Pragma("unroll") for (int n = 0; n < 2; ++n) _Pragma("unroll") for (int k = 0; k < 2; ++k) \
;         acc[ai][bj][m][n] = __builtin_amdgcn_mfma_f32_16x16x32_f16(Bt_[n][k], At[m][k], acc[ai][bj][m][n], 0, 0, 0); __builtin_amdgcn_s_setprio(0); } while (0)
; #define PG8_WAIT_V(n) asm volatile("s_waitcnt vmcnt(" #n ")" ::: "memory")
; #define PG8_WAIT_L(n) asm volatile("s_waitcnt lgkmcnt(" #n ")" ::: "memory")
; #define PG8_BAR __builtin_amdgcn_s_barrier()
; #define PG8_SCHED __builtin_amdgcn_sched_barrier(0)
; template <class Epi, class AMap>
; __device__ __forceinline__ void gemm_phase(LAS unsigned char* lds, const AMap am, const int lda, const h16* Bt, const int ldb, const int M, const int N, const int K, const Epi& E) {
;     ...
;             PG8_STAGE(PG8_SB(0, 1), b2 + hstepB, voffB);
;             PG8_WAIT_V(6); PG8_BAR; PG8_MMA(1, 1, At, B1); PG8_BAR;
;             PG8_LDB(B0, 1, 0); PG8_SCHED; PG8_LDA(At, 1, 0); PG8_STAGE(PG8_SA(0, 1), a2 + hstepA, voffA);
;             PG8_WAIT_L(8); PG8_BAR; PG8_WAIT_L(0); PG8_MMA(0, 0, At, B0); PG8_BAR; PG8_SCHED;
;             PG8_LDB(B1, 1, 1); PG8_STAGE(PG8_SB(1, 0), b3, voffB);
;             PG8_BAR; PG8_WAIT_L(0); PG8_MMA(0, 1, At, B1); PG8_BAR;
	s_add_u32 s22, s26, 0x10000
	s_addc_u32 s23, s27, 0
	s_add_i32 s60, s62, s71
	v_lshl_add_u64 v[130:131], s[22:23], 0, v[0:1]
	s_mov_b32 m0, s60
	s_nop 0
	global_load_lds_dwordx4 v[130:131], off
	v_lshl_add_u64 v[130:131], s[22:23], 0, v[146:147]
	s_add_i32 m0, s60, 0x2000
	s_nop 0
	global_load_lds_dwordx4 v[130:131], off
	s_waitcnt vmcnt(6)
	s_barrier
	v_mfma_f32_16x16x32_f16 v[54:57], v[188:191], v[156:159], v[54:57]
	v_mfma_f32_16x16x32_f16 v[50:53], v[196:199], v[156:159], v[50:53]
	v_mfma_f32_16x16x32_f16 v[38:41], v[188:191], v[164:167], v[38:41]
	v_mfma_f32_16x16x32_f16 v[34:37], v[196:199], v[164:167], v[34:37]
	v_mfma_f32_16x16x32_f16 v[22:25], v[188:191], v[172:175], v[22:25]
	v_mfma_f32_16x16x32_f16 v[18:21], v[196:199], v[172:175], v[18:21]
	v_mfma_f32_16x16x32_f16 v[6:9], v[188:191], v[180:183], v[6:9]
	v_mfma_f32_16x16x32_f16 v[2:5], v[196:199], v[180:183], v[2:5]
	v_mfma_f32_16x16x32_f16 v[54:57], v[192:195], v[160:163], v[54:57]
	v_mfma_f32_16x16x32_f16 v[50:53], v[220:223], v[160:163], v[50:53]
	v_mfma_f32_16x16x32_f16 v[38:41], v[192:195], v[168:171], v[38:41]
	v_mfma_f32_16x16x32_f16 v[34:37], v[220:223], v[168:171], v[34:37]
	v_mfma_f32_16x16x32_f16 v[22:25], v[192:195], v[176:179], v[22:25]
	v_mfma_f32_16x16x32_f16 v[18:21], v[220:223], v[176:179], v[18:21]
	v_mfma_f32_16x16x32_f16 v[6:9], v[192:195], v[184:187], v[6:9]
	v_mfma_f32_16x16x32_f16 v[2:5], v[220:223], v[184:187], v[2:5]
	s_add_i32 s60, 0, 0x18000
	v_add_u32_e32 v152, s60, v203
	s_barrier
	ds_read_b128 v[130:133], v152
	ds_read_b128 v[134:137], v152 offset:1024
	ds_read_b128 v[138:141], v152 offset:2048
	ds_read_b128 v[152:155], v152 offset:3072
	s_add_u32 s22, s48, 0x1c0000
	s_addc_u32 s23, s49, 0
	s_mov_b32 m0, s76
	v_lshl_add_u64 v[188:189], s[22:23], 0, v[142:143]
	ds_read_b128 v[156:159], v205 offset:32768
	ds_read_b128 v[160:163], v205 offset:33792
	ds_read_b128 v[164:167], v205 offset:34816
	ds_read_b128 v[168:171], v205 offset:35840
	ds_read_b128 v[172:175], v205 offset:36864
	ds_read_b128 v[176:179], v205 offset:37888
	ds_read_b128 v[180:183], v205 offset:38912
	ds_read_b128 v[184:187], v205 offset:39936
	global_load_lds_dwordx4 v[188:189], off
	v_lshl_add_u64 v[188:189], s[22:23], 0, v[144:145]
	s_mov_b32 m0, s77
	s_nop 0
	global_load_lds_dwordx4 v[188:189], off
	s_waitcnt lgkmcnt(8)
	s_barrier
	s_waitcnt lgkmcnt(0)
	s_waitcnt lgkmcnt(0)
	v_mfma_f32_16x16x32_f16 v[122:125], v[130:133], v[156:159], v[122:125]
	v_mfma_f32_16x16x32_f16 v[126:129], v[138:141], v[156:159], v[126:129]
	v_mfma_f32_16x16x32_f16 v[110:113], v[130:133], v[164:167], v[110:113]
	v_mfma_f32_16x16x32_f16 v[106:109], v[138:141], v[164:167], v[106:109]
	v_mfma_f32_16x16x32_f16 v[94:97], v[130:133], v[172:175], v[94:97]
	v_mfma_f32_16x16x32_f16 v[90:93], v[138:141], v[172:175], v[90:93]
	v_mfma_f32_16x16x32_f16 v[78:81], v[130:133], v[180:183], v[78:81]
	v_mfma_f32_16x16x32_f16 v[74:77], v[138:141], v[180:183], v[74:77]
	v_mfma_f32_16x16x32_f16 v[122:125], v[134:137], v[160:163], v[122:125]
	v_mfma_f32_16x16x32_f16 v[126:129], v[152:155], v[160:163], v[126:129]
	v_mfma_f32_16x16x32_f16 v[110:113], v[134:137], v[168:171], v[110:113]
	v_mfma_f32_16x16x32_f16 v[106:109], v[152:155], v[168:171], v[106:109]
	v_mfma_f32_16x16x32_f16 v[94:97], v[134:137], v[176:179], v[94:97]
	v_mfma_f32_16x16x32_f16 v[90:93], v[152:155], v[176:179], v[90:93]
	v_mfma_f32_16x16x32_f16 v[78:81], v[134:137], v[184:187], v[78:81]
	v_mfma_f32_16x16x32_f16 v[74:77], v[152:155], v[184:187], v[74:77]
	s_barrier
	s_add_i32 s48, 0, 0x1c000
	s_add_i32 s22, s60, s71
	v_add_u32_e32 v214, s48, v203
	v_lshl_add_u64 v[200:201], v[200:201], 0, s[92:93]
	s_mov_b32 m0, s22
	ds_read_b128 v[188:191], v214
	ds_read_b128 v[192:195], v214 offset:1024
	ds_read_b128 v[196:199], v214 offset:2048
	ds_read_b128 v[220:223], v214 offset:3072
	global_load_lds_dwordx4 v[200:201], off
	v_lshl_add_u64 v[200:201], v[206:207], 0, s[92:93]
	s_add_i32 m0, s22, 0x2000
	s_nop 0
	global_load_lds_dwordx4 v[200:201], off
	s_barrier
; #define PG8_STAGE(bufoff, gbase, voff) do { _Pragma("unroll") for (int _i = 0; _i < 2; ++_i) \
;         __builtin_amdgcn_global_load_lds((const unsigned*)((const char*)(gbase) + (voff)[_i]), (LAS unsigned*)(lds + (bufoff) + ldsw + _i * 8192), 16, 0, 0); } while (0)
; #define PG8_LDA(dst, b, h) do { _Pragma("unroll") for (int m = 0; m < 4; ++m) _Pragma("unroll") for (int k = 0; k < 2; ++k) dst[m][k] = *(const LAS h16x8*)(lds + PG8_SA(b, h) + aoff + m * 2048 + k * 1024); } while (0)
; #define PG8_MMA(ai, bj, At, Bt_) do { __builtin_amdgcn_s_setprio(1); _Pragma("unroll") for (int m = 0; m < 4; ++m) _Pragma("unroll") for (int n = 0; n < 2; ++n) _Pragma("unroll") for (int k = 0; k < 2; ++k) \
;         acc[ai][bj][m][n] = __builtin_amdgcn_mfma_f32_16x16x32_f16(Bt_[n][k], At[m][k], acc[ai][bj][m][n], 0, 0, 0); __builtin_amdgcn_s_setprio(0); } while (0)
; #define PG8_WAIT_V(n) asm volatile("s_waitcnt vmcnt(" #n ")" ::: "memory")
; #define PG8_WAIT_L(n) asm volatile("s_waitcnt lgkmcnt(" #n ")" ::: "memory")
; #define PG8_BAR __builtin_amdgcn_s_barrier()
; #define PG8_SCHED __builtin_amdgcn_sched_barrier(0)
; template <class Epi, class AMap>
; __device__ __forceinline__ void gemm_phase(LAS unsigned char* lds, const AMap am, const int lda, const h16* Bt, const int ldb, const int M, const int N, const int K, const Epi& E) {
;     ...
;             PG8_BAR; PG8_WAIT_L(0); PG8_MMA(0, 1, At, B1); PG8_BAR;
;             PG8_LDA(At, 1, 1); PG8_STAGE(PG8_SA(1, 0), a3, voffA);
;             PG8_BAR; PG8_WAIT_L(0); PG8_MMA(1, 0, At, B0); PG8_BAR; PG8_SCHED;
;             PG8_STAGE(PG8_SB(1, 1), b3 + hstepB, voffB);
;             PG8_WAIT_V(6); PG8_BAR; PG8_MMA(1, 1, At, B1); PG8_BAR;
	s_waitcnt lgkmcnt(0)
	s_waitcnt lgkmcnt(0)
	v_mfma_f32_16x16x32_f16 v[118:121], v[188:191], v[156:159], v[118:121]
	v_mfma_f32_16x16x32_f16 v[114:117], v[196:199], v[156:159], v[114:117]
	v_mfma_f32_16x16x32_f16 v[102:105], v[188:191], v[164:167], v[102:105]
	v_mfma_f32_16x16x32_f16 v[98:101], v[196:199], v[164:167], v[98:101]
	v_mfma_f32_16x16x32_f16 v[86:89], v[188:191], v[172:175], v[86:89]
	v_mfma_f32_16x16x32_f16 v[82:85], v[196:199], v[172:175], v[82:85]
	v_mfma_f32_16x16x32_f16 v[70:73], v[188:191], v[180:183], v[70:73]
	v_mfma_f32_16x16x32_f16 v[66:69], v[196:199], v[180:183], v[66:69]
	v_mfma_f32_16x16x32_f16 v[118:121], v[192:195], v[160:163], v[118:121]
	v_mfma_f32_16x16x32_f16 v[114:117], v[220:223], v[160:163], v[114:117]
	v_mfma_f32_16x16x32_f16 v[102:105], v[192:195], v[168:171], v[102:105]
	v_mfma_f32_16x16x32_f16 v[98:101], v[220:223], v[168:171], v[98:101]
	v_mfma_f32_16x16x32_f16 v[86:89], v[192:195], v[176:179], v[86:89]
	v_mfma_f32_16x16x32_f16 v[82:85], v[220:223], v[176:179], v[82:85]
	v_mfma_f32_16x16x32_f16 v[70:73], v[192:195], v[184:187], v[70:73]
	v_mfma_f32_16x16x32_f16 v[66:69], v[220:223], v[184:187], v[66:69]
	s_mov_b32 m0, s78
	v_lshl_add_u64 v[200:201], v[212:213], 0, s[92:93]
	s_barrier
	ds_read_b128 v[156:159], v205 offset:49152
	ds_read_b128 v[160:163], v205 offset:50176
	ds_read_b128 v[164:167], v205 offset:51200
	ds_read_b128 v[168:171], v205 offset:52224
	ds_read_b128 v[172:175], v205 offset:53248
	ds_read_b128 v[176:179], v205 offset:54272
	ds_read_b128 v[180:183], v205 offset:55296
	ds_read_b128 v[184:187], v205 offset:56320
	global_load_lds_dwordx4 v[200:201], off
	v_lshl_add_u64 v[200:201], v[224:225], 0, s[92:93]
	s_mov_b32 m0, s79
	s_nop 0
	global_load_lds_dwordx4 v[200:201], off
	s_barrier
	s_waitcnt lgkmcnt(0)
	s_waitcnt lgkmcnt(0)
	v_mfma_f32_16x16x32_f16 v[62:65], v[130:133], v[156:159], v[62:65]
	v_mfma_f32_16x16x32_f16 v[58:61], v[138:141], v[156:159], v[58:61]
	v_mfma_f32_16x16x32_f16 v[46:49], v[130:133], v[164:167], v[46:49]
	v_mfma_f32_16x16x32_f16 v[42:45], v[138:141], v[164:167], v[42:45]
	v_mfma_f32_16x16x32_f16 v[30:33], v[130:133], v[172:175], v[30:33]
	v_mfma_f32_16x16x32_f16 v[26:29], v[138:141], v[172:175], v[26:29]
	v_mfma_f32_16x16x32_f16 v[14:17], v[130:133], v[180:183], v[14:17]
	v_mfma_f32_16x16x32_f16 v[10:13], v[138:141], v[180:183], v[10:13]
	v_mfma_f32_16x16x32_f16 v[62:65], v[134:137], v[160:163], v[62:65]
	v_mfma_f32_16x16x32_f16 v[58:61], v[152:155], v[160:163], v[58:61]
	v_mfma_f32_16x16x32_f16 v[46:49], v[134:137], v[168:171], v[46:49]
	v_mfma_f32_16x16x32_f16 v[42:45], v[152:155], v[168:171], v[42:45]
	v_mfma_f32_16x16x32_f16 v[30:33], v[134:137], v[176:179], v[30:33]
	v_mfma_f32_16x16x32_f16 v[26:29], v[152:155], v[176:179], v[26:29]
	v_mfma_f32_16x16x32_f16 v[14:17], v[134:137], v[184:187], v[14:17]
	v_mfma_f32_16x16x32_f16 v[10:13], v[152:155], v[184:187], v[10:13]
	s_barrier
	s_add_u32 s22, s26, 0x10080
	s_addc_u32 s23, s27, 0
	s_add_i32 s26, s48, s71
	v_lshl_add_u64 v[130:131], s[22:23], 0, v[0:1]
	s_mov_b32 m0, s26
	s_nop 0
	global_load_lds_dwordx4 v[130:131], off
	v_lshl_add_u64 v[130:131], s[22:23], 0, v[146:147]
	s_add_i32 m0, s26, 0x2000
	s_nop 0
	global_load_lds_dwordx4 v[130:131], off
	s_waitcnt vmcnt(6)
	s_barrier
	v_mfma_f32_16x16x32_f16 v[54:57], v[188:191], v[156:159], v[54:57]
	v_mfma_f32_16x16x32_f16 v[50:53], v[196:199], v[156:159], v[50:53]
	v_mfma_f32_16x16x32_f16 v[38:41], v[188:191], v[164:167], v[38:41]
	v_mfma_f32_16x16x32_f16 v[34:37], v[196:199], v[164:167], v[34:37]
	v_mfma_f32_16x16x32_f16 v[22:25], v[188:191], v[172:175], v[22:25]
	v_mfma_f32_16x16x32_f16 v[18:21], v[196:199], v[172:175], v[18:21]
	v_mfma_f32_16x16x32_f16 v[6:9], v[188:191], v[180:183], v[6:9]
	v_mfma_f32_16x16x32_f16 v[2:5], v[196:199], v[180:183], v[2:5]
	v_mfma_f32_16x16x32_f16 v[54:57], v[192:195], v[160:163], v[54:57]
	v_mfma_f32_16x16x32_f16 v[50:53], v[220:223], v[160:163], v[50:53]
	v_mfma_f32_16x16x32_f16 v[38:41], v[192:195], v[168:171], v[38:41]
	v_mfma_f32_16x16x32_f16 v[34:37], v[220:223], v[168:171], v[34:37]
	v_mfma_f32_16x16x32_f16 v[22:25], v[192:195], v[176:179], v[22:25]
	v_mfma_f32_16x16x32_f16 v[18:21], v[220:223], v[176:179], v[18:21]
	v_mfma_f32_16x16x32_f16 v[6:9], v[192:195], v[184:187], v[6:9]
	v_mfma_f32_16x16x32_f16 v[2:5], v[220:223], v[184:187], v[2:5]
	s_add_u32 s29, s29, 0x100
	s_addc_u32 s45, s45, 0
	s_cmp_ge_i32 s51, s24
	s_mov_b64 s[22:23], s[0:1]
	s_mov_b32 s26, s51
	s_barrier
	s_cbranch_scc0 .LBB0_644
	s_branch .LBB0_633

; #define PG8_STAGE(bufoff, gbase, voff) do { _Pragma("unroll") for (int _i = 0; _i < 2; ++_i) \
;         __builtin_amdgcn_global_load_lds((const unsigned*)((const char*)(gbase) + (voff)[_i]), (LAS unsigned*)(lds + (bufoff) + ldsw + _i * 8192), 16, 0, 0); } while (0)
; #define PG8_LDA(dst, b, h) do { _Pragma("unroll") for (int m = 0; m < 4; ++m) _Pragma("unroll") for (int k = 0; k < 2; ++k) dst[m][k] = *(const LAS h16x8*)(lds + PG8_SA(b, h) + aoff + m * 2048 + k * 1024); } while (0)
; #define PG8_LDB(dst, b, h) do { _Pragma("unroll") for (int n = 0; n < 2; ++n) _Pragma("unroll") for (int k = 0; k < 2; ++k) dst[n][k] = *(const LAS h16x8*)(lds + PG8_SB(b, h) + boff + n * 2048 + k * 1024); } while (0)
; #define PG8_MMA(ai, bj, At, Bt_) do { __builtin_amdgcn_s_setprio(1); _Pragma("unroll") for (int m = 0; m < 4; ++m) _Pragma("unroll") for (int n = 0; n < 2; ++n) _Pragma("unroll") for (int k = 0; k < 2; ++k) \
;         acc[ai][bj][m][n] = __builtin_amdgcn_mfma_f32_16x16x32_f16(Bt_[n][k], At[m][k], acc[ai][bj][m][n], 0, 0, 0); __builtin_amdgcn_s_setprio(0); } while (0)
; #define PG8_WAIT_L(n) asm volatile("s_waitcnt lgkmcnt(" #n ")" ::: "memory")
; #define PG8_BAR __builtin_amdgcn_s_barrier()
; #define PG8_SCHED __builtin_amdgcn_sched_barrier(0)
; template <class Epi, class AMap>
; __device__ __forceinline__ void gemm_phase(LAS unsigned char* lds, const AMap am, const int lda, const h16* Bt, const int ldb, const int M, const int N, const int K, const Epi& E) {
;     ...
;         for (int t = 0; t < nt; t += 2) {
;             const bool last = (t == nt - 2);
;             const char* a1 = cA + (size_t)(t + 1) * kstep;
;             const char* a2 = last ? nA : cA + (size_t)(t + 2) * kstep; const char* b2 = last ? nB : cB + (size_t)(t + 2) * kstep;
;             const char* a3 = a2 + kstep; const char* b3 = b2 + kstep;
;             PG8_LDB(B0, 0, 0); PG8_SCHED; PG8_LDA(At, 0, 0); PG8_STAGE(PG8_SA(1, 1), a1 + hstepA, voffA);
;             PG8_WAIT_L(8); PG8_BAR; PG8_WAIT_L(0); PG8_MMA(0, 0, At, B0); PG8_BAR; PG8_SCHED;
;             PG8_LDB(B1, 0, 1); PG8_STAGE(PG8_SB(0, 0), b2, voffB);
;             PG8_BAR; PG8_WAIT_L(0); PG8_MMA(0, 1, At, B1); PG8_BAR;
;             PG8_LDA(At, 0, 1); PG8_STAGE(PG8_SA(0, 0), a2, voffA);
;             PG8_BAR; PG8_WAIT_L(0); PG8_MMA(1, 0, At, B0); PG8_BAR; PG8_SCHED;
.LBB0_667:
	s_add_i32 s60, s46, 2
	s_add_u32 s0, s44, 0x100
	s_addc_u32 s1, s45, 0
	s_add_i32 s66, 0, 0x10000
	v_add_u32_e32 v152, s66, v161
	ds_read_b128 v[140:143], v152
	ds_read_b128 v[144:147], v152 offset:1024
	ds_read_b128 v[148:151], v152 offset:2048
	ds_read_b128 v[152:155], v152 offset:3072
	s_cmp_eq_u32 s73, s46
	s_cselect_b32 s46, s21, s27
	s_cselect_b32 s49, s41, s1
	s_cselect_b32 s48, s40, s0
	s_cselect_b32 s47, s20, s29
	v_lshl_add_u64 v[192:193], s[44:45], 0, v[136:137]
	s_add_i32 m0, s65, 0xc000
	ds_read_b128 v[156:159], v163
	ds_read_b128 v[164:167], v163 offset:1024
	ds_read_b128 v[168:171], v163 offset:2048
	ds_read_b128 v[172:175], v163 offset:3072
	ds_read_b128 v[176:179], v163 offset:4096
	ds_read_b128 v[180:183], v163 offset:5120
	ds_read_b128 v[184:187], v163 offset:6144
	ds_read_b128 v[188:191], v163 offset:7168
	global_load_lds_dwordx4 v[192:193], off
	v_lshl_add_u64 v[192:193], s[44:45], 0, v[138:139]
	s_add_i32 m0, s65, 0xe000
	s_nop 0
	global_load_lds_dwordx4 v[192:193], off
	s_waitcnt lgkmcnt(8)
	s_barrier
	s_waitcnt lgkmcnt(0)
	s_waitcnt lgkmcnt(0)
	v_mfma_f32_16x16x32_f16 v[126:129], v[140:143], v[156:159], v[126:129]
	v_mfma_f32_16x16x32_f16 v[122:125], v[148:151], v[156:159], v[122:125]
	v_mfma_f32_16x16x32_f16 v[118:121], v[140:143], v[168:171], v[118:121]
	v_mfma_f32_16x16x32_f16 v[114:117], v[148:151], v[168:171], v[114:117]
	v_mfma_f32_16x16x32_f16 v[110:113], v[140:143], v[176:179], v[110:113]
	v_mfma_f32_16x16x32_f16 v[106:109], v[148:151], v[176:179], v[106:109]
	v_mfma_f32_16x16x32_f16 v[102:105], v[140:143], v[184:187], v[102:105]
	v_mfma_f32_16x16x32_f16 v[98:101], v[148:151], v[184:187], v[98:101]
	v_mfma_f32_16x16x32_f16 v[126:129], v[144:147], v[164:167], v[126:129]
	v_mfma_f32_16x16x32_f16 v[122:125], v[152:155], v[164:167], v[122:125]
	v_mfma_f32_16x16x32_f16 v[118:121], v[144:147], v[172:175], v[118:121]
	v_mfma_f32_16x16x32_f16 v[114:117], v[152:155], v[172:175], v[114:117]
	v_mfma_f32_16x16x32_f16 v[110:113], v[144:147], v[180:183], v[110:113]
	v_mfma_f32_16x16x32_f16 v[106:109], v[152:155], v[180:183], v[106:109]
	v_mfma_f32_16x16x32_f16 v[102:105], v[144:147], v[188:191], v[102:105]
	v_mfma_f32_16x16x32_f16 v[98:101], v[152:155], v[188:191], v[98:101]
	s_barrier
	s_add_i32 s78, 0, 0x14000
	s_add_i32 s44, s66, s62
	v_add_u32_e32 v204, s78, v161
	v_lshl_add_u64 v[212:213], s[46:47], 0, v[0:1]
	s_mov_b32 m0, s44
	ds_read_b128 v[192:195], v204
	ds_read_b128 v[196:199], v204 offset:1024
	ds_read_b128 v[200:203], v204 offset:2048
	ds_read_b128 v[204:207], v204 offset:3072
	global_load_lds_dwordx4 v[212:213], off
	v_lshl_add_u64 v[220:221], s[46:47], 0, v[134:135]
	s_add_i32 m0, s44, 0x2000
	s_nop 0
	global_load_lds_dwordx4 v[220:221], off
	s_barrier
	s_waitcnt lgkmcnt(0)
	s_waitcnt lgkmcnt(0)
	v_mfma_f32_16x16x32_f16 v[94:97], v[192:195], v[156:159], v[94:97]
	v_mfma_f32_16x16x32_f16 v[86:89], v[200:203], v[156:159], v[86:89]
	v_mfma_f32_16x16x32_f16 v[78:81], v[192:195], v[168:171], v[78:81]
	v_mfma_f32_16x16x32_f16 v[70:73], v[200:203], v[168:171], v[70:73]
	v_mfma_f32_16x16x32_f16 v[62:65], v[192:195], v[176:179], v[62:65]
	v_mfma_f32_16x16x32_f16 v[54:57], v[200:203], v[176:179], v[54:57]
	v_mfma_f32_16x16x32_f16 v[46:49], v[192:195], v[184:187], v[46:49]
	v_mfma_f32_16x16x32_f16 v[38:41], v[200:203], v[184:187], v[38:41]
	v_mfma_f32_16x16x32_f16 v[94:97], v[196:199], v[164:167], v[94:97]
	v_mfma_f32_16x16x32_f16 v[86:89], v[204:207], v[164:167], v[86:89]
	v_mfma_f32_16x16x32_f16 v[78:81], v[196:199], v[172:175], v[78:81]
	v_mfma_f32_16x16x32_f16 v[70:73], v[204:207], v[172:175], v[70:73]
	v_mfma_f32_16x16x32_f16 v[62:65], v[196:199], v[180:183], v[62:65]
	v_mfma_f32_16x16x32_f16 v[54:57], v[204:207], v[180:183], v[54:57]
	v_mfma_f32_16x16x32_f16 v[46:49], v[196:199], v[188:191], v[46:49]
	v_mfma_f32_16x16x32_f16 v[38:41], v[204:207], v[188:191], v[38:41]
	s_mov_b32 m0, s65
	v_lshl_add_u64 v[222:223], s[48:49], 0, v[130:131]
	s_barrier
	ds_read_b128 v[156:159], v163 offset:16384
	ds_read_b128 v[164:167], v163 offset:17408
	ds_read_b128 v[168:171], v163 offset:18432
	ds_read_b128 v[172:175], v163 offset:19456
	ds_read_b128 v[176:179], v163 offset:20480
	ds_read_b128 v[180:183], v163 offset:21504
	ds_read_b128 v[184:187], v163 offset:22528
	ds_read_b128 v[188:191], v163 offset:23552
	global_load_lds_dwordx4 v[222:223], off
	v_lshl_add_u64 v[224:225], s[48:49], 0, v[132:133]
	s_mov_b32 m0, s68
	s_nop 0
	global_load_lds_dwordx4 v[224:225], off
	s_barrier
	s_waitcnt lgkmcnt(0)
	s_waitcnt lgkmcnt(0)
	v_mfma_f32_16x16x32_f16 v[90:93], v[140:143], v[156:159], v[90:93]
	v_mfma_f32_16x16x32_f16 v[82:85], v[148:151], v[156:159], v[82:85]
	v_mfma_f32_16x16x32_f16 v[74:77], v[140:143], v[168:171], v[74:77]
	v_mfma_f32_16x16x32_f16 v[66:69], v[148:151], v[168:171], v[66:69]
	v_mfma_f32_16x16x32_f16 v[58:61], v[140:143], v[176:179], v[58:61]
	v_mfma_f32_16x16x32_f16 v[50:53], v[148:151], v[176:179], v[50:53]
	v_mfma_f32_16x16x32_f16 v[42:45], v[140:143], v[184:187], v[42:45]
	v_mfma_f32_16x16x32_f16 v[34:37], v[148:151], v[184:187], v[34:37]
	v_mfma_f32_16x16x32_f16 v[90:93], v[144:147], v[164:167], v[90:93]
	v_mfma_f32_16x16x32_f16 v[82:85], v[152:155], v[164:167], v[82:85]
	v_mfma_f32_16x16x32_f16 v[74:77], v[144:147], v[172:175], v[74:77]
	v_mfma_f32_16x16x32_f16 v[66:69], v[152:155], v[172:175], v[66:69]
	v_mfma_f32_16x16x32_f16 v[58:61], v[144:147], v[180:183], v[58:61]
	v_mfma_f32_16x16x32_f16 v[50:53], v[152:155], v[180:183], v[50:53]
	v_mfma_f32_16x16x32_f16 v[42:45], v[144:147], v[188:191], v[42:45]
	v_mfma_f32_16x16x32_f16 v[34:37], v[152:155], v[188:191], v[34:37]
	s_barrier
; #define PG8_STAGE(bufoff, gbase, voff) do { _Pragma("unroll") for (int _i = 0; _i < 2; ++_i) \
;         __builtin_amdgcn_global_load_lds((const unsigned*)((const char*)(gbase) + (voff)[_i]), (LAS unsigned*)(lds + (bufoff) + ldsw + _i * 8192), 16, 0, 0); } while (0)
; #define PG8_LDA(dst, b, h) do { _Pragma("unroll") for (int m = 0; m < 4; ++m) _Pragma("unroll") for (int k = 0; k < 2; ++k) dst[m][k] = *(const LAS h16x8*)(lds + PG8_SA(b, h) + aoff + m * 2048 + k * 1024); } while (0)
; #define PG8_LDB(dst, b, h) do { _Pragma("unroll") for (int n = 0; n < 2; ++n) _Pragma("unroll") for (int k = 0; k < 2; ++k) dst[n][k] = *(const LAS h16x8*)(lds + PG8_SB(b, h) + boff + n * 2048 + k * 1024); } while (0)
; #define PG8_MMA(ai, bj, At, Bt_) do { __builtin_amdgcn_s_setprio(1); _Pragma("unroll") for (int m = 0; m < 4; ++m) _Pragma("unroll") for (int n = 0; n < 2; ++n) _Pragma("unroll") for (int k = 0; k < 2; ++k) \
;         acc[ai][bj][m][n] = __builtin_amdgcn_mfma_f32_16x16x32_f16(Bt_[n][k], At[m][k], acc[ai][bj][m][n], 0, 0, 0); __builtin_amdgcn_s_setprio(0); } while (0)
; #define PG8_WAIT_V(n) asm volatile("s_waitcnt vmcnt(" #n ")" ::: "memory")
; #define PG8_WAIT_L(n) asm volatile("s_waitcnt lgkmcnt(" #n ")" ::: "memory")
; #define PG8_BAR __builtin_amdgcn_s_barrier()
; #define PG8_SCHED __builtin_amdgcn_sched_barrier(0)
; template <class Epi, class AMap>
; __device__ __forceinline__ void gemm_phase(LAS unsigned char* lds, const AMap am, const int lda, const h16* Bt, const int ldb, const int M, const int N, const int K, const Epi& E) {
;     ...
;             PG8_STAGE(PG8_SB(0, 1), b2 + hstepB, voffB);
;             PG8_WAIT_V(6); PG8_BAR; PG8_MMA(1, 1, At, B1); PG8_BAR;
;             PG8_LDB(B0, 1, 0); PG8_SCHED; PG8_LDA(At, 1, 0); PG8_STAGE(PG8_SA(0, 1), a2 + hstepA, voffA);
;             PG8_WAIT_L(8); PG8_BAR; PG8_WAIT_L(0); PG8_MMA(0, 0, At, B0); PG8_BAR; PG8_SCHED;
;             PG8_LDB(B1, 1, 1); PG8_STAGE(PG8_SB(1, 0), b3, voffB);
;             PG8_BAR; PG8_WAIT_L(0); PG8_MMA(0, 1, At, B1); PG8_BAR;
;             PG8_LDA(At, 1, 1); PG8_STAGE(PG8_SA(1, 0), a3, voffA);
;             PG8_BAR; PG8_WAIT_L(0); PG8_MMA(1, 0, At, B0); PG8_BAR; PG8_SCHED;
	s_add_u32 s44, s46, 0x10000
	s_addc_u32 s45, s47, 0
	s_add_i32 s66, s78, s62
	v_lshl_add_u64 v[140:141], s[44:45], 0, v[0:1]
	s_mov_b32 m0, s66
	s_nop 0
	global_load_lds_dwordx4 v[140:141], off
	v_lshl_add_u64 v[140:141], s[44:45], 0, v[134:135]
	s_add_i32 m0, s66, 0x2000
	s_nop 0
	global_load_lds_dwordx4 v[140:141], off
	s_waitcnt vmcnt(6)
	s_barrier
	v_mfma_f32_16x16x32_f16 v[30:33], v[192:195], v[156:159], v[30:33]
	v_mfma_f32_16x16x32_f16 v[26:29], v[200:203], v[156:159], v[26:29]
	v_mfma_f32_16x16x32_f16 v[22:25], v[192:195], v[168:171], v[22:25]
	v_mfma_f32_16x16x32_f16 v[18:21], v[200:203], v[168:171], v[18:21]
	v_mfma_f32_16x16x32_f16 v[14:17], v[192:195], v[176:179], v[14:17]
	v_mfma_f32_16x16x32_f16 v[10:13], v[200:203], v[176:179], v[10:13]
	v_mfma_f32_16x16x32_f16 v[6:9], v[192:195], v[184:187], v[6:9]
	v_mfma_f32_16x16x32_f16 v[2:5], v[200:203], v[184:187], v[2:5]
	v_mfma_f32_16x16x32_f16 v[30:33], v[196:199], v[164:167], v[30:33]
	v_mfma_f32_16x16x32_f16 v[26:29], v[204:207], v[164:167], v[26:29]
	v_mfma_f32_16x16x32_f16 v[22:25], v[196:199], v[172:175], v[22:25]
	v_mfma_f32_16x16x32_f16 v[18:21], v[204:207], v[172:175], v[18:21]
	v_mfma_f32_16x16x32_f16 v[14:17], v[196:199], v[180:183], v[14:17]
	v_mfma_f32_16x16x32_f16 v[10:13], v[204:207], v[180:183], v[10:13]
	v_mfma_f32_16x16x32_f16 v[6:9], v[196:199], v[188:191], v[6:9]
	v_mfma_f32_16x16x32_f16 v[2:5], v[204:207], v[188:191], v[2:5]
	s_add_i32 s66, 0, 0x18000
	v_add_u32_e32 v152, s66, v161
	s_barrier
	ds_read_b128 v[140:143], v152
	ds_read_b128 v[144:147], v152 offset:1024
	ds_read_b128 v[148:151], v152 offset:2048
	ds_read_b128 v[152:155], v152 offset:3072
	s_add_u32 s44, s48, 0x1c0000
	s_addc_u32 s45, s49, 0
	s_mov_b32 m0, s69
	v_lshl_add_u64 v[192:193], s[44:45], 0, v[130:131]
	ds_read_b128 v[156:159], v163 offset:32768
	ds_read_b128 v[164:167], v163 offset:33792
	ds_read_b128 v[168:171], v163 offset:34816
	ds_read_b128 v[172:175], v163 offset:35840
	ds_read_b128 v[176:179], v163 offset:36864
	ds_read_b128 v[180:183], v163 offset:37888
	ds_read_b128 v[184:187], v163 offset:38912
	ds_read_b128 v[188:191], v163 offset:39936
	global_load_lds_dwordx4 v[192:193], off
	v_lshl_add_u64 v[192:193], s[44:45], 0, v[132:133]
	s_mov_b32 m0, s70
	s_nop 0
	global_load_lds_dwordx4 v[192:193], off
	s_waitcnt lgkmcnt(8)
	s_barrier
	s_waitcnt lgkmcnt(0)
	s_waitcnt lgkmcnt(0)
	v_mfma_f32_16x16x32_f16 v[126:129], v[140:143], v[156:159], v[126:129]
	v_mfma_f32_16x16x32_f16 v[122:125], v[148:151], v[156:159], v[122:125]
	v_mfma_f32_16x16x32_f16 v[118:121], v[140:143], v[168:171], v[118:121]
	v_mfma_f32_16x16x32_f16 v[114:117], v[148:151], v[168:171], v[114:117]
	v_mfma_f32_16x16x32_f16 v[110:113], v[140:143], v[176:179], v[110:113]
	v_mfma_f32_16x16x32_f16 v[106:109], v[148:151], v[176:179], v[106:109]
	v_mfma_f32_16x16x32_f16 v[102:105], v[140:143], v[184:187], v[102:105]
	v_mfma_f32_16x16x32_f16 v[98:101], v[148:151], v[184:187], v[98:101]
	v_mfma_f32_16x16x32_f16 v[126:129], v[144:147], v[164:167], v[126:129]
	v_mfma_f32_16x16x32_f16 v[122:125], v[152:155], v[164:167], v[122:125]
	v_mfma_f32_16x16x32_f16 v[118:121], v[144:147], v[172:175], v[118:121]
	v_mfma_f32_16x16x32_f16 v[114:117], v[152:155], v[172:175], v[114:117]
	v_mfma_f32_16x16x32_f16 v[110:113], v[144:147], v[180:183], v[110:113]
	v_mfma_f32_16x16x32_f16 v[106:109], v[152:155], v[180:183], v[106:109]
	v_mfma_f32_16x16x32_f16 v[102:105], v[144:147], v[188:191], v[102:105]
	v_mfma_f32_16x16x32_f16 v[98:101], v[152:155], v[188:191], v[98:101]
	s_barrier
	s_add_i32 s48, 0, 0x1c000
	s_add_i32 s44, s66, s62
	v_add_u32_e32 v204, s48, v161
	v_lshl_add_u64 v[212:213], v[212:213], 0, s[92:93]
	s_mov_b32 m0, s44
	ds_read_b128 v[192:195], v204
	ds_read_b128 v[196:199], v204 offset:1024
	ds_read_b128 v[200:203], v204 offset:2048
	ds_read_b128 v[204:207], v204 offset:3072
	global_load_lds_dwordx4 v[212:213], off
	v_lshl_add_u64 v[212:213], v[220:221], 0, s[92:93]
	s_add_i32 m0, s44, 0x2000
	s_nop 0
	global_load_lds_dwordx4 v[212:213], off
	s_barrier
	s_waitcnt lgkmcnt(0)
	s_waitcnt lgkmcnt(0)
	v_mfma_f32_16x16x32_f16 v[94:97], v[192:195], v[156:159], v[94:97]
	v_mfma_f32_16x16x32_f16 v[86:89], v[200:203], v[156:159], v[86:89]
	v_mfma_f32_16x16x32_f16 v[78:81], v[192:195], v[168:171], v[78:81]
	v_mfma_f32_16x16x32_f16 v[70:73], v[200:203], v[168:171], v[70:73]
	v_mfma_f32_16x16x32_f16 v[62:65], v[192:195], v[176:179], v[62:65]
	v_mfma_f32_16x16x32_f16 v[54:57], v[200:203], v[176:179], v[54:57]
	v_mfma_f32_16x16x32_f16 v[46:49], v[192:195], v[184:187], v[46:49]
	v_mfma_f32_16x16x32_f16 v[38:41], v[200:203], v[184:187], v[38:41]
	v_mfma_f32_16x16x32_f16 v[94:97], v[196:199], v[164:167], v[94:97]
	v_mfma_f32_16x16x32_f16 v[86:89], v[204:207], v[164:167], v[86:89]
	v_mfma_f32_16x16x32_f16 v[78:81], v[196:199], v[172:175], v[78:81]
	v_mfma_f32_16x16x32_f16 v[70:73], v[204:207], v[172:175], v[70:73]
	v_mfma_f32_16x16x32_f16 v[62:65], v[196:199], v[180:183], v[62:65]
	v_mfma_f32_16x16x32_f16 v[54:57], v[204:207], v[180:183], v[54:57]
	v_mfma_f32_16x16x32_f16 v[46:49], v[196:199], v[188:191], v[46:49]
	v_mfma_f32_16x16x32_f16 v[38:41], v[204:207], v[188:191], v[38:41]
	s_mov_b32 m0, s71
	v_lshl_add_u64 v[212:213], v[222:223], 0, s[92:93]
	s_barrier
	ds_read_b128 v[156:159], v163 offset:49152
	ds_read_b128 v[164:167], v163 offset:50176
	ds_read_b128 v[168:171], v163 offset:51200
	ds_read_b128 v[172:175], v163 offset:52224
	ds_read_b128 v[176:179], v163 offset:53248
	ds_read_b128 v[180:183], v163 offset:54272
	ds_read_b128 v[184:187], v163 offset:55296
	ds_read_b128 v[188:191], v163 offset:56320
	global_load_lds_dwordx4 v[212:213], off
	v_lshl_add_u64 v[212:213], v[224:225], 0, s[92:93]
	s_mov_b32 m0, s72
	s_nop 0
	global_load_lds_dwordx4 v[212:213], off
	s_barrier
; __device__ __forceinline__ float sigmoidf_(float x) { return 1.0f / (1.0f + __expf(-x)); }
; #define PG8_STAGE(bufoff, gbase, voff) do { _Pragma("unroll") for (int _i = 0; _i < 2; ++_i) \
;         __builtin_amdgcn_global_load_lds((const unsigned*)((const char*)(gbase) + (voff)[_i]), (LAS unsigned*)(lds + (bufoff) + ldsw + _i * 8192), 16, 0, 0); } while (0)
; #define PG8_WAIT_V(n) asm volatile("s_waitcnt vmcnt(" #n ")" ::: "memory")
; #define PG8_WAIT_L(n) asm volatile("s_waitcnt lgkmcnt(" #n ")" ::: "memory")
; template <class Epi, class AMap>
; __device__ __forceinline__ void gemm_phase(LAS unsigned char* lds, const AMap am, const int lda, const h16* Bt, const int ldb, const int M, const int N, const int K, const Epi& E) {
;     ...
;             PG8_BAR; PG8_WAIT_L(0); PG8_MMA(1, 0, At, B0); PG8_BAR; PG8_SCHED;
;             PG8_STAGE(PG8_SB(1, 1), b3 + hstepB, voffB);
;             PG8_WAIT_V(6); PG8_BAR; PG8_MMA(1, 1, At, B1); PG8_BAR;
;     template <int GI>
;     __device__ __forceinline__ void body(const f32x4 (&acc)[2][2][4][2], int row0, int colt) const {
;     ...
;             f32x4 b0 = (f32x4){0.f, 0.f, 0.f, 0.f}, b1 = b0;
;             if (GI == 0) { b0 = *(const f32x4*)(w0 + c); b1 = *(const f32x4*)(w0 + c + 4); }
;             else if (GI == 1) { b0 = *(const f32x4*)(a0 + c); b1 = *(const f32x4*)(a0 + c + 4); }
;             else if (GI == 3) { b0 = *(const f32x4*)(v0 + c); b1 = *(const f32x4*)(v0 + c + 4); }
; #pragma unroll
;             for (int ai = 0; ai < 2; ++ai)
; #pragma unroll
;                 for (int m = 0; m < 4; ++m) {
;                     const size_t row = (size_t)(row0 + ai * 128 + m * 16);
;                     f32x4 x0 = acc[ai][bj][m][0] + b0, x1 = acc[ai][bj][m][1] + b1;
;                     if (GI == 0) {
; #pragma unroll
;                         for (int j = 0; j < 4; ++j) {
;                             x0[j] = 0.6065306597126334f * sigmoidf_(x0[j]); x1[j] = 0.6065306597126334f * sigmoidf_(x1[j]); }
;                         *(u32x4*)(DEC + row * DM + c) = pack8(x0, x1);
;                     } else if (GI == 1) {
; #pragma unroll
;                         for (int j = 0; j < 4; ++j) { x0[j] = sigmoidf_(x0[j]); x1[j] = sigmoidf_(x1[j]); }
;                         *(u32x4*)(Ab + row * DM + c) = pack8(x0, x1);
;                     } else if (GI == 2) {
;                         *(u32x4*)(Gb + row * DM + c) = pack8(x0, x1);
	s_waitcnt lgkmcnt(0)
	s_waitcnt lgkmcnt(0)
	v_mfma_f32_16x16x32_f16 v[90:93], v[140:143], v[156:159], v[90:93]
	v_mfma_f32_16x16x32_f16 v[82:85], v[148:151], v[156:159], v[82:85]
	v_mfma_f32_16x16x32_f16 v[74:77], v[140:143], v[168:171], v[74:77]
	v_mfma_f32_16x16x32_f16 v[66:69], v[148:151], v[168:171], v[66:69]
	v_mfma_f32_16x16x32_f16 v[58:61], v[140:143], v[176:179], v[58:61]
	v_mfma_f32_16x16x32_f16 v[50:53], v[148:151], v[176:179], v[50:53]
	v_mfma_f32_16x16x32_f16 v[42:45], v[140:143], v[184:187], v[42:45]
	v_mfma_f32_16x16x32_f16 v[34:37], v[148:151], v[184:187], v[34:37]
	v_mfma_f32_16x16x32_f16 v[90:93], v[144:147], v[164:167], v[90:93]
	v_mfma_f32_16x16x32_f16 v[82:85], v[152:155], v[164:167], v[82:85]
	v_mfma_f32_16x16x32_f16 v[74:77], v[144:147], v[172:175], v[74:77]
	v_mfma_f32_16x16x32_f16 v[66:69], v[152:155], v[172:175], v[66:69]
	v_mfma_f32_16x16x32_f16 v[58:61], v[144:147], v[180:183], v[58:61]
	v_mfma_f32_16x16x32_f16 v[50:53], v[152:155], v[180:183], v[50:53]
	v_mfma_f32_16x16x32_f16 v[42:45], v[144:147], v[188:191], v[42:45]
	v_mfma_f32_16x16x32_f16 v[34:37], v[152:155], v[188:191], v[34:37]
	s_barrier
	s_add_u32 s44, s46, 0x10080
	s_addc_u32 s45, s47, 0
	s_add_i32 s46, s48, s62
	v_lshl_add_u64 v[140:141], s[44:45], 0, v[0:1]
	s_mov_b32 m0, s46
	s_nop 0
	global_load_lds_dwordx4 v[140:141], off
	v_lshl_add_u64 v[140:141], s[44:45], 0, v[134:135]
	s_add_i32 m0, s46, 0x2000
	s_nop 0
	global_load_lds_dwordx4 v[140:141], off
	s_waitcnt vmcnt(6)
	s_barrier
	v_mfma_f32_16x16x32_f16 v[30:33], v[192:195], v[156:159], v[30:33]
	v_mfma_f32_16x16x32_f16 v[26:29], v[200:203], v[156:159], v[26:29]
	v_mfma_f32_16x16x32_f16 v[22:25], v[192:195], v[168:171], v[22:25]
	v_mfma_f32_16x16x32_f16 v[18:21], v[200:203], v[168:171], v[18:21]
	v_mfma_f32_16x16x32_f16 v[14:17], v[192:195], v[176:179], v[14:17]
	v_mfma_f32_16x16x32_f16 v[10:13], v[200:203], v[176:179], v[10:13]
	v_mfma_f32_16x16x32_f16 v[6:9], v[192:195], v[184:187], v[6:9]
	v_mfma_f32_16x16x32_f16 v[2:5], v[200:203], v[184:187], v[2:5]
	v_mfma_f32_16x16x32_f16 v[30:33], v[196:199], v[164:167], v[30:33]
	v_mfma_f32_16x16x32_f16 v[26:29], v[204:207], v[164:167], v[26:29]
	v_mfma_f32_16x16x32_f16 v[22:25], v[196:199], v[172:175], v[22:25]
	v_mfma_f32_16x16x32_f16 v[18:21], v[204:207], v[172:175], v[18:21]
	v_mfma_f32_16x16x32_f16 v[14:17], v[196:199], v[180:183], v[14:17]
	v_mfma_f32_16x16x32_f16 v[10:13], v[204:207], v[180:183], v[10:13]
	v_mfma_f32_16x16x32_f16 v[6:9], v[196:199], v[188:191], v[6:9]
	v_mfma_f32_16x16x32_f16 v[2:5], v[204:207], v[188:191], v[2:5]
	s_add_u32 s27, s27, 0x100
	s_addc_u32 s29, s29, 0
	s_cmp_ge_i32 s60, s24
	s_mov_b64 s[44:45], s[0:1]
	s_mov_b32 s46, s60
	s_barrier
	s_cbranch_scc0 .LBB0_667
	v_pk_add_f32 v[128:129], v[128:129], 0 op_sel_hi:[1,0]
	v_pk_add_f32 v[126:127], v[126:127], 0 op_sel_hi:[1,0]
	v_pk_add_f32 v[124:125], v[124:125], 0 op_sel_hi:[1,0]
	v_pk_add_f32 v[122:123], v[122:123], 0 op_sel_hi:[1,0]
	v_pk_add_f32 v[120:121], v[120:121], 0 op_sel_hi:[1,0]
	v_pk_add_f32 v[118:119], v[118:119], 0 op_sel_hi:[1,0]
	v_pk_add_f32 v[116:117], v[116:117], 0 op_sel_hi:[1,0]
	v_pk_add_f32 v[114:115], v[114:115], 0 op_sel_hi:[1,0]
	v_pk_add_f32 v[112:113], v[112:113], 0 op_sel_hi:[1,0]
	v_pk_add_f32 v[110:111], v[110:111], 0 op_sel_hi:[1,0]
	v_pk_add_f32 v[108:109], v[108:109], 0 op_sel_hi:[1,0]
	v_pk_add_f32 v[106:107], v[106:107], 0 op_sel_hi:[1,0]
	v_pk_add_f32 v[104:105], v[104:105], 0 op_sel_hi:[1,0]
	v_pk_add_f32 v[102:103], v[102:103], 0 op_sel_hi:[1,0]
	v_pk_add_f32 v[100:101], v[100:101], 0 op_sel_hi:[1,0]
	v_pk_add_f32 v[98:99], v[98:99], 0 op_sel_hi:[1,0]
	v_pk_add_f32 v[92:93], v[92:93], 0 op_sel_hi:[1,0]
	v_pk_add_f32 v[90:91], v[90:91], 0 op_sel_hi:[1,0]
	v_pk_add_f32 v[144:145], v[84:85], 0 op_sel_hi:[1,0]
	v_pk_add_f32 v[152:153], v[82:83], 0 op_sel_hi:[1,0]
	v_pk_add_f32 v[76:77], v[76:77], 0 op_sel_hi:[1,0]
	v_pk_add_f32 v[84:85], v[74:75], 0 op_sel_hi:[1,0]
	v_pk_add_f32 v[146:147], v[68:69], 0 op_sel_hi:[1,0]
	v_pk_add_f32 v[154:155], v[66:67], 0 op_sel_hi:[1,0]
	v_pk_add_f32 v[74:75], v[60:61], 0 op_sel_hi:[1,0]
	v_pk_add_f32 v[140:141], v[58:59], 0 op_sel_hi:[1,0]
	v_pk_add_f32 v[148:149], v[52:53], 0 op_sel_hi:[1,0]
	v_pk_add_f32 v[156:157], v[50:51], 0 op_sel_hi:[1,0]
	v_pk_add_f32 v[82:83], v[44:45], 0 op_sel_hi:[1,0]
	v_pk_add_f32 v[142:143], v[42:43], 0 op_sel_hi:[1,0]
	v_pk_add_f32 v[150:151], v[36:37], 0 op_sel_hi:[1,0]
	v_pk_add_f32 v[158:159], v[34:35], 0 op_sel_hi:[1,0]
	v_pk_add_f32 v[34:35], v[96:97], 0 op_sel_hi:[1,0]
	v_pk_add_f32 v[36:37], v[94:95], 0 op_sel_hi:[1,0]
	v_pk_add_f32 v[50:51], v[88:89], 0 op_sel_hi:[1,0]
	v_pk_add_f32 v[52:53], v[86:87], 0 op_sel_hi:[1,0]
	v_pk_add_f32 v[42:43], v[80:81], 0 op_sel_hi:[1,0]
	v_pk_add_f32 v[44:45], v[78:79], 0 op_sel_hi:[1,0]
	v_pk_add_f32 v[66:67], v[72:73], 0 op_sel_hi:[1,0]
	v_pk_add_f32 v[68:69], v[70:71], 0 op_sel_hi:[1,0]
	v_pk_add_f32 v[58:59], v[64:65], 0 op_sel_hi:[1,0]
	v_pk_add_f32 v[60:61], v[62:63], 0 op_sel_hi:[1,0]
	v_pk_add_f32 v[56:57], v[56:57], 0 op_sel_hi:[1,0]
	v_pk_add_f32 v[54:55], v[54:55], 0 op_sel_hi:[1,0]
	v_pk_add_f32 v[48:49], v[48:49], 0 op_sel_hi:[1,0]
	v_pk_add_f32 v[46:47], v[46:47], 0 op_sel_hi:[1,0]
	v_pk_add_f32 v[40:41], v[40:41], 0 op_sel_hi:[1,0]
	v_pk_add_f32 v[38:39], v[38:39], 0 op_sel_hi:[1,0]
	v_pk_add_f32 v[32:33], v[32:33], 0 op_sel_hi:[1,0]
	v_pk_add_f32 v[30:31], v[30:31], 0 op_sel_hi:[1,0]
	v_pk_add_f32 v[28:29], v[28:29], 0 op_sel_hi:[1,0]
	v_pk_add_f32 v[26:27], v[26:27], 0 op_sel_hi:[1,0]
	v_pk_add_f32 v[24:25], v[24:25], 0 op_sel_hi:[1,0]
	v_pk_add_f32 v[22:23], v[22:23], 0 op_sel_hi:[1,0]
	v_pk_add_f32 v[20:21], v[20:21], 0 op_sel_hi:[1,0]
	v_pk_add_f32 v[18:19], v[18:19], 0 op_sel_hi:[1,0]
	v_pk_add_f32 v[16:17], v[16:17], 0 op_sel_hi:[1,0]
	v_pk_add_f32 v[14:15], v[14:15], 0 op_sel_hi:[1,0]
	v_pk_add_f32 v[12:13], v[12:13], 0 op_sel_hi:[1,0]
	v_pk_add_f32 v[10:11], v[10:11], 0 op_sel_hi:[1,0]
	v_pk_add_f32 v[8:9], v[8:9], 0 op_sel_hi:[1,0]
	v_pk_add_f32 v[6:7], v[6:7], 0 op_sel_hi:[1,0]
	v_pk_add_f32 v[4:5], v[4:5], 0 op_sel_hi:[1,0]
	v_pk_add_f32 v[2:3], v[2:3], 0 op_sel_hi:[1,0]
	s_movk_i32 s66, 0x80
	s_branch .LBB0_656

; #define PG8_STAGE(bufoff, gbase, voff) do { _Pragma("unroll") for (int _i = 0; _i < 2; ++_i) \
;         __builtin_amdgcn_global_load_lds((const unsigned*)((const char*)(gbase) + (voff)[_i]), (LAS unsigned*)(lds + (bufoff) + ldsw + _i * 8192), 16, 0, 0); } while (0)
; #define PG8_LDA(dst, b, h) do { _Pragma("unroll") for (int m = 0; m < 4; ++m) _Pragma("unroll") for (int k = 0; k < 2; ++k) dst[m][k] = *(const LAS h16x8*)(lds + PG8_SA(b, h) + aoff + m * 2048 + k * 1024); } while (0)
; #define PG8_LDB(dst, b, h) do { _Pragma("unroll") for (int n = 0; n < 2; ++n) _Pragma("unroll") for (int k = 0; k < 2; ++k) dst[n][k] = *(const LAS h16x8*)(lds + PG8_SB(b, h) + boff + n * 2048 + k * 1024); } while (0)
; #define PG8_MMA(ai, bj, At, Bt_) do { __builtin_amdgcn_s_setprio(1); _Pragma("unroll") for (int m = 0; m < 4; ++m) _Pragma("unroll") for (int n = 0; n < 2; ++n) _Pragma("unroll") for (int k = 0; k < 2; ++k) \
;         acc[ai][bj][m][n] = __builtin_amdgcn_mfma_f32_16x16x32_f16(Bt_[n][k], At[m][k], acc[ai][bj][m][n], 0, 0, 0); __builtin_amdgcn_s_setprio(0); } while (0)
; #define PG8_WAIT_L(n) asm volatile("s_waitcnt lgkmcnt(" #n ")" ::: "memory")
; #define PG8_BAR __builtin_amdgcn_s_barrier()
; #define PG8_SCHED __builtin_amdgcn_sched_barrier(0)
; template <class Epi, class AMap>
; __device__ __forceinline__ void gemm_phase(LAS unsigned char* lds, const AMap am, const int lda, const h16* Bt, const int ldb, const int M, const int N, const int K, const Epi& E) {
;     ...
;         for (int t = 0; t < nt; t += 2) {
;             const bool last = (t == nt - 2);
;             const char* a1 = cA + (size_t)(t + 1) * kstep;
;             const char* a2 = last ? nA : cA + (size_t)(t + 2) * kstep; const char* b2 = last ? nB : cB + (size_t)(t + 2) * kstep;
;             const char* a3 = a2 + kstep; const char* b3 = b2 + kstep;
;             PG8_LDB(B0, 0, 0); PG8_SCHED; PG8_LDA(At, 0, 0); PG8_STAGE(PG8_SA(1, 1), a1 + hstepA, voffA);
;             PG8_WAIT_L(8); PG8_BAR; PG8_WAIT_L(0); PG8_MMA(0, 0, At, B0); PG8_BAR; PG8_SCHED;
;             PG8_LDB(B1, 0, 1); PG8_STAGE(PG8_SB(0, 0), b2, voffB);
;             PG8_BAR; PG8_WAIT_L(0); PG8_MMA(0, 1, At, B1); PG8_BAR;
;             PG8_LDA(At, 0, 1); PG8_STAGE(PG8_SA(0, 0), a2, voffA);
;             PG8_BAR; PG8_WAIT_L(0); PG8_MMA(1, 0, At, B0); PG8_BAR; PG8_SCHED;
.LBB0_692:
	s_add_i32 s51, s26, 2
	s_add_u32 s0, s22, 0x100
	s_addc_u32 s1, s23, 0
	s_add_i32 s60, 0, 0x10000
	v_add_u32_e32 v142, s60, v175
	ds_read_b128 v[82:85], v142
	ds_read_b128 v[86:89], v142 offset:1024
	ds_read_b128 v[138:141], v142 offset:2048
	ds_read_b128 v[142:145], v142 offset:3072
	s_cmp_eq_u32 s61, s26
	s_cselect_b32 s26, s21, s29
	s_cselect_b32 s49, s47, s1
	s_cselect_b32 s48, s46, s0
	s_cselect_b32 s27, s20, s45
	v_lshl_add_u64 v[172:173], s[22:23], 0, v[152:153]
	s_add_i32 m0, s74, 0xc000
	ds_read_b128 v[156:159], v177
	ds_read_b128 v[160:163], v177 offset:1024
	ds_read_b128 v[164:167], v177 offset:2048
	ds_read_b128 v[168:171], v177 offset:3072
	ds_read_b128 v[178:181], v177 offset:4096
	ds_read_b128 v[182:185], v177 offset:5120
	ds_read_b128 v[186:189], v177 offset:6144
	ds_read_b128 v[190:193], v177 offset:7168
	global_load_lds_dwordx4 v[172:173], off
	v_lshl_add_u64 v[172:173], s[22:23], 0, v[154:155]
	s_add_i32 m0, s74, 0xe000
	s_nop 0
	global_load_lds_dwordx4 v[172:173], off
	s_waitcnt lgkmcnt(8)
	s_barrier
	s_waitcnt lgkmcnt(0)
	s_waitcnt lgkmcnt(0)
	v_mfma_f32_16x16x32_f16 v[134:137], v[82:85], v[156:159], v[134:137]
	v_mfma_f32_16x16x32_f16 v[130:133], v[138:141], v[156:159], v[130:133]
	v_mfma_f32_16x16x32_f16 v[126:129], v[82:85], v[164:167], v[126:129]
	v_mfma_f32_16x16x32_f16 v[122:125], v[138:141], v[164:167], v[122:125]
	v_mfma_f32_16x16x32_f16 v[118:121], v[82:85], v[178:181], v[118:121]
	v_mfma_f32_16x16x32_f16 v[114:117], v[138:141], v[178:181], v[114:117]
	v_mfma_f32_16x16x32_f16 v[110:113], v[82:85], v[186:189], v[110:113]
	v_mfma_f32_16x16x32_f16 v[106:109], v[138:141], v[186:189], v[106:109]
	v_mfma_f32_16x16x32_f16 v[134:137], v[86:89], v[160:163], v[134:137]
	v_mfma_f32_16x16x32_f16 v[130:133], v[142:145], v[160:163], v[130:133]
	v_mfma_f32_16x16x32_f16 v[126:129], v[86:89], v[168:171], v[126:129]
	v_mfma_f32_16x16x32_f16 v[122:125], v[142:145], v[168:171], v[122:125]
	v_mfma_f32_16x16x32_f16 v[118:121], v[86:89], v[182:185], v[118:121]
	v_mfma_f32_16x16x32_f16 v[114:117], v[142:145], v[182:185], v[114:117]
	v_mfma_f32_16x16x32_f16 v[110:113], v[86:89], v[190:193], v[110:113]
	v_mfma_f32_16x16x32_f16 v[106:109], v[142:145], v[190:193], v[106:109]
	s_barrier
	s_add_i32 s62, 0, 0x14000
	v_add_u32_e32 v172, s62, v175
	s_add_i32 s22, s60, s71
	ds_read_b128 v[194:197], v172
	ds_read_b128 v[198:201], v172 offset:1024
	ds_read_b128 v[202:205], v172 offset:2048
	ds_read_b128 v[220:223], v172 offset:3072
	v_lshl_add_u64 v[172:173], s[26:27], 0, v[0:1]
	s_mov_b32 m0, s22
	v_lshl_add_u64 v[206:207], s[26:27], 0, v[150:151]
	global_load_lds_dwordx4 v[172:173], off
	s_add_i32 m0, s22, 0x2000
	s_nop 0
	global_load_lds_dwordx4 v[206:207], off
	s_barrier
	s_waitcnt lgkmcnt(0)
	s_waitcnt lgkmcnt(0)
	v_mfma_f32_16x16x32_f16 v[62:65], v[194:197], v[156:159], v[62:65]
	v_mfma_f32_16x16x32_f16 v[58:61], v[202:205], v[156:159], v[58:61]
	v_mfma_f32_16x16x32_f16 v[54:57], v[194:197], v[164:167], v[54:57]
	v_mfma_f32_16x16x32_f16 v[50:53], v[202:205], v[164:167], v[50:53]
	v_mfma_f32_16x16x32_f16 v[46:49], v[194:197], v[178:181], v[46:49]
	v_mfma_f32_16x16x32_f16 v[42:45], v[202:205], v[178:181], v[42:45]
	v_mfma_f32_16x16x32_f16 v[38:41], v[194:197], v[186:189], v[38:41]
	v_mfma_f32_16x16x32_f16 v[34:37], v[202:205], v[186:189], v[34:37]
	v_mfma_f32_16x16x32_f16 v[62:65], v[198:201], v[160:163], v[62:65]
	v_mfma_f32_16x16x32_f16 v[58:61], v[220:223], v[160:163], v[58:61]
	v_mfma_f32_16x16x32_f16 v[54:57], v[198:201], v[168:171], v[54:57]
	v_mfma_f32_16x16x32_f16 v[50:53], v[220:223], v[168:171], v[50:53]
	v_mfma_f32_16x16x32_f16 v[46:49], v[198:201], v[182:185], v[46:49]
	v_mfma_f32_16x16x32_f16 v[42:45], v[220:223], v[182:185], v[42:45]
	v_mfma_f32_16x16x32_f16 v[38:41], v[198:201], v[190:193], v[38:41]
	v_mfma_f32_16x16x32_f16 v[34:37], v[220:223], v[190:193], v[34:37]
	s_mov_b32 m0, s74
	v_lshl_add_u64 v[212:213], s[48:49], 0, v[146:147]
	s_barrier
	ds_read_b128 v[156:159], v177 offset:16384
	ds_read_b128 v[160:163], v177 offset:17408
	ds_read_b128 v[164:167], v177 offset:18432
	ds_read_b128 v[168:171], v177 offset:19456
	ds_read_b128 v[178:181], v177 offset:20480
	ds_read_b128 v[182:185], v177 offset:21504
	ds_read_b128 v[186:189], v177 offset:22528
	ds_read_b128 v[190:193], v177 offset:23552
	global_load_lds_dwordx4 v[212:213], off
	v_lshl_add_u64 v[224:225], s[48:49], 0, v[148:149]
	s_mov_b32 m0, s75
	s_nop 0
	global_load_lds_dwordx4 v[224:225], off
	s_barrier
	s_waitcnt lgkmcnt(0)
	s_waitcnt lgkmcnt(0)
	v_mfma_f32_16x16x32_f16 v[102:105], v[82:85], v[156:159], v[102:105]
	v_mfma_f32_16x16x32_f16 v[98:101], v[138:141], v[156:159], v[98:101]
	v_mfma_f32_16x16x32_f16 v[94:97], v[82:85], v[164:167], v[94:97]
	v_mfma_f32_16x16x32_f16 v[90:93], v[138:141], v[164:167], v[90:93]
	v_mfma_f32_16x16x32_f16 v[78:81], v[82:85], v[178:181], v[78:81]
	v_mfma_f32_16x16x32_f16 v[74:77], v[138:141], v[178:181], v[74:77]
	v_mfma_f32_16x16x32_f16 v[70:73], v[82:85], v[186:189], v[70:73]
	v_mfma_f32_16x16x32_f16 v[66:69], v[138:141], v[186:189], v[66:69]
	v_mfma_f32_16x16x32_f16 v[102:105], v[86:89], v[160:163], v[102:105]
	v_mfma_f32_16x16x32_f16 v[98:101], v[142:145], v[160:163], v[98:101]
	v_mfma_f32_16x16x32_f16 v[94:97], v[86:89], v[168:171], v[94:97]
	v_mfma_f32_16x16x32_f16 v[90:93], v[142:145], v[168:171], v[90:93]
	v_mfma_f32_16x16x32_f16 v[78:81], v[86:89], v[182:185], v[78:81]
	v_mfma_f32_16x16x32_f16 v[74:77], v[142:145], v[182:185], v[74:77]
	v_mfma_f32_16x16x32_f16 v[70:73], v[86:89], v[190:193], v[70:73]
	v_mfma_f32_16x16x32_f16 v[66:69], v[142:145], v[190:193], v[66:69]
	s_barrier
; #define PG8_STAGE(bufoff, gbase, voff) do { _Pragma("unroll") for (int _i = 0; _i < 2; ++_i) \
;         __builtin_amdgcn_global_load_lds((const unsigned*)((const char*)(gbase) + (voff)[_i]), (LAS unsigned*)(lds + (bufoff) + ldsw + _i * 8192), 16, 0, 0); } while (0)
; #define PG8_LDA(dst, b, h) do { _Pragma("unroll") for (int m = 0; m < 4; ++m) _Pragma("unroll") for (int k = 0; k < 2; ++k) dst[m][k] = *(const LAS h16x8*)(lds + PG8_SA(b, h) + aoff + m * 2048 + k * 1024); } while (0)
; #define PG8_LDB(dst, b, h) do { _Pragma("unroll") for (int n = 0; n < 2; ++n) _Pragma("unroll") for (int k = 0; k < 2; ++k) dst[n][k] = *(const LAS h16x8*)(lds + PG8_SB(b, h) + boff + n * 2048 + k * 1024); } while (0)
; #define PG8_MMA(ai, bj, At, Bt_) do { __builtin_amdgcn_s_setprio(1); _Pragma("unroll") for (int m = 0; m < 4; ++m) _Pragma("unroll") for (int n = 0; n < 2; ++n) _Pragma("unroll") for (int k = 0; k < 2; ++k) \
;         acc[ai][bj][m][n] = __builtin_amdgcn_mfma_f32_16x16x32_f16(Bt_[n][k], At[m][k], acc[ai][bj][m][n], 0, 0, 0); __builtin_amdgcn_s_setprio(0); } while (0)
; #define PG8_WAIT_V(n) asm volatile("s_waitcnt vmcnt(" #n ")" ::: "memory")
; #define PG8_WAIT_L(n) asm volatile("s_waitcnt lgkmcnt(" #n ")" ::: "memory")
; #define PG8_BAR __builtin_amdgcn_s_barrier()
; #define PG8_SCHED __builtin_amdgcn_sched_barrier(0)
; template <class Epi, class AMap>
; __device__ __forceinline__ void gemm_phase(LAS unsigned char* lds, const AMap am, const int lda, const h16* Bt, const int ldb, const int M, const int N, const int K, const Epi& E) {
;     ...
;             PG8_STAGE(PG8_SB(0, 1), b2 + hstepB, voffB);
;             PG8_WAIT_V(6); PG8_BAR; PG8_MMA(1, 1, At, B1); PG8_BAR;
;             PG8_LDB(B0, 1, 0); PG8_SCHED; PG8_LDA(At, 1, 0); PG8_STAGE(PG8_SA(0, 1), a2 + hstepA, voffA);
;             PG8_WAIT_L(8); PG8_BAR; PG8_WAIT_L(0); PG8_MMA(0, 0, At, B0); PG8_BAR; PG8_SCHED;
;             PG8_LDB(B1, 1, 1); PG8_STAGE(PG8_SB(1, 0), b3, voffB);
;             PG8_BAR; PG8_WAIT_L(0); PG8_MMA(0, 1, At, B1); PG8_BAR;
	s_add_u32 s22, s26, 0x10000
	s_addc_u32 s23, s27, 0
	s_add_i32 s60, s62, s71
	v_lshl_add_u64 v[82:83], s[22:23], 0, v[0:1]
	s_mov_b32 m0, s60
	s_nop 0
	global_load_lds_dwordx4 v[82:83], off
	v_lshl_add_u64 v[82:83], s[22:23], 0, v[150:151]
	s_add_i32 m0, s60, 0x2000
	s_nop 0
	global_load_lds_dwordx4 v[82:83], off
	s_waitcnt vmcnt(6)
	s_barrier
	v_mfma_f32_16x16x32_f16 v[30:33], v[194:197], v[156:159], v[30:33]
	v_mfma_f32_16x16x32_f16 v[26:29], v[202:205], v[156:159], v[26:29]
	v_mfma_f32_16x16x32_f16 v[22:25], v[194:197], v[164:167], v[22:25]
	v_mfma_f32_16x16x32_f16 v[18:21], v[202:205], v[164:167], v[18:21]
	v_mfma_f32_16x16x32_f16 v[14:17], v[194:197], v[178:181], v[14:17]
	v_mfma_f32_16x16x32_f16 v[10:13], v[202:205], v[178:181], v[10:13]
	v_mfma_f32_16x16x32_f16 v[6:9], v[194:197], v[186:189], v[6:9]
	v_mfma_f32_16x16x32_f16 v[2:5], v[202:205], v[186:189], v[2:5]
	v_mfma_f32_16x16x32_f16 v[30:33], v[198:201], v[160:163], v[30:33]
	v_mfma_f32_16x16x32_f16 v[26:29], v[220:223], v[160:163], v[26:29]
	v_mfma_f32_16x16x32_f16 v[22:25], v[198:201], v[168:171], v[22:25]
	v_mfma_f32_16x16x32_f16 v[18:21], v[220:223], v[168:171], v[18:21]
	v_mfma_f32_16x16x32_f16 v[14:17], v[198:201], v[182:185], v[14:17]
	v_mfma_f32_16x16x32_f16 v[10:13], v[220:223], v[182:185], v[10:13]
	v_mfma_f32_16x16x32_f16 v[6:9], v[198:201], v[190:193], v[6:9]
	v_mfma_f32_16x16x32_f16 v[2:5], v[220:223], v[190:193], v[2:5]
	s_add_i32 s60, 0, 0x18000
	v_add_u32_e32 v142, s60, v175
	s_barrier
	ds_read_b128 v[82:85], v142
	ds_read_b128 v[86:89], v142 offset:1024
	ds_read_b128 v[138:141], v142 offset:2048
	ds_read_b128 v[142:145], v142 offset:3072
	s_add_u32 s22, s48, 0x1c0000
	s_addc_u32 s23, s49, 0
	s_mov_b32 m0, s76
	v_lshl_add_u64 v[194:195], s[22:23], 0, v[146:147]
	ds_read_b128 v[156:159], v177 offset:32768
	ds_read_b128 v[160:163], v177 offset:33792
	ds_read_b128 v[164:167], v177 offset:34816
	ds_read_b128 v[168:171], v177 offset:35840
	ds_read_b128 v[178:181], v177 offset:36864
	ds_read_b128 v[182:185], v177 offset:37888
	ds_read_b128 v[186:189], v177 offset:38912
	ds_read_b128 v[190:193], v177 offset:39936
	global_load_lds_dwordx4 v[194:195], off
	v_lshl_add_u64 v[194:195], s[22:23], 0, v[148:149]
	s_mov_b32 m0, s77
	s_nop 0
	global_load_lds_dwordx4 v[194:195], off
	s_waitcnt lgkmcnt(8)
	s_barrier
	s_waitcnt lgkmcnt(0)
	s_waitcnt lgkmcnt(0)
	v_mfma_f32_16x16x32_f16 v[134:137], v[82:85], v[156:159], v[134:137]
	v_mfma_f32_16x16x32_f16 v[130:133], v[138:141], v[156:159], v[130:133]
	v_mfma_f32_16x16x32_f16 v[126:129], v[82:85], v[164:167], v[126:129]
	v_mfma_f32_16x16x32_f16 v[122:125], v[138:141], v[164:167], v[122:125]
	v_mfma_f32_16x16x32_f16 v[118:121], v[82:85], v[178:181], v[118:121]
	v_mfma_f32_16x16x32_f16 v[114:117], v[138:141], v[178:181], v[114:117]
	v_mfma_f32_16x16x32_f16 v[110:113], v[82:85], v[186:189], v[110:113]
	v_mfma_f32_16x16x32_f16 v[106:109], v[138:141], v[186:189], v[106:109]
	v_mfma_f32_16x16x32_f16 v[134:137], v[86:89], v[160:163], v[134:137]
	v_mfma_f32_16x16x32_f16 v[130:133], v[142:145], v[160:163], v[130:133]
	v_mfma_f32_16x16x32_f16 v[126:129], v[86:89], v[168:171], v[126:129]
	v_mfma_f32_16x16x32_f16 v[122:125], v[142:145], v[168:171], v[122:125]
	v_mfma_f32_16x16x32_f16 v[118:121], v[86:89], v[182:185], v[118:121]
	v_mfma_f32_16x16x32_f16 v[114:117], v[142:145], v[182:185], v[114:117]
	v_mfma_f32_16x16x32_f16 v[110:113], v[86:89], v[190:193], v[110:113]
	v_mfma_f32_16x16x32_f16 v[106:109], v[142:145], v[190:193], v[106:109]
	s_barrier
	s_add_i32 s48, 0, 0x1c000
	s_add_i32 s22, s60, s71
	v_add_u32_e32 v214, s48, v175
	v_lshl_add_u64 v[172:173], v[172:173], 0, s[92:93]
	s_mov_b32 m0, s22
	ds_read_b128 v[194:197], v214
	ds_read_b128 v[198:201], v214 offset:1024
	ds_read_b128 v[202:205], v214 offset:2048
	ds_read_b128 v[220:223], v214 offset:3072
	global_load_lds_dwordx4 v[172:173], off
	v_lshl_add_u64 v[172:173], v[206:207], 0, s[92:93]
	s_add_i32 m0, s22, 0x2000
	s_nop 0
	global_load_lds_dwordx4 v[172:173], off
	s_barrier
; #define PG8_STAGE(bufoff, gbase, voff) do { _Pragma("unroll") for (int _i = 0; _i < 2; ++_i) \
;         __builtin_amdgcn_global_load_lds((const unsigned*)((const char*)(gbase) + (voff)[_i]), (LAS unsigned*)(lds + (bufoff) + ldsw + _i * 8192), 16, 0, 0); } while (0)
; #define PG8_LDA(dst, b, h) do { _Pragma("unroll") for (int m = 0; m < 4; ++m) _Pragma("unroll") for (int k = 0; k < 2; ++k) dst[m][k] = *(const LAS h16x8*)(lds + PG8_SA(b, h) + aoff + m * 2048 + k * 1024); } while (0)
; #define PG8_MMA(ai, bj, At, Bt_) do { __builtin_amdgcn_s_setprio(1); _Pragma("unroll") for (int m = 0; m < 4; ++m) _Pragma("unroll") for (int n = 0; n < 2; ++n) _Pragma("unroll") for (int k = 0; k < 2; ++k) \
;         acc[ai][bj][m][n] = __builtin_amdgcn_mfma_f32_16x16x32_f16(Bt_[n][k], At[m][k], acc[ai][bj][m][n], 0, 0, 0); __builtin_amdgcn_s_setprio(0); } while (0)
; #define PG8_WAIT_V(n) asm volatile("s_waitcnt vmcnt(" #n ")" ::: "memory")
; #define PG8_WAIT_L(n) asm volatile("s_waitcnt lgkmcnt(" #n ")" ::: "memory")
; #define PG8_BAR __builtin_amdgcn_s_barrier()
; #define PG8_SCHED __builtin_amdgcn_sched_barrier(0)
; template <class Epi, class AMap>
; __device__ __forceinline__ void gemm_phase(LAS unsigned char* lds, const AMap am, const int lda, const h16* Bt, const int ldb, const int M, const int N, const int K, const Epi& E) {
;     ...
;             PG8_BAR; PG8_WAIT_L(0); PG8_MMA(0, 1, At, B1); PG8_BAR;
;             PG8_LDA(At, 1, 1); PG8_STAGE(PG8_SA(1, 0), a3, voffA);
;             PG8_BAR; PG8_WAIT_L(0); PG8_MMA(1, 0, At, B0); PG8_BAR; PG8_SCHED;
;             PG8_STAGE(PG8_SB(1, 1), b3 + hstepB, voffB);
;             PG8_WAIT_V(6); PG8_BAR; PG8_MMA(1, 1, At, B1); PG8_BAR;
	s_waitcnt lgkmcnt(0)
	s_waitcnt lgkmcnt(0)
	v_mfma_f32_16x16x32_f16 v[62:65], v[194:197], v[156:159], v[62:65]
	v_mfma_f32_16x16x32_f16 v[58:61], v[202:205], v[156:159], v[58:61]
	v_mfma_f32_16x16x32_f16 v[54:57], v[194:197], v[164:167], v[54:57]
	v_mfma_f32_16x16x32_f16 v[50:53], v[202:205], v[164:167], v[50:53]
	v_mfma_f32_16x16x32_f16 v[46:49], v[194:197], v[178:181], v[46:49]
	v_mfma_f32_16x16x32_f16 v[42:45], v[202:205], v[178:181], v[42:45]
	v_mfma_f32_16x16x32_f16 v[38:41], v[194:197], v[186:189], v[38:41]
	v_mfma_f32_16x16x32_f16 v[34:37], v[202:205], v[186:189], v[34:37]
	v_mfma_f32_16x16x32_f16 v[62:65], v[198:201], v[160:163], v[62:65]
	v_mfma_f32_16x16x32_f16 v[58:61], v[220:223], v[160:163], v[58:61]
	v_mfma_f32_16x16x32_f16 v[54:57], v[198:201], v[168:171], v[54:57]
	v_mfma_f32_16x16x32_f16 v[50:53], v[220:223], v[168:171], v[50:53]
	v_mfma_f32_16x16x32_f16 v[46:49], v[198:201], v[182:185], v[46:49]
	v_mfma_f32_16x16x32_f16 v[42:45], v[220:223], v[182:185], v[42:45]
	v_mfma_f32_16x16x32_f16 v[38:41], v[198:201], v[190:193], v[38:41]
	v_mfma_f32_16x16x32_f16 v[34:37], v[220:223], v[190:193], v[34:37]
	s_mov_b32 m0, s79
	v_lshl_add_u64 v[172:173], v[212:213], 0, s[92:93]
	s_barrier
	ds_read_b128 v[156:159], v177 offset:49152
	ds_read_b128 v[160:163], v177 offset:50176
	ds_read_b128 v[164:167], v177 offset:51200
	ds_read_b128 v[168:171], v177 offset:52224
	ds_read_b128 v[178:181], v177 offset:53248
	ds_read_b128 v[182:185], v177 offset:54272
	ds_read_b128 v[186:189], v177 offset:55296
	ds_read_b128 v[190:193], v177 offset:56320
	global_load_lds_dwordx4 v[172:173], off
	v_lshl_add_u64 v[172:173], v[224:225], 0, s[92:93]
	s_mov_b32 m0, s80
	s_nop 0
	global_load_lds_dwordx4 v[172:173], off
	s_barrier
	s_waitcnt lgkmcnt(0)
	s_waitcnt lgkmcnt(0)
	v_mfma_f32_16x16x32_f16 v[102:105], v[82:85], v[156:159], v[102:105]
	v_mfma_f32_16x16x32_f16 v[98:101], v[138:141], v[156:159], v[98:101]
	v_mfma_f32_16x16x32_f16 v[94:97], v[82:85], v[164:167], v[94:97]
	v_mfma_f32_16x16x32_f16 v[90:93], v[138:141], v[164:167], v[90:93]
	v_mfma_f32_16x16x32_f16 v[78:81], v[82:85], v[178:181], v[78:81]
	v_mfma_f32_16x16x32_f16 v[74:77], v[138:141], v[178:181], v[74:77]
	v_mfma_f32_16x16x32_f16 v[70:73], v[82:85], v[186:189], v[70:73]
	v_mfma_f32_16x16x32_f16 v[66:69], v[138:141], v[186:189], v[66:69]
	v_mfma_f32_16x16x32_f16 v[102:105], v[86:89], v[160:163], v[102:105]
	v_mfma_f32_16x16x32_f16 v[98:101], v[142:145], v[160:163], v[98:101]
	v_mfma_f32_16x16x32_f16 v[94:97], v[86:89], v[168:171], v[94:97]
	v_mfma_f32_16x16x32_f16 v[90:93], v[142:145], v[168:171], v[90:93]
	v_mfma_f32_16x16x32_f16 v[78:81], v[86:89], v[182:185], v[78:81]
	v_mfma_f32_16x16x32_f16 v[74:77], v[142:145], v[182:185], v[74:77]
	v_mfma_f32_16x16x32_f16 v[70:73], v[86:89], v[190:193], v[70:73]
	v_mfma_f32_16x16x32_f16 v[66:69], v[142:145], v[190:193], v[66:69]
	s_barrier
	s_add_u32 s22, s26, 0x10080
	s_addc_u32 s23, s27, 0
	s_add_i32 s26, s48, s71
	v_lshl_add_u64 v[82:83], s[22:23], 0, v[0:1]
	s_mov_b32 m0, s26
	s_nop 0
	global_load_lds_dwordx4 v[82:83], off
	v_lshl_add_u64 v[82:83], s[22:23], 0, v[150:151]
	s_add_i32 m0, s26, 0x2000
	s_nop 0
	global_load_lds_dwordx4 v[82:83], off
	s_waitcnt vmcnt(6)
	s_barrier
	v_mfma_f32_16x16x32_f16 v[30:33], v[194:197], v[156:159], v[30:33]
	v_mfma_f32_16x16x32_f16 v[26:29], v[202:205], v[156:159], v[26:29]
	v_mfma_f32_16x16x32_f16 v[22:25], v[194:197], v[164:167], v[22:25]
	v_mfma_f32_16x16x32_f16 v[18:21], v[202:205], v[164:167], v[18:21]
	v_mfma_f32_16x16x32_f16 v[14:17], v[194:197], v[178:181], v[14:17]
	v_mfma_f32_16x16x32_f16 v[10:13], v[202:205], v[178:181], v[10:13]
	v_mfma_f32_16x16x32_f16 v[6:9], v[194:197], v[186:189], v[6:9]
	v_mfma_f32_16x16x32_f16 v[2:5], v[202:205], v[186:189], v[2:5]
	v_mfma_f32_16x16x32_f16 v[30:33], v[198:201], v[160:163], v[30:33]
	v_mfma_f32_16x16x32_f16 v[26:29], v[220:223], v[160:163], v[26:29]
	v_mfma_f32_16x16x32_f16 v[22:25], v[198:201], v[168:171], v[22:25]
	v_mfma_f32_16x16x32_f16 v[18:21], v[220:223], v[168:171], v[18:21]
	v_mfma_f32_16x16x32_f16 v[14:17], v[198:201], v[182:185], v[14:17]
	v_mfma_f32_16x16x32_f16 v[10:13], v[220:223], v[182:185], v[10:13]
	v_mfma_f32_16x16x32_f16 v[6:9], v[198:201], v[190:193], v[6:9]
	v_mfma_f32_16x16x32_f16 v[2:5], v[220:223], v[190:193], v[2:5]
	s_add_u32 s29, s29, 0x100
	s_addc_u32 s45, s45, 0
	s_cmp_ge_i32 s51, s24
	s_mov_b64 s[22:23], s[0:1]
	s_mov_b32 s26, s51
	s_barrier
	s_cbranch_scc0 .LBB0_692
	s_branch .LBB0_681

; #define PG8_STAGE(bufoff, gbase, voff) do { _Pragma("unroll") for (int _i = 0; _i < 2; ++_i) \
;         __builtin_amdgcn_global_load_lds((const unsigned*)((const char*)(gbase) + (voff)[_i]), (LAS unsigned*)(lds + (bufoff) + ldsw + _i * 8192), 16, 0, 0); } while (0)
; #define PG8_LDA(dst, b, h) do { _Pragma("unroll") for (int m = 0; m < 4; ++m) _Pragma("unroll") for (int k = 0; k < 2; ++k) dst[m][k] = *(const LAS h16x8*)(lds + PG8_SA(b, h) + aoff + m * 2048 + k * 1024); } while (0)
; #define PG8_LDB(dst, b, h) do { _Pragma("unroll") for (int n = 0; n < 2; ++n) _Pragma("unroll") for (int k = 0; k < 2; ++k) dst[n][k] = *(const LAS h16x8*)(lds + PG8_SB(b, h) + boff + n * 2048 + k * 1024); } while (0)
; #define PG8_MMA(ai, bj, At, Bt_) do { __builtin_amdgcn_s_setprio(1); _Pragma("unroll") for (int m = 0; m < 4; ++m) _Pragma("unroll") for (int n = 0; n < 2; ++n) _Pragma("unroll") for (int k = 0; k < 2; ++k) \
;         acc[ai][bj][m][n] = __builtin_amdgcn_mfma_f32_16x16x32_f16(Bt_[n][k], At[m][k], acc[ai][bj][m][n], 0, 0, 0); __builtin_amdgcn_s_setprio(0); } while (0)
; #define PG8_WAIT_L(n) asm volatile("s_waitcnt lgkmcnt(" #n ")" ::: "memory")
; #define PG8_BAR __builtin_amdgcn_s_barrier()
; #define PG8_SCHED __builtin_amdgcn_sched_barrier(0)
; template <class Epi, class AMap>
; __device__ __forceinline__ void gemm_phase(LAS unsigned char* lds, const AMap am, const int lda, const h16* Bt, const int ldb, const int M, const int N, const int K, const Epi& E) {
;     ...
;         for (int t = 0; t < nt; t += 2) {
;             const bool last = (t == nt - 2);
;             const char* a1 = cA + (size_t)(t + 1) * kstep;
;             const char* a2 = last ? nA : cA + (size_t)(t + 2) * kstep; const char* b2 = last ? nB : cB + (size_t)(t + 2) * kstep;
;             const char* a3 = a2 + kstep; const char* b3 = b2 + kstep;
;             PG8_LDB(B0, 0, 0); PG8_SCHED; PG8_LDA(At, 0, 0); PG8_STAGE(PG8_SA(1, 1), a1 + hstepA, voffA);
;             PG8_WAIT_L(8); PG8_BAR; PG8_WAIT_L(0); PG8_MMA(0, 0, At, B0); PG8_BAR; PG8_SCHED;
;             PG8_LDB(B1, 0, 1); PG8_STAGE(PG8_SB(0, 0), b2, voffB);
;             PG8_BAR; PG8_WAIT_L(0); PG8_MMA(0, 1, At, B1); PG8_BAR;
;             PG8_LDA(At, 0, 1); PG8_STAGE(PG8_SA(0, 0), a2, voffA);
;             PG8_BAR; PG8_WAIT_L(0); PG8_MMA(1, 0, At, B0); PG8_BAR; PG8_SCHED;
.LBB0_799:
	s_add_u32 s40, s0, 0xfff80080
	s_addc_u32 s41, s1, -1
	s_add_i32 s45, 0, 0x10000
	v_add_u32_e32 v152, s45, v155
	ds_read_b128 v[130:133], v152
	ds_read_b128 v[134:137], v152 offset:1024
	ds_read_b128 v[148:151], v152 offset:2048
	ds_read_b128 v[158:161], v152 offset:3072
	s_cmp_eq_u32 s43, 28
	s_cselect_b32 s49, s47, s41
	s_cselect_b32 s48, s46, s40
	s_cselect_b32 s41, s29, s35
	s_cselect_b32 s40, s20, s21
	v_lshl_add_u64 v[152:153], s[0:1], 0, v[144:145]
	s_add_i32 m0, s23, 0xc000
	ds_read_b128 v[162:165], v157
	ds_read_b128 v[166:169], v157 offset:1024
	ds_read_b128 v[170:173], v157 offset:2048
	ds_read_b128 v[174:177], v157 offset:3072
	ds_read_b128 v[178:181], v157 offset:4096
	ds_read_b128 v[182:185], v157 offset:5120
	ds_read_b128 v[186:189], v157 offset:6144
	ds_read_b128 v[190:193], v157 offset:7168
	global_load_lds_dwordx4 v[152:153], off
	v_lshl_add_u64 v[152:153], s[0:1], 0, v[146:147]
	s_add_i32 m0, s23, 0xe000
	s_nop 0
	global_load_lds_dwordx4 v[152:153], off
	s_waitcnt lgkmcnt(8)
	s_barrier
	s_waitcnt lgkmcnt(0)
	s_waitcnt lgkmcnt(0)
	v_mfma_f32_16x16x32_f16 v[126:129], v[130:133], v[162:165], v[126:129]
	v_mfma_f32_16x16x32_f16 v[122:125], v[148:151], v[162:165], v[122:125]
	v_mfma_f32_16x16x32_f16 v[110:113], v[130:133], v[170:173], v[110:113]
	v_mfma_f32_16x16x32_f16 v[106:109], v[148:151], v[170:173], v[106:109]
	v_mfma_f32_16x16x32_f16 v[94:97], v[130:133], v[178:181], v[94:97]
	v_mfma_f32_16x16x32_f16 v[90:93], v[148:151], v[178:181], v[90:93]
	v_mfma_f32_16x16x32_f16 v[78:81], v[130:133], v[186:189], v[78:81]
	v_mfma_f32_16x16x32_f16 v[74:77], v[148:151], v[186:189], v[74:77]
	v_mfma_f32_16x16x32_f16 v[126:129], v[134:137], v[166:169], v[126:129]
	v_mfma_f32_16x16x32_f16 v[122:125], v[158:161], v[166:169], v[122:125]
	v_mfma_f32_16x16x32_f16 v[110:113], v[134:137], v[174:177], v[110:113]
	v_mfma_f32_16x16x32_f16 v[106:109], v[158:161], v[174:177], v[106:109]
	v_mfma_f32_16x16x32_f16 v[94:97], v[134:137], v[182:185], v[94:97]
	v_mfma_f32_16x16x32_f16 v[90:93], v[158:161], v[182:185], v[90:93]
	v_mfma_f32_16x16x32_f16 v[78:81], v[134:137], v[190:193], v[78:81]
	v_mfma_f32_16x16x32_f16 v[74:77], v[158:161], v[190:193], v[74:77]
	s_barrier
	s_add_i32 s60, 0, 0x14000
	v_add_u32_e32 v152, s60, v155
	s_add_i32 s45, s45, s72
	ds_read_b128 v[194:197], v152
	ds_read_b128 v[198:201], v152 offset:1024
	ds_read_b128 v[202:205], v152 offset:2048
	ds_read_b128 v[220:223], v152 offset:3072
	v_lshl_add_u64 v[152:153], s[40:41], 0, v[0:1]
	s_mov_b32 m0, s45
	v_lshl_add_u64 v[206:207], s[40:41], 0, v[142:143]
	global_load_lds_dwordx4 v[152:153], off
	s_add_i32 m0, s45, 0x2000
	s_nop 0
	global_load_lds_dwordx4 v[206:207], off
	s_barrier
	s_waitcnt lgkmcnt(0)
	s_waitcnt lgkmcnt(0)
	v_mfma_f32_16x16x32_f16 v[118:121], v[194:197], v[162:165], v[118:121]
	v_mfma_f32_16x16x32_f16 v[114:117], v[202:205], v[162:165], v[114:117]
	v_mfma_f32_16x16x32_f16 v[102:105], v[194:197], v[170:173], v[102:105]
	v_mfma_f32_16x16x32_f16 v[98:101], v[202:205], v[170:173], v[98:101]
	v_mfma_f32_16x16x32_f16 v[86:89], v[194:197], v[178:181], v[86:89]
	v_mfma_f32_16x16x32_f16 v[82:85], v[202:205], v[178:181], v[82:85]
	v_mfma_f32_16x16x32_f16 v[70:73], v[194:197], v[186:189], v[70:73]
	v_mfma_f32_16x16x32_f16 v[66:69], v[202:205], v[186:189], v[66:69]
	v_mfma_f32_16x16x32_f16 v[118:121], v[198:201], v[166:169], v[118:121]
	v_mfma_f32_16x16x32_f16 v[114:117], v[220:223], v[166:169], v[114:117]
	v_mfma_f32_16x16x32_f16 v[102:105], v[198:201], v[174:177], v[102:105]
	v_mfma_f32_16x16x32_f16 v[98:101], v[220:223], v[174:177], v[98:101]
	v_mfma_f32_16x16x32_f16 v[86:89], v[198:201], v[182:185], v[86:89]
	v_mfma_f32_16x16x32_f16 v[82:85], v[220:223], v[182:185], v[82:85]
	v_mfma_f32_16x16x32_f16 v[70:73], v[198:201], v[190:193], v[70:73]
	v_mfma_f32_16x16x32_f16 v[66:69], v[220:223], v[190:193], v[66:69]
	s_mov_b32 m0, s23
	v_lshl_add_u64 v[212:213], s[48:49], 0, v[138:139]
	s_barrier
	ds_read_b128 v[162:165], v157 offset:16384
	ds_read_b128 v[166:169], v157 offset:17408
	ds_read_b128 v[170:173], v157 offset:18432
	ds_read_b128 v[174:177], v157 offset:19456
	ds_read_b128 v[178:181], v157 offset:20480
	ds_read_b128 v[182:185], v157 offset:21504
	ds_read_b128 v[186:189], v157 offset:22528
	ds_read_b128 v[190:193], v157 offset:23552
	global_load_lds_dwordx4 v[212:213], off
	v_lshl_add_u64 v[224:225], s[48:49], 0, v[140:141]
	s_mov_b32 m0, s27
	s_nop 0
	global_load_lds_dwordx4 v[224:225], off
	s_barrier
	s_waitcnt lgkmcnt(0)
	s_waitcnt lgkmcnt(0)
	v_mfma_f32_16x16x32_f16 v[62:65], v[130:133], v[162:165], v[62:65]
	v_mfma_f32_16x16x32_f16 v[58:61], v[148:151], v[162:165], v[58:61]
	v_mfma_f32_16x16x32_f16 v[46:49], v[130:133], v[170:173], v[46:49]
	v_mfma_f32_16x16x32_f16 v[42:45], v[148:151], v[170:173], v[42:45]
	v_mfma_f32_16x16x32_f16 v[30:33], v[130:133], v[178:181], v[30:33]
	v_mfma_f32_16x16x32_f16 v[26:29], v[148:151], v[178:181], v[26:29]
	v_mfma_f32_16x16x32_f16 v[14:17], v[130:133], v[186:189], v[14:17]
	v_mfma_f32_16x16x32_f16 v[10:13], v[148:151], v[186:189], v[10:13]
	v_mfma_f32_16x16x32_f16 v[62:65], v[134:137], v[166:169], v[62:65]
	v_mfma_f32_16x16x32_f16 v[58:61], v[158:161], v[166:169], v[58:61]
	v_mfma_f32_16x16x32_f16 v[46:49], v[134:137], v[174:177], v[46:49]
	v_mfma_f32_16x16x32_f16 v[42:45], v[158:161], v[174:177], v[42:45]
	v_mfma_f32_16x16x32_f16 v[30:33], v[134:137], v[182:185], v[30:33]
	v_mfma_f32_16x16x32_f16 v[26:29], v[158:161], v[182:185], v[26:29]
	v_mfma_f32_16x16x32_f16 v[14:17], v[134:137], v[190:193], v[14:17]
	v_mfma_f32_16x16x32_f16 v[10:13], v[158:161], v[190:193], v[10:13]
	s_barrier
; #define PG8_STAGE(bufoff, gbase, voff) do { _Pragma("unroll") for (int _i = 0; _i < 2; ++_i) \
;         __builtin_amdgcn_global_load_lds((const unsigned*)((const char*)(gbase) + (voff)[_i]), (LAS unsigned*)(lds + (bufoff) + ldsw + _i * 8192), 16, 0, 0); } while (0)
; #define PG8_LDA(dst, b, h) do { _Pragma("unroll") for (int m = 0; m < 4; ++m) _Pragma("unroll") for (int k = 0; k < 2; ++k) dst[m][k] = *(const LAS h16x8*)(lds + PG8_SA(b, h) + aoff + m * 2048 + k * 1024); } while (0)
; #define PG8_LDB(dst, b, h) do { _Pragma("unroll") for (int n = 0; n < 2; ++n) _Pragma("unroll") for (int k = 0; k < 2; ++k) dst[n][k] = *(const LAS h16x8*)(lds + PG8_SB(b, h) + boff + n * 2048 + k * 1024); } while (0)
; #define PG8_MMA(ai, bj, At, Bt_) do { __builtin_amdgcn_s_setprio(1); _Pragma("unroll") for (int m = 0; m < 4; ++m) _Pragma("unroll") for (int n = 0; n < 2; ++n) _Pragma("unroll") for (int k = 0; k < 2; ++k) \
;         acc[ai][bj][m][n] = __builtin_amdgcn_mfma_f32_16x16x32_f16(Bt_[n][k], At[m][k], acc[ai][bj][m][n], 0, 0, 0); __builtin_amdgcn_s_setprio(0); } while (0)
; #define PG8_WAIT_V(n) asm volatile("s_waitcnt vmcnt(" #n ")" ::: "memory")
; #define PG8_WAIT_L(n) asm volatile("s_waitcnt lgkmcnt(" #n ")" ::: "memory")
; #define PG8_BAR __builtin_amdgcn_s_barrier()
; #define PG8_SCHED __builtin_amdgcn_sched_barrier(0)
; template <class Epi, class AMap>
; __device__ __forceinline__ void gemm_phase(LAS unsigned char* lds, const AMap am, const int lda, const h16* Bt, const int ldb, const int M, const int N, const int K, const Epi& E) {
;     ...
;             PG8_STAGE(PG8_SB(0, 1), b2 + hstepB, voffB);
;             PG8_WAIT_V(6); PG8_BAR; PG8_MMA(1, 1, At, B1); PG8_BAR;
;             PG8_LDB(B0, 1, 0); PG8_SCHED; PG8_LDA(At, 1, 0); PG8_STAGE(PG8_SA(0, 1), a2 + hstepA, voffA);
;             PG8_WAIT_L(8); PG8_BAR; PG8_WAIT_L(0); PG8_MMA(0, 0, At, B0); PG8_BAR; PG8_SCHED;
;             PG8_LDB(B1, 1, 1); PG8_STAGE(PG8_SB(1, 0), b3, voffB);
;             PG8_BAR; PG8_WAIT_L(0); PG8_MMA(0, 1, At, B1); PG8_BAR;
;             PG8_LDA(At, 1, 1); PG8_STAGE(PG8_SA(1, 0), a3, voffA);
;             PG8_BAR; PG8_WAIT_L(0); PG8_MMA(1, 0, At, B0); PG8_BAR; PG8_SCHED;
	s_add_u32 s50, s40, 0x80000
	s_addc_u32 s51, s41, 0
	s_add_i32 s45, s60, s72
	v_lshl_add_u64 v[130:131], s[50:51], 0, v[0:1]
	s_mov_b32 m0, s45
	s_nop 0
	global_load_lds_dwordx4 v[130:131], off
	v_lshl_add_u64 v[130:131], s[50:51], 0, v[142:143]
	s_add_i32 m0, s45, 0x2000
	s_nop 0
	global_load_lds_dwordx4 v[130:131], off
	s_waitcnt vmcnt(6)
	s_barrier
	v_mfma_f32_16x16x32_f16 v[54:57], v[194:197], v[162:165], v[54:57]
	v_mfma_f32_16x16x32_f16 v[50:53], v[202:205], v[162:165], v[50:53]
	v_mfma_f32_16x16x32_f16 v[38:41], v[194:197], v[170:173], v[38:41]
	v_mfma_f32_16x16x32_f16 v[34:37], v[202:205], v[170:173], v[34:37]
	v_mfma_f32_16x16x32_f16 v[22:25], v[194:197], v[178:181], v[22:25]
	v_mfma_f32_16x16x32_f16 v[18:21], v[202:205], v[178:181], v[18:21]
	v_mfma_f32_16x16x32_f16 v[6:9], v[194:197], v[186:189], v[6:9]
	v_mfma_f32_16x16x32_f16 v[2:5], v[202:205], v[186:189], v[2:5]
	v_mfma_f32_16x16x32_f16 v[54:57], v[198:201], v[166:169], v[54:57]
	v_mfma_f32_16x16x32_f16 v[50:53], v[220:223], v[166:169], v[50:53]
	v_mfma_f32_16x16x32_f16 v[38:41], v[198:201], v[174:177], v[38:41]
	v_mfma_f32_16x16x32_f16 v[34:37], v[220:223], v[174:177], v[34:37]
	v_mfma_f32_16x16x32_f16 v[22:25], v[198:201], v[182:185], v[22:25]
	v_mfma_f32_16x16x32_f16 v[18:21], v[220:223], v[182:185], v[18:21]
	v_mfma_f32_16x16x32_f16 v[6:9], v[198:201], v[190:193], v[6:9]
	v_mfma_f32_16x16x32_f16 v[2:5], v[220:223], v[190:193], v[2:5]
	s_add_i32 s45, 0, 0x18000
	v_add_u32_e32 v158, s45, v155
	s_barrier
	ds_read_b128 v[130:133], v158
	ds_read_b128 v[134:137], v158 offset:1024
	ds_read_b128 v[148:151], v158 offset:2048
	ds_read_b128 v[158:161], v158 offset:3072
	s_add_u32 s48, s48, 0x80000
	s_addc_u32 s49, s49, 0
	s_mov_b32 m0, s73
	v_lshl_add_u64 v[194:195], s[48:49], 0, v[138:139]
	ds_read_b128 v[162:165], v157 offset:32768
	ds_read_b128 v[166:169], v157 offset:33792
	ds_read_b128 v[170:173], v157 offset:34816
	ds_read_b128 v[174:177], v157 offset:35840
	ds_read_b128 v[178:181], v157 offset:36864
	ds_read_b128 v[182:185], v157 offset:37888
	ds_read_b128 v[186:189], v157 offset:38912
	ds_read_b128 v[190:193], v157 offset:39936
	global_load_lds_dwordx4 v[194:195], off
	v_lshl_add_u64 v[194:195], s[48:49], 0, v[140:141]
	s_mov_b32 m0, s74
	s_nop 0
	global_load_lds_dwordx4 v[194:195], off
	s_waitcnt lgkmcnt(8)
	s_barrier
	s_waitcnt lgkmcnt(0)
	s_waitcnt lgkmcnt(0)
	v_mfma_f32_16x16x32_f16 v[126:129], v[130:133], v[162:165], v[126:129]
	v_mfma_f32_16x16x32_f16 v[122:125], v[148:151], v[162:165], v[122:125]
	v_mfma_f32_16x16x32_f16 v[110:113], v[130:133], v[170:173], v[110:113]
	v_mfma_f32_16x16x32_f16 v[106:109], v[148:151], v[170:173], v[106:109]
	v_mfma_f32_16x16x32_f16 v[94:97], v[130:133], v[178:181], v[94:97]
	v_mfma_f32_16x16x32_f16 v[90:93], v[148:151], v[178:181], v[90:93]
	v_mfma_f32_16x16x32_f16 v[78:81], v[130:133], v[186:189], v[78:81]
	v_mfma_f32_16x16x32_f16 v[74:77], v[148:151], v[186:189], v[74:77]
	v_mfma_f32_16x16x32_f16 v[126:129], v[134:137], v[166:169], v[126:129]
	v_mfma_f32_16x16x32_f16 v[122:125], v[158:161], v[166:169], v[122:125]
	v_mfma_f32_16x16x32_f16 v[110:113], v[134:137], v[174:177], v[110:113]
	v_mfma_f32_16x16x32_f16 v[106:109], v[158:161], v[174:177], v[106:109]
	v_mfma_f32_16x16x32_f16 v[94:97], v[134:137], v[182:185], v[94:97]
	v_mfma_f32_16x16x32_f16 v[90:93], v[158:161], v[182:185], v[90:93]
	v_mfma_f32_16x16x32_f16 v[78:81], v[134:137], v[190:193], v[78:81]
	v_mfma_f32_16x16x32_f16 v[74:77], v[158:161], v[190:193], v[74:77]
	s_barrier
	s_add_i32 s48, 0, 0x1c000
	s_add_i32 s45, s45, s72
	v_add_u32_e32 v214, s48, v155
	v_lshl_add_u64 v[152:153], v[152:153], 0, s[92:93]
	s_mov_b32 m0, s45
	ds_read_b128 v[194:197], v214
	ds_read_b128 v[198:201], v214 offset:1024
	ds_read_b128 v[202:205], v214 offset:2048
	ds_read_b128 v[220:223], v214 offset:3072
	global_load_lds_dwordx4 v[152:153], off
	v_lshl_add_u64 v[152:153], v[206:207], 0, s[92:93]
	s_add_i32 m0, s45, 0x2000
	s_nop 0
	global_load_lds_dwordx4 v[152:153], off
	s_barrier
	s_waitcnt lgkmcnt(0)
	s_waitcnt lgkmcnt(0)
	v_mfma_f32_16x16x32_f16 v[118:121], v[194:197], v[162:165], v[118:121]
	v_mfma_f32_16x16x32_f16 v[114:117], v[202:205], v[162:165], v[114:117]
	v_mfma_f32_16x16x32_f16 v[102:105], v[194:197], v[170:173], v[102:105]
	v_mfma_f32_16x16x32_f16 v[98:101], v[202:205], v[170:173], v[98:101]
	v_mfma_f32_16x16x32_f16 v[86:89], v[194:197], v[178:181], v[86:89]
	v_mfma_f32_16x16x32_f16 v[82:85], v[202:205], v[178:181], v[82:85]
	v_mfma_f32_16x16x32_f16 v[70:73], v[194:197], v[186:189], v[70:73]
	v_mfma_f32_16x16x32_f16 v[66:69], v[202:205], v[186:189], v[66:69]
	v_mfma_f32_16x16x32_f16 v[118:121], v[198:201], v[166:169], v[118:121]
	v_mfma_f32_16x16x32_f16 v[114:117], v[220:223], v[166:169], v[114:117]
	v_mfma_f32_16x16x32_f16 v[102:105], v[198:201], v[174:177], v[102:105]
	v_mfma_f32_16x16x32_f16 v[98:101], v[220:223], v[174:177], v[98:101]
	v_mfma_f32_16x16x32_f16 v[86:89], v[198:201], v[182:185], v[86:89]
	v_mfma_f32_16x16x32_f16 v[82:85], v[220:223], v[182:185], v[82:85]
	v_mfma_f32_16x16x32_f16 v[70:73], v[198:201], v[190:193], v[70:73]
	v_mfma_f32_16x16x32_f16 v[66:69], v[220:223], v[190:193], v[66:69]
	s_mov_b32 m0, s75
	v_lshl_add_u64 v[152:153], v[212:213], 0, s[92:93]
	s_barrier
	ds_read_b128 v[162:165], v157 offset:49152
	ds_read_b128 v[166:169], v157 offset:50176
	ds_read_b128 v[170:173], v157 offset:51200
	ds_read_b128 v[174:177], v157 offset:52224
	ds_read_b128 v[178:181], v157 offset:53248
	ds_read_b128 v[182:185], v157 offset:54272
	ds_read_b128 v[186:189], v157 offset:55296
	ds_read_b128 v[190:193], v157 offset:56320
	global_load_lds_dwordx4 v[152:153], off
	v_lshl_add_u64 v[152:153], v[224:225], 0, s[92:93]
	s_mov_b32 m0, s76
	s_nop 0
	global_load_lds_dwordx4 v[152:153], off
	s_barrier
; __device__ __forceinline__ float sigmoidf_(float x) { return 1.0f / (1.0f + __expf(-x)); }
; #define PG8_STAGE(bufoff, gbase, voff) do { _Pragma("unroll") for (int _i = 0; _i < 2; ++_i) \
;         __builtin_amdgcn_global_load_lds((const unsigned*)((const char*)(gbase) + (voff)[_i]), (LAS unsigned*)(lds + (bufoff) + ldsw + _i * 8192), 16, 0, 0); } while (0)
; #define PG8_MMA(ai, bj, At, Bt_) do { __builtin_amdgcn_s_setprio(1); _Pragma("unroll") for (int m = 0; m < 4; ++m) _Pragma("unroll") for (int n = 0; n < 2; ++n) _Pragma("unroll") for (int k = 0; k < 2; ++k) \
;         acc[ai][bj][m][n] = __builtin_amdgcn_mfma_f32_16x16x32_f16(Bt_[n][k], At[m][k], acc[ai][bj][m][n], 0, 0, 0); __builtin_amdgcn_s_setprio(0); } while (0)
; #define PG8_WAIT_V(n) asm volatile("s_waitcnt vmcnt(" #n ")" ::: "memory")
; #define PG8_WAIT_L(n) asm volatile("s_waitcnt lgkmcnt(" #n ")" ::: "memory")
; #define PG8_BAR __builtin_amdgcn_s_barrier()
; #define PG8_SCHED __builtin_amdgcn_sched_barrier(0)
; template <class Epi, class AMap>
; __device__ __forceinline__ void gemm_phase(LAS unsigned char* lds, const AMap am, const int lda, const h16* Bt, const int ldb, const int M, const int N, const int K, const Epi& E) {
;     ...
;             PG8_BAR; PG8_WAIT_L(0); PG8_MMA(1, 0, At, B0); PG8_BAR; PG8_SCHED;
;             PG8_STAGE(PG8_SB(1, 1), b3 + hstepB, voffB);
;             PG8_WAIT_V(6); PG8_BAR; PG8_MMA(1, 1, At, B1); PG8_BAR;
;     __device__ __forceinline__ void operator()(const f32x4 (&acc)[2][2][4][2], const Unit& u, int wr, int wc, int fr, int fq) const {
;     ...
;         const int mode = u.pn == 24 ? 1 : (u.pn == 26 ? 2 : 0);
;         const bool vtile = VFw != nullptr && u.pn >= 16 && u.pn < 24;
; #pragma unroll
;         for (int ai = 0; ai < 2; ++ai)
; #pragma unroll
;             for (int m = 0; m < 4; ++m) { h16* rowp = O + (size_t)(row0 + ai * 128 + m * 16) * LDC1 + colt;
; #pragma unroll
;                 for (int bj = 0; bj < 2; ++bj) { f32x4 v0 = acc[ai][bj][m][0], v1 = acc[ai][bj][m][1];
;                     if (mode == 1) {
; #pragma unroll
;                         for (int j = 0; j < 4; ++j) { v0[j] = 1.0f - 2.0f / (1.0f + __expf(2.0f * v0[j])); v1[j] = 1.0f - 2.0f / (1.0f + __expf(2.0f * v1[j])); } }
;                     else if (mode == 2) {
; #pragma unroll
;                         for (int j = 0; j < 4; ++j) { v0[j] = sigmoidf_(v0[j]); v1[j] = sigmoidf_(v1[j]); } }
	s_waitcnt lgkmcnt(0)
	s_waitcnt lgkmcnt(0)
	v_mfma_f32_16x16x32_f16 v[62:65], v[130:133], v[162:165], v[62:65]
	v_mfma_f32_16x16x32_f16 v[58:61], v[148:151], v[162:165], v[58:61]
	v_mfma_f32_16x16x32_f16 v[46:49], v[130:133], v[170:173], v[46:49]
	v_mfma_f32_16x16x32_f16 v[42:45], v[148:151], v[170:173], v[42:45]
	v_mfma_f32_16x16x32_f16 v[30:33], v[130:133], v[178:181], v[30:33]
	v_mfma_f32_16x16x32_f16 v[26:29], v[148:151], v[178:181], v[26:29]
	v_mfma_f32_16x16x32_f16 v[14:17], v[130:133], v[186:189], v[14:17]
	v_mfma_f32_16x16x32_f16 v[10:13], v[148:151], v[186:189], v[10:13]
	v_mfma_f32_16x16x32_f16 v[62:65], v[134:137], v[166:169], v[62:65]
	v_mfma_f32_16x16x32_f16 v[58:61], v[158:161], v[166:169], v[58:61]
	v_mfma_f32_16x16x32_f16 v[46:49], v[134:137], v[174:177], v[46:49]
	v_mfma_f32_16x16x32_f16 v[42:45], v[158:161], v[174:177], v[42:45]
	v_mfma_f32_16x16x32_f16 v[30:33], v[134:137], v[182:185], v[30:33]
	v_mfma_f32_16x16x32_f16 v[26:29], v[158:161], v[182:185], v[26:29]
	v_mfma_f32_16x16x32_f16 v[14:17], v[134:137], v[190:193], v[14:17]
	v_mfma_f32_16x16x32_f16 v[10:13], v[158:161], v[190:193], v[10:13]
	s_barrier
	s_add_u32 s40, s40, 0x80080
	s_addc_u32 s41, s41, 0
	s_add_i32 s45, s48, s72
	v_lshl_add_u64 v[130:131], s[40:41], 0, v[0:1]
	s_mov_b32 m0, s45
	s_nop 0
	global_load_lds_dwordx4 v[130:131], off
	v_lshl_add_u64 v[130:131], s[40:41], 0, v[142:143]
	s_add_i32 m0, s45, 0x2000
	s_nop 0
	global_load_lds_dwordx4 v[130:131], off
	s_waitcnt vmcnt(6)
	s_barrier
	v_mfma_f32_16x16x32_f16 v[54:57], v[194:197], v[162:165], v[54:57]
	v_mfma_f32_16x16x32_f16 v[50:53], v[202:205], v[162:165], v[50:53]
	v_mfma_f32_16x16x32_f16 v[38:41], v[194:197], v[170:173], v[38:41]
	v_mfma_f32_16x16x32_f16 v[34:37], v[202:205], v[170:173], v[34:37]
	v_mfma_f32_16x16x32_f16 v[22:25], v[194:197], v[178:181], v[22:25]
	v_mfma_f32_16x16x32_f16 v[18:21], v[202:205], v[178:181], v[18:21]
	v_mfma_f32_16x16x32_f16 v[6:9], v[194:197], v[186:189], v[6:9]
	v_mfma_f32_16x16x32_f16 v[2:5], v[202:205], v[186:189], v[2:5]
	v_mfma_f32_16x16x32_f16 v[54:57], v[198:201], v[166:169], v[54:57]
	v_mfma_f32_16x16x32_f16 v[50:53], v[220:223], v[166:169], v[50:53]
	v_mfma_f32_16x16x32_f16 v[38:41], v[198:201], v[174:177], v[38:41]
	v_mfma_f32_16x16x32_f16 v[34:37], v[220:223], v[174:177], v[34:37]
	v_mfma_f32_16x16x32_f16 v[22:25], v[198:201], v[182:185], v[22:25]
	v_mfma_f32_16x16x32_f16 v[18:21], v[220:223], v[182:185], v[18:21]
	v_mfma_f32_16x16x32_f16 v[6:9], v[198:201], v[190:193], v[6:9]
	v_mfma_f32_16x16x32_f16 v[2:5], v[220:223], v[190:193], v[2:5]
	s_add_i32 s43, s43, 2
	s_add_u32 s0, s0, 0x100
	s_addc_u32 s1, s1, 0
	s_add_u32 s21, s21, 0x100
	s_addc_u32 s35, s35, 0
	s_cmp_gt_u32 s43, 29
	s_barrier
	s_cbranch_scc0 .LBB0_799
	s_cmp_eq_u32 s22, 26
	s_cselect_b32 s0, 2, 0
	s_cmp_lg_u32 s22, 24
	s_cselect_b32 s43, s0, 1
	s_cmp_gt_i32 s43, 1
	s_mov_b64 s[0:1], -1
	s_cbranch_scc0 .LBB0_802
	v_mul_f32_e32 v132, 0xbfb8aa3b, v123
	v_mul_f32_e32 v133, 0xbfb8aa3b, v124
	v_exp_f32_e32 v135, v132
	v_mul_f32_e32 v132, 0xbfb8aa3b, v128
	v_exp_f32_e32 v136, v133
	v_mul_f32_e32 v133, 0xbfb8aa3b, v129
	v_exp_f32_e32 v132, v132
	v_exp_f32_e32 v133, v133
	v_mul_f32_e32 v131, 0xbfb8aa3b, v122
	v_mul_f32_e32 v130, 0xbfb8aa3b, v126
	v_exp_f32_e32 v134, v131
	v_pk_add_f32 v[132:133], v[132:133], 1.0 op_sel_hi:[1,0]
	v_mul_f32_e32 v131, 0xbfb8aa3b, v127
	v_div_scale_f32 v137, s[0:1], v133, v133, 1.0
	v_rcp_f32_e32 v148, v137
	v_exp_f32_e32 v130, v130
	v_exp_f32_e32 v131, v131
	v_pk_add_f32 v[134:135], v[134:135], 1.0 op_sel_hi:[1,0]
	v_fma_f32 v149, -v137, v148, 1.0
	v_fmac_f32_e32 v148, v149, v148
	v_div_scale_f32 v149, vcc, 1.0, v133, 1.0
	v_mul_f32_e32 v150, v149, v148
	v_fma_f32 v151, -v137, v150, v149
	v_fmac_f32_e32 v150, v151, v148
	v_fma_f32 v137, -v137, v150, v149
	v_div_fmas_f32 v137, v137, v148, v150
	v_div_fixup_f32 v133, v137, v133, 1.0
	v_div_scale_f32 v137, s[0:1], v132, v132, 1.0
	v_rcp_f32_e32 v148, v137
	v_pk_add_f32 v[130:131], v[130:131], 1.0 op_sel_hi:[1,0]
	v_fma_f32 v149, -v137, v148, 1.0
	v_fmac_f32_e32 v148, v149, v148
	v_div_scale_f32 v149, vcc, 1.0, v132, 1.0
	v_mul_f32_e32 v150, v149, v148
	v_fma_f32 v151, -v137, v150, v149
	v_fmac_f32_e32 v150, v151, v148
	v_fma_f32 v137, -v137, v150, v149
	v_div_fmas_f32 v137, v137, v148, v150
	v_div_fixup_f32 v132, v137, v132, 1.0
	v_div_scale_f32 v137, s[0:1], v131, v131, 1.0
	v_rcp_f32_e32 v148, v137
	s_nop 0
	v_fma_f32 v149, -v137, v148, 1.0
	v_fmac_f32_e32 v148, v149, v148
	v_div_scale_f32 v149, vcc, 1.0, v131, 1.0
	v_mul_f32_e32 v150, v149, v148
	v_fma_f32 v151, -v137, v150, v149
	v_fmac_f32_e32 v150, v151, v148
	v_fma_f32 v137, -v137, v150, v149
	v_div_fmas_f32 v137, v137, v148, v150
	v_div_fixup_f32 v131, v137, v131, 1.0
	v_div_scale_f32 v137, s[0:1], v130, v130, 1.0
	v_rcp_f32_e32 v148, v137
	s_nop 0
	v_fma_f32 v149, -v137, v148, 1.0
	v_fmac_f32_e32 v148, v149, v148
	v_div_scale_f32 v149, vcc, 1.0, v130, 1.0
	v_mul_f32_e32 v150, v149, v148
	v_fma_f32 v151, -v137, v150, v149
	v_fmac_f32_e32 v150, v151, v148
	v_fma_f32 v137, -v137, v150, v149
	v_div_fmas_f32 v137, v137, v148, v150
	v_div_fixup_f32 v130, v137, v130, 1.0
	v_mul_f32_e32 v137, 0xbfb8aa3b, v125
	v_exp_f32_e32 v137, v137
	s_nop 0
	v_pk_add_f32 v[136:137], v[136:137], 1.0 op_sel_hi:[1,0]
	s_nop 0
	v_div_scale_f32 v148, s[0:1], v137, v137, 1.0
	v_rcp_f32_e32 v149, v148
	s_nop 0
	v_fma_f32 v150, -v148, v149, 1.0
	v_fmac_f32_e32 v149, v150, v149
	v_div_scale_f32 v150, vcc, 1.0, v137, 1.0
	v_mul_f32_e32 v151, v150, v149
	v_fma_f32 v152, -v148, v151, v150
	v_fmac_f32_e32 v151, v152, v149
	v_fma_f32 v148, -v148, v151, v150
	v_div_fmas_f32 v148, v148, v149, v151
	v_div_fixup_f32 v137, v148, v137, 1.0
	v_div_scale_f32 v148, s[0:1], v136, v136, 1.0
	v_rcp_f32_e32 v149, v148
	s_nop 0
	v_fma_f32 v150, -v148, v149, 1.0
	v_fmac_f32_e32 v149, v150, v149
	v_div_scale_f32 v150, vcc, 1.0, v136, 1.0
	v_mul_f32_e32 v151, v150, v149
	v_fma_f32 v152, -v148, v151, v150
	v_fmac_f32_e32 v151, v152, v149
	v_fma_f32 v148, -v148, v151, v150
	v_div_fmas_f32 v148, v148, v149, v151
	v_div_fixup_f32 v136, v148, v136, 1.0
	v_div_scale_f32 v148, s[0:1], v135, v135, 1.0
	v_rcp_f32_e32 v149, v148
	s_nop 0
	v_fma_f32 v150, -v148, v149, 1.0
	v_fmac_f32_e32 v149, v150, v149
	v_div_scale_f32 v150, vcc, 1.0, v135, 1.0
	v_mul_f32_e32 v151, v150, v149
	v_fma_f32 v152, -v148, v151, v150
	v_fmac_f32_e32 v151, v152, v149
	v_fma_f32 v148, -v148, v151, v150
	v_div_fmas_f32 v148, v148, v149, v151
	v_div_fixup_f32 v135, v148, v135, 1.0
	v_div_scale_f32 v148, s[0:1], v134, v134, 1.0
	v_rcp_f32_e32 v149, v148
	s_mov_b64 s[0:1], 0
	v_fma_f32 v150, -v148, v149, 1.0
	v_fmac_f32_e32 v149, v150, v149
	v_div_scale_f32 v150, vcc, 1.0, v134, 1.0
	v_mul_f32_e32 v151, v150, v149
	v_fma_f32 v152, -v148, v151, v150
	v_fmac_f32_e32 v151, v152, v149
	v_fma_f32 v148, -v148, v151, v150
	v_div_fmas_f32 v148, v148, v149, v151
	v_div_fixup_f32 v134, v148, v134, 1.0
